# removed m0 save/restore and inter-issue nops around LDS-DMA issues in all GEMM loops
# speedup vs baseline: 1.0076x; 1.0076x over previous
; #define PG8_STAGE(bufoff, gbase, voff) do { _Pragma("unroll") for (int _i = 0; _i < 2; ++_i) \
;         glds_s((voff)[_i], (const void*)(gbase), ldsbase + (unsigned)((bufoff) + _i * 8192)); } while (0)
; #define PG8_WAIT_V(n) asm volatile("s_waitcnt vmcnt(" #n ")" ::: "memory")
; #define PG8_BAR __builtin_amdgcn_s_barrier()
; template <class Epi, class Sched, bool ALIGN_EPI, bool SP2>
; __device__ __forceinline__ void gemm_phase(LAS unsigned char* lds, const int K, const Sched& S, const Epi& E) {
;     ...
;     for (int i = 0; i < 2; ++i) { int R, C; stage_rc(tid * 16 + i * 8192, R, C); const int Rb = Epi::PERM ? ((R & ~31) + perm32(R & 31)) : R;
;         voffA[i] = (unsigned)(R * K + C) * 2u; voffB[i] = (unsigned)(Rb * K + C) * 2u; }
;     const size_t kstep = (size_t)(BK * 2);
;     const size_t hstep = (size_t)HALF * K * 2;
;     const unsigned ldsw = (unsigned)wid * 1024u;
;     const unsigned ldsbase = (unsigned)__builtin_amdgcn_readfirstlane((int)((unsigned)(uintptr_t)lds + ldsw));
;     const int aoff = lds_byte(wr * 64 + fr, fq * 8), boff = lds_byte(wc * 32 + fr, fq * 8);
;     ...
;     Unit cur, nxt; int ui = 0;
;     if (!S.next(0, cur)) return;
;     f32x4 acc[2][2][4][2];
; #pragma unroll
;     for (int a = 0; a < 2; ++a)
; #pragma unroll
;         for (int b = 0; b < 2; ++b)
; #pragma unroll
;             for (int m = 0; m < 4; ++m)
; #pragma unroll
;                 for (int n = 0; n < 2; ++n) acc[a][b][m][n] = (f32x4){0.f, 0.f, 0.f, 0.f};
;     bf16x8 At[4][2], B0[2][2], B1[2][2];
;     const char* cA = cur.A; const char* cB = cur.B;
;     if constexpr (SP2) {
;         PG8_STAGE(PG8_SB(0, 0), cB, voffB); PG8_STAGE(PG8_SB(0, 1), cB + hstep, voffB); PG8_STAGE(PG8_SA(0, 0), cA, voffA); PG8_STAGE(PG8_SA(0, 1), cA + hstep, voffA);
;         if (wr == 1) PG8_BAR;
;         PG8_WAIT_V(2); PG8_BAR;
;         PG8_STAGE(PG8_SB(1, 0), cB + kstep, voffB); PG8_STAGE(PG8_SA(1, 0), cA + kstep, voffA); PG8_STAGE(PG8_SB(1, 1), cB + hstep + kstep, voffB);
;         PG8_WAIT_V(6); PG8_BAR;
.LBB0_437:
	s_andn2_b64 vcc, exec, s[18:19]
	s_cbranch_vccnz .LBB0_515
	v_bfe_i32 v4, v2, 27, 1
	v_lshlrev_b32_e32 v0, 4, v2
	v_lshrrev_b32_e32 v4, 22, v4
	v_add_u32_e32 v4, v0, v4
	v_and_b32_e32 v4, 0xfffffc00, v4
	v_sub_u32_e32 v4, v0, v4
	v_ashrrev_i32_e32 v3, 31, v2
	v_lshrrev_b32_e32 v5, 4, v4
	v_lshrrev_b32_e32 v3, 26, v3
	v_bitop3_b32 v4, v5, v4, 32 bitop3:0x6c
	v_add_u32_e32 v3, v2, v3
	v_ashrrev_i32_e32 v6, 31, v4
	v_ashrrev_i32_e32 v3, 6, v3
	v_lshrrev_b32_e32 v6, 26, v6
	v_lshlrev_b32_e32 v5, 3, v3
	v_add_u32_e32 v6, v4, v6
	v_and_b32_e32 v5, -16, v5
	v_ashrrev_i32_e32 v7, 6, v6
	v_and_b32_e32 v6, 0xc0, v6
	v_add_u32_e32 v5, v7, v5
	v_sub_u32_e32 v4, v4, v6
	v_lshlrev_b32_e32 v3, 5, v3
	v_ashrrev_i16_sdwa v4, v205, sext(v4) dst_sel:DWORD dst_unused:UNUSED_PAD src0_sel:DWORD src1_sel:BYTE_0
	v_lshlrev_b32_e32 v6, 1, v5
	v_lshrrev_b32_e32 v8, 2, v5
	v_and_b32_e32 v7, 3, v7
	v_and_b32_e32 v3, 32, v3
	v_bfe_i32 v4, v4, 0, 16
	v_and_b32_e32 v6, 24, v6
	v_and_b32_e32 v8, 4, v8
	v_and_or_b32 v7, v5, s83, v7
	v_or3_b32 v6, v7, v8, v6
	v_add_lshl_u32 v3, v3, v4, 1
	v_add_u32_e32 v0, 0x2000, v0
	s_waitcnt vmcnt(20)
	v_lshl_add_u32 v164, v5, 12, v3
	v_lshl_add_u32 v165, v6, 12, v3
	v_ashrrev_i32_e32 v3, 31, v0
	v_lshrrev_b32_e32 v3, 22, v3
	v_add_u32_e32 v3, v0, v3
	v_ashrrev_i32_e32 v3, 10, v3
	v_mul_i32_i24_e32 v4, 0x400, v3
	v_sub_u32_e32 v0, v0, v4
	v_lshrrev_b32_e32 v4, 4, v0
	v_bitop3_b32 v0, v4, v0, 32 bitop3:0x6c
	v_ashrrev_i32_e32 v5, 31, v0
	v_lshrrev_b32_e32 v5, 26, v5
	v_lshlrev_b32_e32 v4, 3, v3
	v_add_u32_e32 v5, v0, v5
	v_and_b32_e32 v4, -16, v4
	v_ashrrev_i32_e32 v6, 6, v5
	v_and_b32_e32 v5, 0xc0, v5
	v_add_u32_e32 v4, v6, v4
	v_sub_u32_e32 v0, v0, v5
	v_lshlrev_b32_e32 v3, 5, v3
	v_ashrrev_i16_sdwa v0, v205, sext(v0) dst_sel:DWORD dst_unused:UNUSED_PAD src0_sel:DWORD src1_sel:BYTE_0
	v_lshlrev_b32_e32 v5, 1, v4
	v_lshrrev_b32_e32 v7, 2, v4
	v_and_b32_e32 v6, 3, v6
	s_lshl_b32 s1, s8, 10
	v_and_b32_e32 v3, 32, v3
	v_bfe_i32 v0, v0, 0, 16
	v_and_b32_e32 v5, 24, v5
	v_and_b32_e32 v7, 4, v7
	v_and_or_b32 v6, v4, s83, v6
	s_add_i32 s53, s1, 0
	v_or3_b32 v5, v6, v7, v5
	v_add_lshl_u32 v0, v3, v0, 1
	s_ashr_i32 s0, s7, 8
	s_add_i32 s54, s53, 0x10000
	s_mov_b32 m0, s54
	s_nop 0
	global_load_lds_dwordx4 v165, s[16:17]
	s_add_i32 s55, s53, 0x12000
	v_lshl_add_u32 v167, v5, 12, v0
	s_mov_b32 m0, s55
	s_nop 0
	global_load_lds_dwordx4 v167, s[16:17]
	s_add_u32 s10, s16, 0x80000
	s_addc_u32 s11, s17, 0
	s_add_i32 s62, s53, 0x14000
	s_mov_b32 m0, s62
	s_nop 0
	global_load_lds_dwordx4 v165, s[10:11]
	s_add_i32 s63, s53, 0x16000
	s_mov_b32 m0, s63
	s_nop 0
	global_load_lds_dwordx4 v167, s[10:11]
	s_add_i32 s64, s53, 0x2000
	s_mov_b32 m0, s53
	s_nop 0
	global_load_lds_dwordx4 v164, s[12:13]
	v_lshl_add_u32 v166, v4, 12, v0
	s_mov_b32 m0, s64
	s_nop 0
	global_load_lds_dwordx4 v166, s[12:13]
	s_add_u32 s10, s12, 0x80000
	s_addc_u32 s11, s13, 0
	s_add_i32 s65, s53, 0x4000
	s_mov_b32 m0, s65
	s_nop 0
	global_load_lds_dwordx4 v164, s[10:11]
	s_add_i32 s66, s53, 0x6000
	s_mov_b32 m0, s66
	s_nop 0
	global_load_lds_dwordx4 v166, s[10:11]
	s_cmp_eq_u32 s0, 1
	s_cselect_b64 s[14:15], -1, 0
	s_cmp_lg_u32 s0, 1
	s_cbranch_scc1 .LBB0_440
	s_barrier
.LBB0_440:
	s_lshl_b32 s60, s82, 9
	s_lshl_b64 s[10:11], s[60:61], 2
	v_readlane_b32 s1, v252, 13
	v_bfe_u32 v5, v2, 4, 2
	s_add_u32 s67, s1, s10
	v_readlane_b32 s1, v252, 14
	v_and_b32_e32 v3, 15, v2
	v_lshlrev_b32_e32 v0, 4, v5
	v_lshlrev_b32_e32 v2, 2, v2
	s_addc_u32 s68, s1, s11
	s_and_b32 s8, s8, 3
	s_waitcnt vmcnt(19)
	v_lshl_or_b32 v168, s0, 6, v3
	v_lshl_or_b32 v3, v3, 6, v0
	s_lshl_b32 s0, s0, 13
	v_and_b32_e32 v2, 32, v2
	v_bitop3_b32 v6, v3, s0, v2 bitop3:0xde
	s_lshl_b32 s9, s8, 5
	s_lshl_b32 s0, s8, 12
	v_bitop3_b32 v3, v3, s0, v2 bitop3:0xde
	s_add_u32 s0, s16, 0x80
	s_waitcnt vmcnt(2)
	s_barrier
	s_addc_u32 s1, s17, 0
	s_add_i32 s69, s53, 0x18000
	s_mov_b32 m0, s69
	s_nop 0
	global_load_lds_dwordx4 v165, s[0:1]
	s_add_i32 s76, s53, 0x1a000
	s_mov_b32 m0, s76
	s_nop 0
	global_load_lds_dwordx4 v167, s[0:1]
	s_add_u32 s0, s12, 0x80
	s_addc_u32 s1, s13, 0
	s_add_i32 s77, s53, 0x8000
	s_mov_b32 m0, s77
	s_nop 0
	global_load_lds_dwordx4 v164, s[0:1]
	s_add_i32 s86, s53, 0xa000
	s_mov_b32 m0, s86
	s_nop 0
	global_load_lds_dwordx4 v166, s[0:1]
	s_add_u32 s0, s16, 0x80080
	s_addc_u32 s1, s17, 0
	s_add_i32 s87, s53, 0x1c000
	s_add_i32 s96, s53, 0x1e000
	s_add_i32 s97, s53, 0xc000
	s_cmpk_lt_u32 s7, 0x100
	s_mov_b32 m0, s87
	s_nop 0
	global_load_lds_dwordx4 v165, s[0:1]
	s_cselect_b64 s[22:23], -1, 0
	v_lshlrev_b32_e32 v7, 5, v168
	s_cmp_eq_u32 s8, 0
	v_or_b32_e32 v169, 16, v168
	v_readlane_b32 s7, v254, 43
	v_lshlrev_b32_e32 v4, 3, v5
	s_mov_b32 m0, s96
	s_nop 0
	global_load_lds_dwordx4 v167, s[0:1]
	v_cmp_eq_u32_e64 s[0:1], 0, v5
	s_cselect_b64 s[36:37], -1, 0
	v_lshlrev_b32_e32 v2, 2, v5
	v_lshlrev_b32_e32 v5, 5, v169
	v_or_b32_e32 v170, 32, v168
	v_add_u32_e32 v176, s7, v7
	s_lshl_b32 s7, s8, 2
	v_lshlrev_b32_e32 v8, 5, v170
	v_or_b32_e32 v171, 48, v168
	v_add_u32_e32 v177, s7, v176
	s_add_i32 s7, s7, 0
	s_waitcnt vmcnt(17)
	v_lshlrev_b32_e32 v158, 2, v2
	v_add_u32_e32 v2, 0, v5
	v_lshlrev_b32_e32 v9, 5, v171
	v_add_u32_e32 v172, 0x80, v168
	s_add_i32 s8, s7, 0x20200
	v_add_u32_e32 v192, 0x20000, v2
	v_add_u32_e32 v2, 0, v8
	v_lshlrev_b32_e32 v10, 5, v172
	v_add_u32_e32 v173, 0x90, v168
	v_add_u32_e32 v182, s8, v7
	s_add_i32 s8, s7, 0x20400
	v_add_u32_e32 v193, 0x20000, v2
	v_add_u32_e32 v2, 0, v9
	v_lshlrev_b32_e32 v11, 5, v173
	v_add_u32_e32 v174, 0xa0, v168
	v_readlane_b32 s10, v252, 17
	v_add_u32_e32 v183, s8, v7
	s_add_i32 s8, s7, 0x20600
	v_add_u32_e32 v194, 0x20000, v2
	v_add_u32_e32 v2, 0, v10
	v_lshlrev_b32_e32 v12, 5, v174
	v_add_u32_e32 v175, 0xb0, v168
	v_readlane_b32 s11, v252, 18
	v_add_u32_e32 v184, s8, v7
	s_add_i32 s8, s7, 0x21000
	v_add_u32_e32 v195, 0x20000, v2
	v_add_u32_e32 v2, 0, v11
	s_waitcnt vmcnt(6)
	v_lshlrev_b32_e32 v13, 5, v175
	v_lshl_add_u64 v[154:155], s[10:11], 0, v[0:1]
	v_readlane_b32 s10, v252, 15
	v_add_u32_e32 v185, s8, v7
	s_add_i32 s8, s7, 0x21200
	v_add_u32_e32 v196, 0x20000, v2
	v_add_u32_e32 v2, 0, v12
	v_readlane_b32 s11, v252, 16
	v_add_u32_e32 v186, s8, v7
	s_add_i32 s8, s7, 0x21400
	s_add_i32 s7, s7, 0x21600
	v_add_u32_e32 v197, 0x20000, v2
	v_add_u32_e32 v2, 0, v13
	s_mov_b32 s46, 0
	s_add_i32 s47, s53, 0xe000
	v_lshl_add_u64 v[156:157], s[10:11], 0, v[0:1]
	v_add_u32_e32 v187, s8, v7
	v_add_u32_e32 v188, s7, v7
	v_or_b32_e32 v189, s9, v4
	v_add_u32_e32 v190, 0, v3
	v_add_u32_e32 v191, 0, v6
	s_lshl_b32 s52, s9, 2
	v_lshlrev_b32_e32 v0, 2, v4
	v_add_u32_e32 v198, 0x20000, v2
	s_barrier
	s_branch .LBB0_443

; #define PG8_STAGE(bufoff, gbase, voff) do { _Pragma("unroll") for (int _i = 0; _i < 2; ++_i) \
;         glds_s((voff)[_i], (const void*)(gbase), ldsbase + (unsigned)((bufoff) + _i * 8192)); } while (0)
; #define PG8_LDA(dst, b, h) do { _Pragma("unroll") for (int m = 0; m < 4; ++m) _Pragma("unroll") for (int k = 0; k < 2; ++k) dst[m][k] = *(const LAS bf16x8*)(lds + PG8_SA(b, h) + aoff + m * 2048 + k * 1024); } while (0)
; #define PG8_LDB(dst, b, h) do { _Pragma("unroll") for (int n = 0; n < 2; ++n) _Pragma("unroll") for (int k = 0; k < 2; ++k) dst[n][k] = *(const LAS bf16x8*)(lds + PG8_SB(b, h) + boff + n * 2048 + k * 1024); } while (0)
; #define PG8_MMA(ai, bj, At, Bt) do { __builtin_amdgcn_s_setprio(1); _Pragma("unroll") for (int m = 0; m < 4; ++m) _Pragma("unroll") for (int n = 0; n < 2; ++n) _Pragma("unroll") for (int k = 0; k < 2; ++k) \
;         acc[ai][bj][m][n] = __builtin_amdgcn_mfma_f32_16x16x32_bf16(Bt[n][k], At[m][k], acc[ai][bj][m][n], 0, 0, 0); __builtin_amdgcn_s_setprio(0); } while (0)
; #define PG8_WAIT_V(n) asm volatile("s_waitcnt vmcnt(" #n ")" ::: "memory")
; #define PG8_WAIT_L(n) asm volatile("s_waitcnt lgkmcnt(" #n ")" ::: "memory")
; #define PG8_BAR __builtin_amdgcn_s_barrier()
; #define PG8_SCHED __builtin_amdgcn_sched_barrier(0)
; template <class Epi, class Sched, bool ALIGN_EPI, bool SP2>
; __device__ __forceinline__ void gemm_phase(LAS unsigned char* lds, const int K, const Sched& S, const Epi& E) {
;     ...
;             PG8_LDB(B0, 0, 0); PG8_LDB(B1, 0, 1); PG8_SCHED; PG8_LDA(At, 0, 0); PG8_STAGE(PG8_SA(1, 1), a1 + hstep, voffA);
;             PG8_WAIT_V(8); PG8_WAIT_L(0); PG8_BAR; PG8_MMA(0, 0, At, B0); PG8_MMA(0, 1, At, B1); PG8_BAR; PG8_SCHED;
;             PG8_LDA(At, 0, 1); PG8_STAGE(PG8_SB(0, 0), b2, voffB); PG8_STAGE(PG8_SB(0, 1), b2 + hstep, voffB); PG8_STAGE(PG8_SA(0, 0), a2, voffA);
;             PG8_WAIT_V(8); PG8_WAIT_L(0); PG8_BAR; PG8_MMA(1, 0, At, B0); PG8_MMA(1, 1, At, B1); PG8_BAR; PG8_SCHED;
.LBB0_449:
	v_add_u32_e32 v142, 0x10000, v190
	v_add_u32_e32 v159, 0x14000, v190
	ds_read_b128 v[130:133], v142
	ds_read_b128 v[134:137], v142 offset:1024
	ds_read_b128 v[138:141], v142 offset:2048
	ds_read_b128 v[142:145], v142 offset:3072
	ds_read_b128 v[146:149], v159
	ds_read_b128 v[150:153], v159 offset:1024
	ds_read_b128 v[160:163], v159 offset:2048
	ds_read_b128 v[214:217], v159 offset:3072
	s_add_u32 s16, s12, 0x100
	s_addc_u32 s17, s13, 0
	s_cmp_eq_u32 s21, 28
	s_cselect_b32 s38, s8, s16
	s_cselect_b32 s39, s7, s17
	s_cselect_b32 s26, s10, s11
	s_cselect_b32 s27, s9, s20
	s_add_u32 s18, s38, 0x80
	s_addc_u32 s19, s39, 0
	ds_read_b128 v[218:221], v191
	ds_read_b128 v[222:225], v191 offset:1024
	ds_read_b128 v[226:229], v191 offset:2048
	ds_read_b128 v[230:233], v191 offset:3072
	ds_read_b128 v[234:237], v191 offset:4096
	ds_read_b128 v[238:241], v191 offset:5120
	ds_read_b128 v[242:245], v191 offset:6144
	ds_read_b128 v[246:249], v191 offset:7168
	s_add_u32 s12, s12, 0x80080
	s_addc_u32 s13, s13, 0
	s_mov_b32 m0, s97
	s_nop 0
	global_load_lds_dwordx4 v164, s[12:13]
	s_mov_b32 m0, s47
	s_nop 0
	global_load_lds_dwordx4 v166, s[12:13]
	s_waitcnt vmcnt(8)
	s_waitcnt lgkmcnt(0)
	s_barrier
	s_setprio 1
	s_waitcnt lgkmcnt(7)
	v_mfma_f32_16x16x32_bf16 v[126:129], v[130:133], v[218:221], v[126:129]
	v_mfma_f32_16x16x32_bf16 v[122:125], v[138:141], v[218:221], v[122:125]
	s_waitcnt lgkmcnt(5)
	v_mfma_f32_16x16x32_bf16 v[118:121], v[130:133], v[226:229], v[118:121]
	v_mfma_f32_16x16x32_bf16 v[110:113], v[138:141], v[226:229], v[110:113]
	s_waitcnt lgkmcnt(3)
	v_mfma_f32_16x16x32_bf16 v[102:105], v[130:133], v[234:237], v[102:105]
	v_mfma_f32_16x16x32_bf16 v[94:97], v[138:141], v[234:237], v[94:97]
	s_waitcnt lgkmcnt(1)
	v_mfma_f32_16x16x32_bf16 v[86:89], v[130:133], v[242:245], v[86:89]
	v_mfma_f32_16x16x32_bf16 v[78:81], v[138:141], v[242:245], v[78:81]
	v_mfma_f32_16x16x32_bf16 v[126:129], v[134:137], v[222:225], v[126:129]
	v_mfma_f32_16x16x32_bf16 v[122:125], v[142:145], v[222:225], v[122:125]
	v_mfma_f32_16x16x32_bf16 v[118:121], v[134:137], v[230:233], v[118:121]
	v_mfma_f32_16x16x32_bf16 v[110:113], v[142:145], v[230:233], v[110:113]
	v_mfma_f32_16x16x32_bf16 v[102:105], v[134:137], v[238:241], v[102:105]
	v_mfma_f32_16x16x32_bf16 v[94:97], v[142:145], v[238:241], v[94:97]
	s_waitcnt lgkmcnt(0)
	v_mfma_f32_16x16x32_bf16 v[86:89], v[134:137], v[246:249], v[86:89]
	v_mfma_f32_16x16x32_bf16 v[78:81], v[142:145], v[246:249], v[78:81]
	s_setprio 0
	s_setprio 1
	v_mfma_f32_16x16x32_bf16 v[114:117], v[146:149], v[218:221], v[114:117]
	v_mfma_f32_16x16x32_bf16 v[106:109], v[160:163], v[218:221], v[106:109]
	v_mfma_f32_16x16x32_bf16 v[98:101], v[146:149], v[226:229], v[98:101]
	v_mfma_f32_16x16x32_bf16 v[90:93], v[160:163], v[226:229], v[90:93]
	v_mfma_f32_16x16x32_bf16 v[82:85], v[146:149], v[234:237], v[82:85]
	v_mfma_f32_16x16x32_bf16 v[74:77], v[160:163], v[234:237], v[74:77]
	v_mfma_f32_16x16x32_bf16 v[70:73], v[146:149], v[242:245], v[70:73]
	v_mfma_f32_16x16x32_bf16 v[66:69], v[160:163], v[242:245], v[66:69]
	v_mfma_f32_16x16x32_bf16 v[114:117], v[150:153], v[222:225], v[114:117]
	v_mfma_f32_16x16x32_bf16 v[106:109], v[214:217], v[222:225], v[106:109]
	v_mfma_f32_16x16x32_bf16 v[98:101], v[150:153], v[230:233], v[98:101]
	v_mfma_f32_16x16x32_bf16 v[90:93], v[214:217], v[230:233], v[90:93]
	v_mfma_f32_16x16x32_bf16 v[82:85], v[150:153], v[238:241], v[82:85]
	v_mfma_f32_16x16x32_bf16 v[74:77], v[214:217], v[238:241], v[74:77]
	v_mfma_f32_16x16x32_bf16 v[70:73], v[150:153], v[246:249], v[70:73]
	v_mfma_f32_16x16x32_bf16 v[66:69], v[214:217], v[246:249], v[66:69]
	s_setprio 0
	s_barrier
	ds_read_b128 v[218:221], v191 offset:16384
	ds_read_b128 v[222:225], v191 offset:17408
	ds_read_b128 v[226:229], v191 offset:18432
	ds_read_b128 v[230:233], v191 offset:19456
	ds_read_b128 v[234:237], v191 offset:20480
	ds_read_b128 v[238:241], v191 offset:21504
	ds_read_b128 v[242:245], v191 offset:22528
	ds_read_b128 v[246:249], v191 offset:23552
	s_mov_b32 m0, s54
	s_nop 0
	global_load_lds_dwordx4 v165, s[26:27]
	s_mov_b32 m0, s55
	s_nop 0
	global_load_lds_dwordx4 v167, s[26:27]
	s_add_u32 s12, s26, 0x80000
	s_addc_u32 s13, s27, 0
	s_mov_b32 m0, s62
	s_nop 0
	global_load_lds_dwordx4 v165, s[12:13]
	s_mov_b32 m0, s63
	s_nop 0
	global_load_lds_dwordx4 v167, s[12:13]
	s_mov_b32 m0, s53
	s_nop 0
	global_load_lds_dwordx4 v164, s[38:39]
	s_mov_b32 m0, s64
	s_nop 0
	global_load_lds_dwordx4 v166, s[38:39]
	s_waitcnt vmcnt(8)
	s_waitcnt lgkmcnt(0)
	s_barrier
; #define PG8_STAGE(bufoff, gbase, voff) do { _Pragma("unroll") for (int _i = 0; _i < 2; ++_i) \
;         glds_s((voff)[_i], (const void*)(gbase), ldsbase + (unsigned)((bufoff) + _i * 8192)); } while (0)
; #define PG8_LDA(dst, b, h) do { _Pragma("unroll") for (int m = 0; m < 4; ++m) _Pragma("unroll") for (int k = 0; k < 2; ++k) dst[m][k] = *(const LAS bf16x8*)(lds + PG8_SA(b, h) + aoff + m * 2048 + k * 1024); } while (0)
; #define PG8_LDB(dst, b, h) do { _Pragma("unroll") for (int n = 0; n < 2; ++n) _Pragma("unroll") for (int k = 0; k < 2; ++k) dst[n][k] = *(const LAS bf16x8*)(lds + PG8_SB(b, h) + boff + n * 2048 + k * 1024); } while (0)
; #define PG8_MMA(ai, bj, At, Bt) do { __builtin_amdgcn_s_setprio(1); _Pragma("unroll") for (int m = 0; m < 4; ++m) _Pragma("unroll") for (int n = 0; n < 2; ++n) _Pragma("unroll") for (int k = 0; k < 2; ++k) \
;         acc[ai][bj][m][n] = __builtin_amdgcn_mfma_f32_16x16x32_bf16(Bt[n][k], At[m][k], acc[ai][bj][m][n], 0, 0, 0); __builtin_amdgcn_s_setprio(0); } while (0)
; #define PG8_WAIT_V(n) asm volatile("s_waitcnt vmcnt(" #n ")" ::: "memory")
; #define PG8_WAIT_L(n) asm volatile("s_waitcnt lgkmcnt(" #n ")" ::: "memory")
; #define PG8_BAR __builtin_amdgcn_s_barrier()
; #define PG8_SCHED __builtin_amdgcn_sched_barrier(0)
; template <class Epi, class Sched, bool ALIGN_EPI, bool SP2>
; __device__ __forceinline__ void gemm_phase(LAS unsigned char* lds, const int K, const Sched& S, const Epi& E) {
;     ...
;             PG8_WAIT_V(8); PG8_WAIT_L(0); PG8_BAR; PG8_MMA(1, 0, At, B0); PG8_MMA(1, 1, At, B1); PG8_BAR; PG8_SCHED;
;             PG8_LDB(B0, 1, 0); PG8_LDB(B1, 1, 1); PG8_SCHED; PG8_LDA(At, 1, 0); PG8_STAGE(PG8_SA(0, 1), a2 + hstep, voffA);
;             PG8_WAIT_V(8); PG8_WAIT_L(0); PG8_BAR; PG8_MMA(0, 0, At, B0); PG8_MMA(0, 1, At, B1); PG8_BAR; PG8_SCHED;
	s_setprio 1
	s_waitcnt lgkmcnt(7)
	v_mfma_f32_16x16x32_bf16 v[62:65], v[130:133], v[218:221], v[62:65]
	v_mfma_f32_16x16x32_bf16 v[58:61], v[138:141], v[218:221], v[58:61]
	s_waitcnt lgkmcnt(5)
	v_mfma_f32_16x16x32_bf16 v[54:57], v[130:133], v[226:229], v[54:57]
	v_mfma_f32_16x16x32_bf16 v[46:49], v[138:141], v[226:229], v[46:49]
	s_waitcnt lgkmcnt(3)
	v_mfma_f32_16x16x32_bf16 v[38:41], v[130:133], v[234:237], v[38:41]
	v_mfma_f32_16x16x32_bf16 v[30:33], v[138:141], v[234:237], v[30:33]
	s_waitcnt lgkmcnt(1)
	v_mfma_f32_16x16x32_bf16 v[22:25], v[130:133], v[242:245], v[22:25]
	v_mfma_f32_16x16x32_bf16 v[14:17], v[138:141], v[242:245], v[14:17]
	v_mfma_f32_16x16x32_bf16 v[62:65], v[134:137], v[222:225], v[62:65]
	v_mfma_f32_16x16x32_bf16 v[58:61], v[142:145], v[222:225], v[58:61]
	v_mfma_f32_16x16x32_bf16 v[54:57], v[134:137], v[230:233], v[54:57]
	v_mfma_f32_16x16x32_bf16 v[46:49], v[142:145], v[230:233], v[46:49]
	v_mfma_f32_16x16x32_bf16 v[38:41], v[134:137], v[238:241], v[38:41]
	v_mfma_f32_16x16x32_bf16 v[30:33], v[142:145], v[238:241], v[30:33]
	s_waitcnt lgkmcnt(0)
	v_mfma_f32_16x16x32_bf16 v[22:25], v[134:137], v[246:249], v[22:25]
	v_mfma_f32_16x16x32_bf16 v[14:17], v[142:145], v[246:249], v[14:17]
	s_setprio 0
	s_setprio 1
	v_mfma_f32_16x16x32_bf16 v[50:53], v[146:149], v[218:221], v[50:53]
	v_mfma_f32_16x16x32_bf16 v[42:45], v[160:163], v[218:221], v[42:45]
	v_mfma_f32_16x16x32_bf16 v[34:37], v[146:149], v[226:229], v[34:37]
	v_mfma_f32_16x16x32_bf16 v[26:29], v[160:163], v[226:229], v[26:29]
	v_mfma_f32_16x16x32_bf16 v[18:21], v[146:149], v[234:237], v[18:21]
	v_mfma_f32_16x16x32_bf16 v[10:13], v[160:163], v[234:237], v[10:13]
	v_mfma_f32_16x16x32_bf16 v[6:9], v[146:149], v[242:245], v[6:9]
	v_mfma_f32_16x16x32_bf16 v[2:5], v[160:163], v[242:245], v[2:5]
	v_mfma_f32_16x16x32_bf16 v[50:53], v[150:153], v[222:225], v[50:53]
	v_mfma_f32_16x16x32_bf16 v[42:45], v[214:217], v[222:225], v[42:45]
	v_mfma_f32_16x16x32_bf16 v[34:37], v[150:153], v[230:233], v[34:37]
	v_mfma_f32_16x16x32_bf16 v[26:29], v[214:217], v[230:233], v[26:29]
	v_mfma_f32_16x16x32_bf16 v[18:21], v[150:153], v[238:241], v[18:21]
	v_mfma_f32_16x16x32_bf16 v[10:13], v[214:217], v[238:241], v[10:13]
	v_mfma_f32_16x16x32_bf16 v[6:9], v[150:153], v[246:249], v[6:9]
	v_mfma_f32_16x16x32_bf16 v[2:5], v[214:217], v[246:249], v[2:5]
	s_setprio 0
	s_barrier
	v_add_u32_e32 v142, 0x18000, v190
	v_add_u32_e32 v159, 0x1c000, v190
	ds_read_b128 v[130:133], v142
	ds_read_b128 v[134:137], v142 offset:1024
	ds_read_b128 v[138:141], v142 offset:2048
	ds_read_b128 v[142:145], v142 offset:3072
	ds_read_b128 v[146:149], v159
	ds_read_b128 v[150:153], v159 offset:1024
	ds_read_b128 v[160:163], v159 offset:2048
	ds_read_b128 v[214:217], v159 offset:3072
	ds_read_b128 v[218:221], v191 offset:32768
	ds_read_b128 v[222:225], v191 offset:33792
	ds_read_b128 v[226:229], v191 offset:34816
	ds_read_b128 v[230:233], v191 offset:35840
	ds_read_b128 v[234:237], v191 offset:36864
	ds_read_b128 v[238:241], v191 offset:37888
	ds_read_b128 v[242:245], v191 offset:38912
	ds_read_b128 v[246:249], v191 offset:39936
	s_add_u32 s12, s38, 0x80000
	s_addc_u32 s13, s39, 0
	s_mov_b32 m0, s65
	s_nop 0
	global_load_lds_dwordx4 v164, s[12:13]
	s_mov_b32 m0, s66
	s_nop 0
	global_load_lds_dwordx4 v166, s[12:13]
	s_waitcnt vmcnt(8)
	s_waitcnt lgkmcnt(0)
	s_barrier
	s_setprio 1
	s_waitcnt lgkmcnt(7)
	v_mfma_f32_16x16x32_bf16 v[126:129], v[130:133], v[218:221], v[126:129]
	v_mfma_f32_16x16x32_bf16 v[122:125], v[138:141], v[218:221], v[122:125]
	s_waitcnt lgkmcnt(5)
	v_mfma_f32_16x16x32_bf16 v[118:121], v[130:133], v[226:229], v[118:121]
	v_mfma_f32_16x16x32_bf16 v[110:113], v[138:141], v[226:229], v[110:113]
	s_waitcnt lgkmcnt(3)
	v_mfma_f32_16x16x32_bf16 v[102:105], v[130:133], v[234:237], v[102:105]
	v_mfma_f32_16x16x32_bf16 v[94:97], v[138:141], v[234:237], v[94:97]
	s_waitcnt lgkmcnt(1)
	v_mfma_f32_16x16x32_bf16 v[86:89], v[130:133], v[242:245], v[86:89]
	v_mfma_f32_16x16x32_bf16 v[78:81], v[138:141], v[242:245], v[78:81]
	v_mfma_f32_16x16x32_bf16 v[126:129], v[134:137], v[222:225], v[126:129]
	v_mfma_f32_16x16x32_bf16 v[122:125], v[142:145], v[222:225], v[122:125]
	v_mfma_f32_16x16x32_bf16 v[118:121], v[134:137], v[230:233], v[118:121]
	v_mfma_f32_16x16x32_bf16 v[110:113], v[142:145], v[230:233], v[110:113]
	v_mfma_f32_16x16x32_bf16 v[102:105], v[134:137], v[238:241], v[102:105]
	v_mfma_f32_16x16x32_bf16 v[94:97], v[142:145], v[238:241], v[94:97]
	s_waitcnt lgkmcnt(0)
	v_mfma_f32_16x16x32_bf16 v[86:89], v[134:137], v[246:249], v[86:89]
	v_mfma_f32_16x16x32_bf16 v[78:81], v[142:145], v[246:249], v[78:81]
	s_setprio 0
	s_setprio 1
	v_mfma_f32_16x16x32_bf16 v[114:117], v[146:149], v[218:221], v[114:117]
	v_mfma_f32_16x16x32_bf16 v[106:109], v[160:163], v[218:221], v[106:109]
	v_mfma_f32_16x16x32_bf16 v[98:101], v[146:149], v[226:229], v[98:101]
	v_mfma_f32_16x16x32_bf16 v[90:93], v[160:163], v[226:229], v[90:93]
	v_mfma_f32_16x16x32_bf16 v[82:85], v[146:149], v[234:237], v[82:85]
	v_mfma_f32_16x16x32_bf16 v[74:77], v[160:163], v[234:237], v[74:77]
	v_mfma_f32_16x16x32_bf16 v[70:73], v[146:149], v[242:245], v[70:73]
	v_mfma_f32_16x16x32_bf16 v[66:69], v[160:163], v[242:245], v[66:69]
	v_mfma_f32_16x16x32_bf16 v[114:117], v[150:153], v[222:225], v[114:117]
	v_mfma_f32_16x16x32_bf16 v[106:109], v[214:217], v[222:225], v[106:109]
	v_mfma_f32_16x16x32_bf16 v[98:101], v[150:153], v[230:233], v[98:101]
	v_mfma_f32_16x16x32_bf16 v[90:93], v[214:217], v[230:233], v[90:93]
	v_mfma_f32_16x16x32_bf16 v[82:85], v[150:153], v[238:241], v[82:85]
	v_mfma_f32_16x16x32_bf16 v[74:77], v[214:217], v[238:241], v[74:77]
	v_mfma_f32_16x16x32_bf16 v[70:73], v[150:153], v[246:249], v[70:73]
	v_mfma_f32_16x16x32_bf16 v[66:69], v[214:217], v[246:249], v[66:69]
	s_setprio 0
	s_barrier
; #define PG8_STAGE(bufoff, gbase, voff) do { _Pragma("unroll") for (int _i = 0; _i < 2; ++_i) \
;         glds_s((voff)[_i], (const void*)(gbase), ldsbase + (unsigned)((bufoff) + _i * 8192)); } while (0)
; #define PG8_LDA(dst, b, h) do { _Pragma("unroll") for (int m = 0; m < 4; ++m) _Pragma("unroll") for (int k = 0; k < 2; ++k) dst[m][k] = *(const LAS bf16x8*)(lds + PG8_SA(b, h) + aoff + m * 2048 + k * 1024); } while (0)
; #define PG8_LDB(dst, b, h) do { _Pragma("unroll") for (int n = 0; n < 2; ++n) _Pragma("unroll") for (int k = 0; k < 2; ++k) dst[n][k] = *(const LAS bf16x8*)(lds + PG8_SB(b, h) + boff + n * 2048 + k * 1024); } while (0)
; #define PG8_WAIT_V(n) asm volatile("s_waitcnt vmcnt(" #n ")" ::: "memory")
; #define PG8_WAIT_L(n) asm volatile("s_waitcnt lgkmcnt(" #n ")" ::: "memory")
; template <class Epi, class Sched, bool ALIGN_EPI, bool SP2>
; __device__ __forceinline__ void gemm_phase(LAS unsigned char* lds, const int K, const Sched& S, const Epi& E) {
;     ...
;         for (int t = 0; t < nt; t += 2) {
;             const bool last = (t == nt - 2);
;             const char* a1 = cA + (size_t)(t + 1) * kstep;
;             const char* a2 = last ? nA : cA + (size_t)(t + 2) * kstep; const char* b2 = last ? nB : cB + (size_t)(t + 2) * kstep;
;             const char* a3 = a2 + kstep; const char* b3 = b2 + kstep;
;             if constexpr (SP2) {
;             PG8_LDB(B0, 0, 0); PG8_LDB(B1, 0, 1); PG8_SCHED; PG8_LDA(At, 0, 0); PG8_STAGE(PG8_SA(1, 1), a1 + hstep, voffA);
;             PG8_WAIT_V(8); PG8_WAIT_L(0); PG8_BAR; PG8_MMA(0, 0, At, B0); PG8_MMA(0, 1, At, B1); PG8_BAR; PG8_SCHED;
;             PG8_LDA(At, 0, 1); PG8_STAGE(PG8_SB(0, 0), b2, voffB); PG8_STAGE(PG8_SB(0, 1), b2 + hstep, voffB); PG8_STAGE(PG8_SA(0, 0), a2, voffA);
;             PG8_WAIT_V(8); PG8_WAIT_L(0); PG8_BAR; PG8_MMA(1, 0, At, B0); PG8_MMA(1, 1, At, B1); PG8_BAR; PG8_SCHED;
;             PG8_LDB(B0, 1, 0); PG8_LDB(B1, 1, 1); PG8_SCHED; PG8_LDA(At, 1, 0); PG8_STAGE(PG8_SA(0, 1), a2 + hstep, voffA);
;             PG8_WAIT_V(8); PG8_WAIT_L(0); PG8_BAR; PG8_MMA(0, 0, At, B0); PG8_MMA(0, 1, At, B1); PG8_BAR; PG8_SCHED;
;             PG8_LDA(At, 1, 1); PG8_STAGE(PG8_SB(1, 0), b3, voffB); PG8_STAGE(PG8_SB(1, 1), b3 + hstep, voffB); PG8_STAGE(PG8_SA(1, 0), a3, voffA);
;             PG8_WAIT_V(8); PG8_WAIT_L(0); PG8_BAR; PG8_MMA(1, 0, At, B0); PG8_MMA(1, 1, At, B1); PG8_BAR; PG8_SCHED;
	ds_read_b128 v[218:221], v191 offset:49152
	ds_read_b128 v[222:225], v191 offset:50176
	ds_read_b128 v[226:229], v191 offset:51200
	ds_read_b128 v[230:233], v191 offset:52224
	ds_read_b128 v[234:237], v191 offset:53248
	ds_read_b128 v[238:241], v191 offset:54272
	ds_read_b128 v[242:245], v191 offset:55296
	ds_read_b128 v[246:249], v191 offset:56320
	s_add_u32 s12, s26, 0x80
	s_addc_u32 s13, s27, 0
	s_mov_b32 m0, s69
	s_nop 0
	global_load_lds_dwordx4 v165, s[12:13]
	s_mov_b32 m0, s76
	s_nop 0
	global_load_lds_dwordx4 v167, s[12:13]
	s_add_u32 s12, s26, 0x80080
	s_addc_u32 s13, s27, 0
	s_mov_b32 m0, s87
	s_nop 0
	global_load_lds_dwordx4 v165, s[12:13]
	s_mov_b32 m0, s96
	s_nop 0
	global_load_lds_dwordx4 v167, s[12:13]
	s_mov_b32 m0, s77
	s_nop 0
	global_load_lds_dwordx4 v164, s[18:19]
	s_mov_b32 m0, s86
	s_nop 0
	global_load_lds_dwordx4 v166, s[18:19]
	s_waitcnt vmcnt(8)
	s_waitcnt lgkmcnt(0)
	s_barrier
	s_setprio 1
	s_waitcnt lgkmcnt(7)
	v_mfma_f32_16x16x32_bf16 v[62:65], v[130:133], v[218:221], v[62:65]
	v_mfma_f32_16x16x32_bf16 v[58:61], v[138:141], v[218:221], v[58:61]
	s_waitcnt lgkmcnt(5)
	v_mfma_f32_16x16x32_bf16 v[54:57], v[130:133], v[226:229], v[54:57]
	v_mfma_f32_16x16x32_bf16 v[46:49], v[138:141], v[226:229], v[46:49]
	s_waitcnt lgkmcnt(3)
	v_mfma_f32_16x16x32_bf16 v[38:41], v[130:133], v[234:237], v[38:41]
	v_mfma_f32_16x16x32_bf16 v[30:33], v[138:141], v[234:237], v[30:33]
	s_waitcnt lgkmcnt(1)
	v_mfma_f32_16x16x32_bf16 v[22:25], v[130:133], v[242:245], v[22:25]
	v_mfma_f32_16x16x32_bf16 v[14:17], v[138:141], v[242:245], v[14:17]
	v_mfma_f32_16x16x32_bf16 v[62:65], v[134:137], v[222:225], v[62:65]
	v_mfma_f32_16x16x32_bf16 v[58:61], v[142:145], v[222:225], v[58:61]
	v_mfma_f32_16x16x32_bf16 v[54:57], v[134:137], v[230:233], v[54:57]
	v_mfma_f32_16x16x32_bf16 v[46:49], v[142:145], v[230:233], v[46:49]
	v_mfma_f32_16x16x32_bf16 v[38:41], v[134:137], v[238:241], v[38:41]
	v_mfma_f32_16x16x32_bf16 v[30:33], v[142:145], v[238:241], v[30:33]
	s_waitcnt lgkmcnt(0)
	v_mfma_f32_16x16x32_bf16 v[22:25], v[134:137], v[246:249], v[22:25]
	v_mfma_f32_16x16x32_bf16 v[14:17], v[142:145], v[246:249], v[14:17]
	s_setprio 0
	s_setprio 1
	v_mfma_f32_16x16x32_bf16 v[50:53], v[146:149], v[218:221], v[50:53]
	v_mfma_f32_16x16x32_bf16 v[42:45], v[160:163], v[218:221], v[42:45]
	v_mfma_f32_16x16x32_bf16 v[34:37], v[146:149], v[226:229], v[34:37]
	v_mfma_f32_16x16x32_bf16 v[26:29], v[160:163], v[226:229], v[26:29]
	v_mfma_f32_16x16x32_bf16 v[18:21], v[146:149], v[234:237], v[18:21]
	v_mfma_f32_16x16x32_bf16 v[10:13], v[160:163], v[234:237], v[10:13]
	v_mfma_f32_16x16x32_bf16 v[6:9], v[146:149], v[242:245], v[6:9]
	v_mfma_f32_16x16x32_bf16 v[2:5], v[160:163], v[242:245], v[2:5]
	v_mfma_f32_16x16x32_bf16 v[50:53], v[150:153], v[222:225], v[50:53]
	v_mfma_f32_16x16x32_bf16 v[42:45], v[214:217], v[222:225], v[42:45]
	v_mfma_f32_16x16x32_bf16 v[34:37], v[150:153], v[230:233], v[34:37]
	v_mfma_f32_16x16x32_bf16 v[26:29], v[214:217], v[230:233], v[26:29]
	v_mfma_f32_16x16x32_bf16 v[18:21], v[150:153], v[238:241], v[18:21]
	v_mfma_f32_16x16x32_bf16 v[10:13], v[214:217], v[238:241], v[10:13]
	v_mfma_f32_16x16x32_bf16 v[6:9], v[150:153], v[246:249], v[6:9]
	v_mfma_f32_16x16x32_bf16 v[2:5], v[214:217], v[246:249], v[2:5]
	s_setprio 0
	s_barrier
	s_add_i32 s21, s21, 2
	s_add_u32 s11, s11, 0x100
	s_addc_u32 s20, s20, 0
	s_cmp_gt_u32 s21, 29
	s_mov_b64 s[12:13], s[16:17]
	s_cbranch_scc0 .LBB0_449
	s_and_b64 vcc, exec, s[22:23]
	s_cbranch_vccz .LBB0_452
	s_barrier

; #define PG8_STAGE(bufoff, gbase, voff) do { _Pragma("unroll") for (int _i = 0; _i < 2; ++_i) \
;         glds_s((voff)[_i], (const void*)(gbase), ldsbase + (unsigned)((bufoff) + _i * 8192)); } while (0)
; #define PG8_BAR __builtin_amdgcn_s_barrier()
; template <class Epi, class Sched, bool ALIGN_EPI, bool SP2>
; __device__ __forceinline__ void gemm_phase(LAS unsigned char* lds, const int K, const Sched& S, const Epi& E) {
;     ...
;     for (int i = 0; i < 2; ++i) { int R, C; stage_rc(tid * 16 + i * 8192, R, C); const int Rb = Epi::PERM ? ((R & ~31) + perm32(R & 31)) : R;
;         voffA[i] = (unsigned)(R * K + C) * 2u; voffB[i] = (unsigned)(Rb * K + C) * 2u; }
;     const size_t kstep = (size_t)(BK * 2);
;     const size_t hstep = (size_t)HALF * K * 2;
;     const unsigned ldsw = (unsigned)wid * 1024u;
;     const unsigned ldsbase = (unsigned)__builtin_amdgcn_readfirstlane((int)((unsigned)(uintptr_t)lds + ldsw));
;     const int aoff = lds_byte(wr * 64 + fr, fq * 8), boff = lds_byte(wc * 32 + fr, fq * 8);
;     ...
;     Unit cur, nxt; int ui = 0;
;     if (!S.next(0, cur)) return;
;     f32x4 acc[2][2][4][2];
; #pragma unroll
;     for (int a = 0; a < 2; ++a)
; #pragma unroll
;         for (int b = 0; b < 2; ++b)
; #pragma unroll
;             for (int m = 0; m < 4; ++m)
; #pragma unroll
;                 for (int n = 0; n < 2; ++n) acc[a][b][m][n] = (f32x4){0.f, 0.f, 0.f, 0.f};
;     bf16x8 At[4][2], B0[2][2], B1[2][2];
;     const char* cA = cur.A; const char* cB = cur.B;
;     if constexpr (SP2) {
;         PG8_STAGE(PG8_SB(0, 0), cB, voffB); PG8_STAGE(PG8_SB(0, 1), cB + hstep, voffB); PG8_STAGE(PG8_SA(0, 0), cA, voffA); PG8_STAGE(PG8_SA(0, 1), cA + hstep, voffA);
;         if (wr == 1) PG8_BAR;
.LBB0_672:
	s_or_b64 exec, exec, s[0:1]
	v_readlane_b32 s4, v252, 34
	v_readlane_b32 s5, v252, 35
	v_mov_b32_e32 v0, v202
	s_waitcnt lgkmcnt(0)
	v_cndmask_b32_e64 v2, 0, 1, s[4:5]
	s_barrier
	v_cmp_ne_u32_e64 s[6:7], 1, v2
	v_readfirstlane_b32 s0, v0
	s_andn2_b64 vcc, exec, s[4:5]
	v_writelane_b32 v250, s6, 21
	s_ashr_i32 s1, s0, 6
	s_nop 0
	v_writelane_b32 v250, s7, 22
	s_cbranch_vccnz .LBB0_758
	v_bfe_i32 v4, v0, 27, 1
	v_lshlrev_b32_e32 v2, 4, v0
	v_lshrrev_b32_e32 v4, 22, v4
	v_add_u32_e32 v4, v2, v4
	v_and_b32_e32 v4, 0xfffffc00, v4
	v_sub_u32_e32 v4, v2, v4
	v_ashrrev_i32_e32 v3, 31, v0
	v_lshrrev_b32_e32 v5, 4, v4
	v_lshrrev_b32_e32 v3, 26, v3
	v_bitop3_b32 v4, v5, v4, 32 bitop3:0x6c
	v_add_u32_e32 v3, v0, v3
	v_ashrrev_i32_e32 v6, 31, v4
	v_ashrrev_i32_e32 v3, 6, v3
	v_lshrrev_b32_e32 v6, 26, v6
	v_lshlrev_b32_e32 v5, 3, v3
	v_add_u32_e32 v6, v4, v6
	v_and_b32_e32 v5, -16, v5
	v_ashrrev_i32_e32 v7, 6, v6
	v_and_b32_e32 v6, 0xc0, v6
	v_add_u32_e32 v5, v7, v5
	v_sub_u32_e32 v4, v4, v6
	v_lshlrev_b32_e32 v3, 5, v3
	v_ashrrev_i16_sdwa v4, v205, sext(v4) dst_sel:DWORD dst_unused:UNUSED_PAD src0_sel:DWORD src1_sel:BYTE_0
	v_lshlrev_b32_e32 v6, 1, v5
	v_lshrrev_b32_e32 v8, 2, v5
	v_and_b32_e32 v7, 3, v7
	s_mov_b32 s4, 0x1fffe0
	v_and_b32_e32 v3, 32, v3
	v_bfe_i32 v4, v4, 0, 16
	v_and_b32_e32 v6, 24, v6
	v_and_b32_e32 v8, 4, v8
	v_and_or_b32 v7, v5, s4, v7
	v_or3_b32 v6, v7, v8, v6
	v_add_lshl_u32 v3, v3, v4, 1
	v_add_u32_e32 v2, 0x2000, v2
	s_waitcnt vmcnt(16)
	v_lshl_add_u32 v146, v5, 11, v3
	v_lshl_add_u32 v147, v6, 11, v3
	v_ashrrev_i32_e32 v3, 31, v2
	v_lshrrev_b32_e32 v3, 22, v3
	v_add_u32_e32 v3, v2, v3
	v_ashrrev_i32_e32 v3, 10, v3
	v_mul_i32_i24_e32 v4, 0x400, v3
	v_sub_u32_e32 v2, v2, v4
	v_lshrrev_b32_e32 v4, 4, v2
	v_bitop3_b32 v2, v4, v2, 32 bitop3:0x6c
	v_ashrrev_i32_e32 v5, 31, v2
	v_lshrrev_b32_e32 v5, 26, v5
	v_lshlrev_b32_e32 v4, 3, v3
	v_add_u32_e32 v5, v2, v5
	v_and_b32_e32 v4, -16, v4
	v_ashrrev_i32_e32 v6, 6, v5
	v_and_b32_e32 v5, 0xc0, v5
	v_add_u32_e32 v4, v6, v4
	v_sub_u32_e32 v2, v2, v5
	v_and_b32_e32 v6, 3, v6
	v_lshlrev_b32_e32 v3, 5, v3
	v_ashrrev_i16_sdwa v2, v205, sext(v2) dst_sel:DWORD dst_unused:UNUSED_PAD src0_sel:DWORD src1_sel:BYTE_0
	v_lshlrev_b32_e32 v5, 1, v4
	v_lshrrev_b32_e32 v7, 2, v4
	v_and_or_b32 v6, v4, s4, v6
	s_lshl_b32 s4, s1, 10
	v_and_b32_e32 v3, 32, v3
	v_bfe_i32 v2, v2, 0, 16
	v_and_b32_e32 v5, 24, v5
	v_and_b32_e32 v7, 4, v7
	s_add_i32 s4, s4, 0
	v_readlane_b32 s8, v253, 30
	v_or3_b32 v5, v6, v7, v5
	v_add_lshl_u32 v2, v3, v2, 1
	s_add_i32 s5, s4, 0x10000
	v_readlane_b32 s9, v253, 31
	s_mov_b32 m0, s5
	s_nop 0
	global_load_lds_dwordx4 v147, s[8:9]
	v_lshl_add_u32 v149, v5, 11, v2
	s_add_i32 s6, s4, 0x12000
	s_mov_b32 m0, s6
	s_nop 0
	global_load_lds_dwordx4 v149, s[8:9]
	v_readlane_b32 s10, v253, 20
	s_add_i32 s7, s4, 0x14000
	v_readlane_b32 s11, v253, 21
	s_mov_b32 m0, s7
	s_nop 0
	global_load_lds_dwordx4 v147, s[10:11]
	s_add_i32 s8, s4, 0x16000
	s_mov_b32 m0, s8
	s_nop 0
	global_load_lds_dwordx4 v149, s[10:11]
	v_readlane_b32 s12, v253, 26
	v_readlane_b32 s13, v253, 27
	s_mov_b32 m0, s4
	s_nop 0
	global_load_lds_dwordx4 v146, s[12:13]
	v_lshl_add_u32 v148, v4, 11, v2
	s_add_i32 s9, s4, 0x2000
	s_mov_b32 m0, s9
	s_nop 0
	global_load_lds_dwordx4 v148, s[12:13]
	v_readlane_b32 s16, v253, 22
	s_add_i32 s10, s4, 0x4000
	v_readlane_b32 s17, v253, 23
	s_mov_b32 m0, s10
	s_nop 0
	global_load_lds_dwordx4 v146, s[16:17]
	s_ashr_i32 s14, s0, 8
	s_add_i32 s11, s4, 0x6000
	s_mov_b32 m0, s11
	s_nop 0
	global_load_lds_dwordx4 v148, s[16:17]
	s_cmp_eq_u32 s14, 1
	s_cselect_b64 s[12:13], -1, 0
	s_cmp_lg_u32 s14, 1
	s_cbranch_scc1 .LBB0_675
	s_barrier
; #define PG8_STAGE(bufoff, gbase, voff) do { _Pragma("unroll") for (int _i = 0; _i < 2; ++_i) \
;         glds_s((voff)[_i], (const void*)(gbase), ldsbase + (unsigned)((bufoff) + _i * 8192)); } while (0)
; #define PG8_WAIT_V(n) asm volatile("s_waitcnt vmcnt(" #n ")" ::: "memory")
; #define PG8_BAR __builtin_amdgcn_s_barrier()
; template <class Epi, class Sched, bool ALIGN_EPI, bool SP2>
; __device__ __forceinline__ void gemm_phase(LAS unsigned char* lds, const int K, const Sched& S, const Epi& E) {
;     ...
;     const int aoff = lds_byte(wr * 64 + fr, fq * 8), boff = lds_byte(wc * 32 + fr, fq * 8);
;     ...
;     Unit cur, nxt; int ui = 0;
;     if (!S.next(0, cur)) return;
;     f32x4 acc[2][2][4][2];
; #pragma unroll
;     for (int a = 0; a < 2; ++a)
; #pragma unroll
;         for (int b = 0; b < 2; ++b)
; #pragma unroll
;             for (int m = 0; m < 4; ++m)
; #pragma unroll
;                 for (int n = 0; n < 2; ++n) acc[a][b][m][n] = (f32x4){0.f, 0.f, 0.f, 0.f};
;     bf16x8 At[4][2], B0[2][2], B1[2][2];
;     const char* cA = cur.A; const char* cB = cur.B;
;     if constexpr (SP2) {
;         PG8_STAGE(PG8_SB(0, 0), cB, voffB); PG8_STAGE(PG8_SB(0, 1), cB + hstep, voffB); PG8_STAGE(PG8_SA(0, 0), cA, voffA); PG8_STAGE(PG8_SA(0, 1), cA + hstep, voffA);
;         if (wr == 1) PG8_BAR;
;         PG8_WAIT_V(2); PG8_BAR;
;         PG8_STAGE(PG8_SB(1, 0), cB + kstep, voffB); PG8_STAGE(PG8_SA(1, 0), cA + kstep, voffA); PG8_STAGE(PG8_SB(1, 1), cB + hstep + kstep, voffB);
;         PG8_WAIT_V(6); PG8_BAR;
.LBB0_675:
	v_lshrrev_b32_e32 v3, 1, v0
	v_and_b32_e32 v3, 24, v3
	v_and_b32_e32 v2, 15, v0
	v_lshlrev_b32_e32 v4, 1, v3
	v_lshlrev_b32_e32 v0, 2, v0
	s_lshl_b32 s1, s1, 5
	v_lshl_or_b32 v150, s14, 6, v2
	v_lshl_or_b32 v2, v2, 6, v4
	s_lshl_b32 s14, s14, 13
	v_and_b32_e32 v0, 32, v0
	s_and_b32 s1, s1, 0x60
	v_bitop3_b32 v4, v2, s14, v0 bitop3:0xde
	s_lshl_b32 s14, s1, 7
	v_readlane_b32 s16, v253, 24
	v_bitop3_b32 v5, v2, s14, v0 bitop3:0xde
	s_waitcnt vmcnt(2)
	s_barrier
	s_add_i32 s20, s4, 0x18000
	v_readlane_b32 s17, v253, 25
	s_mov_b32 m0, s20
	s_nop 0
	global_load_lds_dwordx4 v147, s[16:17]
	s_add_i32 s21, s4, 0x1a000
	s_mov_b32 m0, s21
	s_nop 0
	global_load_lds_dwordx4 v149, s[16:17]
	v_readlane_b32 s16, v253, 28
	s_add_i32 s28, s4, 0x8000
	v_readlane_b32 s17, v253, 29
	s_mov_b32 m0, s28
	s_nop 0
	global_load_lds_dwordx4 v146, s[16:17]
	s_add_i32 s30, s4, 0xa000
	s_mov_b32 m0, s30
	s_nop 0
	global_load_lds_dwordx4 v148, s[16:17]
	s_add_i32 s31, s4, 0x1c000
	v_readlane_b32 s16, v253, 32
	s_add_i32 s42, s4, 0x1e000
	s_add_i32 s43, s4, 0xc000
	v_readlane_b32 s17, v253, 33
	s_mov_b32 m0, s31
	s_nop 0
	global_load_lds_dwordx4 v147, s[16:17]
	s_cmpk_lt_u32 s0, 0x100
	v_or_b32_e32 v151, s1, v3
	v_readlane_b32 s0, v253, 1
	s_mov_b32 m0, s42
	s_nop 0
	global_load_lds_dwordx4 v149, s[16:17]
	v_readlane_b32 s1, v253, 2
	s_waitcnt vmcnt(6)
	v_mov_b32_e32 v2, v1
	v_mov_b32_e32 v3, v1
	s_mov_b32 s51, s0
	v_readlane_b32 s0, v253, 30
	v_readlane_b32 s34, v253, 26
	v_mov_b32_e32 v0, v1
	v_add_u32_e32 v152, 0, v5
	v_add_u32_e32 v153, 0, v4
	v_mov_b64_e32 v[6:7], v[2:3]
	v_mov_b64_e32 v[10:11], v[2:3]
	v_mov_b64_e32 v[14:15], v[2:3]
	v_mov_b64_e32 v[18:19], v[2:3]
	v_mov_b64_e32 v[22:23], v[2:3]
	v_mov_b64_e32 v[26:27], v[2:3]
	v_mov_b64_e32 v[30:31], v[2:3]
	v_mov_b64_e32 v[34:35], v[2:3]
	v_mov_b64_e32 v[38:39], v[2:3]
	v_mov_b64_e32 v[42:43], v[2:3]
	v_mov_b64_e32 v[46:47], v[2:3]
	v_mov_b64_e32 v[50:51], v[2:3]
	v_mov_b64_e32 v[54:55], v[2:3]
	v_mov_b64_e32 v[58:59], v[2:3]
	v_mov_b64_e32 v[66:67], v[2:3]
	v_mov_b64_e32 v[74:75], v[2:3]
	v_mov_b64_e32 v[62:63], v[2:3]
	v_mov_b64_e32 v[70:71], v[2:3]
	v_mov_b64_e32 v[78:79], v[2:3]
	v_mov_b64_e32 v[82:83], v[2:3]
	v_mov_b64_e32 v[86:87], v[2:3]
	v_mov_b64_e32 v[90:91], v[2:3]
	v_mov_b64_e32 v[94:95], v[2:3]
	v_mov_b64_e32 v[98:99], v[2:3]
	v_mov_b64_e32 v[102:103], v[2:3]
	v_mov_b64_e32 v[106:107], v[2:3]
	v_mov_b64_e32 v[110:111], v[2:3]
	v_mov_b64_e32 v[114:115], v[2:3]
	v_mov_b64_e32 v[118:119], v[2:3]
	v_mov_b64_e32 v[122:123], v[2:3]
	v_mov_b64_e32 v[126:127], v[2:3]
	v_mov_b64_e32 v[130:131], v[2:3]
	v_readlane_b32 s1, v253, 31
	v_readlane_b32 s35, v253, 27
	s_cselect_b64 s[14:15], -1, 0
	s_add_i32 s44, s4, 0xe000
	s_mov_b32 s24, 0
	v_mov_b64_e32 v[4:5], v[0:1]
	v_mov_b64_e32 v[8:9], v[0:1]
	v_mov_b64_e32 v[12:13], v[0:1]
	v_mov_b64_e32 v[16:17], v[0:1]
	v_mov_b64_e32 v[20:21], v[0:1]
	v_mov_b64_e32 v[24:25], v[0:1]
	v_mov_b64_e32 v[28:29], v[0:1]
	v_mov_b64_e32 v[32:33], v[0:1]
	v_mov_b64_e32 v[36:37], v[0:1]
	v_mov_b64_e32 v[40:41], v[0:1]
	v_mov_b64_e32 v[44:45], v[0:1]
	v_mov_b64_e32 v[48:49], v[0:1]
	v_mov_b64_e32 v[52:53], v[0:1]
	v_mov_b64_e32 v[56:57], v[0:1]
	v_mov_b64_e32 v[64:65], v[0:1]
	v_mov_b64_e32 v[72:73], v[0:1]
	v_mov_b64_e32 v[60:61], v[0:1]
	v_mov_b64_e32 v[68:69], v[0:1]
	v_mov_b64_e32 v[76:77], v[0:1]
	v_mov_b64_e32 v[80:81], v[0:1]
	v_mov_b64_e32 v[84:85], v[0:1]
	v_mov_b64_e32 v[88:89], v[0:1]
	v_mov_b64_e32 v[92:93], v[0:1]
	v_mov_b64_e32 v[96:97], v[0:1]
	v_mov_b64_e32 v[100:101], v[0:1]
	v_mov_b64_e32 v[104:105], v[0:1]
	v_mov_b64_e32 v[108:109], v[0:1]
	v_mov_b64_e32 v[112:113], v[0:1]
	v_mov_b64_e32 v[116:117], v[0:1]
	v_mov_b64_e32 v[120:121], v[0:1]
	v_mov_b64_e32 v[124:125], v[0:1]
	v_mov_b64_e32 v[128:129], v[0:1]
	v_readlane_b32 s25, v253, 3
	s_mov_b32 s45, 0
	s_mov_b64 s[18:19], s[34:35]
	s_mov_b64 s[22:23], s[0:1]
	s_barrier
	s_branch .LBB0_678

; #define PG8_STAGE(bufoff, gbase, voff) do { _Pragma("unroll") for (int _i = 0; _i < 2; ++_i) \
;         glds_s((voff)[_i], (const void*)(gbase), ldsbase + (unsigned)((bufoff) + _i * 8192)); } while (0)
; #define PG8_LDA(dst, b, h) do { _Pragma("unroll") for (int m = 0; m < 4; ++m) _Pragma("unroll") for (int k = 0; k < 2; ++k) dst[m][k] = *(const LAS bf16x8*)(lds + PG8_SA(b, h) + aoff + m * 2048 + k * 1024); } while (0)
; #define PG8_LDB(dst, b, h) do { _Pragma("unroll") for (int n = 0; n < 2; ++n) _Pragma("unroll") for (int k = 0; k < 2; ++k) dst[n][k] = *(const LAS bf16x8*)(lds + PG8_SB(b, h) + boff + n * 2048 + k * 1024); } while (0)
; #define PG8_MMA(ai, bj, At, Bt) do { __builtin_amdgcn_s_setprio(1); _Pragma("unroll") for (int m = 0; m < 4; ++m) _Pragma("unroll") for (int n = 0; n < 2; ++n) _Pragma("unroll") for (int k = 0; k < 2; ++k) \
;         acc[ai][bj][m][n] = __builtin_amdgcn_mfma_f32_16x16x32_bf16(Bt[n][k], At[m][k], acc[ai][bj][m][n], 0, 0, 0); __builtin_amdgcn_s_setprio(0); } while (0)
; #define PG8_WAIT_V(n) asm volatile("s_waitcnt vmcnt(" #n ")" ::: "memory")
; #define PG8_WAIT_L(n) asm volatile("s_waitcnt lgkmcnt(" #n ")" ::: "memory")
; #define PG8_BAR __builtin_amdgcn_s_barrier()
; #define PG8_SCHED __builtin_amdgcn_sched_barrier(0)
; template <class Epi, class Sched, bool ALIGN_EPI, bool SP2>
; __device__ __forceinline__ void gemm_phase(LAS unsigned char* lds, const int K, const Sched& S, const Epi& E) {
;     ...
;             PG8_LDB(B0, 0, 0); PG8_LDB(B1, 0, 1); PG8_SCHED; PG8_LDA(At, 0, 0); PG8_STAGE(PG8_SA(1, 1), a1 + hstep, voffA);
;             PG8_WAIT_V(8); PG8_WAIT_L(0); PG8_BAR; PG8_MMA(0, 0, At, B0); PG8_MMA(0, 1, At, B1); PG8_BAR; PG8_SCHED;
;             PG8_LDA(At, 0, 1); PG8_STAGE(PG8_SB(0, 0), b2, voffB); PG8_STAGE(PG8_SB(0, 1), b2 + hstep, voffB); PG8_STAGE(PG8_SA(0, 0), a2, voffA);
;             PG8_WAIT_V(8); PG8_WAIT_L(0); PG8_BAR; PG8_MMA(1, 0, At, B0); PG8_MMA(1, 1, At, B1); PG8_BAR; PG8_SCHED;
.LBB0_685:
	v_add_u32_e32 v0, 0x10000, v152
	ds_read_b128 v[132:135], v0
	ds_read_b128 v[136:139], v0 offset:1024
	ds_read_b128 v[140:143], v0 offset:2048
	ds_read_b128 v[154:157], v0 offset:3072
	v_add_u32_e32 v0, 0x14000, v152
	ds_read_b128 v[158:161], v0
	ds_read_b128 v[162:165], v0 offset:1024
	ds_read_b128 v[166:169], v0 offset:2048
	ds_read_b128 v[170:173], v0 offset:3072
	s_add_u32 s0, s34, 0x100
	s_addc_u32 s1, s35, 0
	s_cmp_eq_u32 s53, 12
	s_cselect_b32 s40, s18, s0
	s_cselect_b32 s41, s19, s1
	s_cselect_b32 s38, s22, s17
	s_cselect_b32 s39, s23, s52
	s_add_u32 s36, s40, 0x80
	s_addc_u32 s37, s41, 0
	ds_read_b128 v[174:177], v153
	ds_read_b128 v[182:185], v153 offset:1024
	ds_read_b128 v[186:189], v153 offset:2048
	ds_read_b128 v[190:193], v153 offset:3072
	ds_read_b128 v[194:197], v153 offset:4096
	ds_read_b128 v[198:201], v153 offset:5120
	ds_read_b128 v[214:217], v153 offset:6144
	ds_read_b128 v[218:221], v153 offset:7168
	s_add_u32 s34, s34, 0x40080
	s_addc_u32 s35, s35, 0
	s_mov_b32 m0, s43
	s_nop 0
	global_load_lds_dwordx4 v146, s[34:35]
	s_mov_b32 m0, s44
	s_nop 0
	global_load_lds_dwordx4 v148, s[34:35]
	s_waitcnt vmcnt(8)
	s_waitcnt lgkmcnt(0)
	s_barrier
	s_setprio 1
	s_waitcnt lgkmcnt(7)
	v_mfma_f32_16x16x32_bf16 v[128:131], v[132:135], v[174:177], v[128:131]
	v_mfma_f32_16x16x32_bf16 v[124:127], v[140:143], v[174:177], v[124:127]
	s_waitcnt lgkmcnt(5)
	v_mfma_f32_16x16x32_bf16 v[120:123], v[132:135], v[186:189], v[120:123]
	v_mfma_f32_16x16x32_bf16 v[116:119], v[140:143], v[186:189], v[116:119]
	s_waitcnt lgkmcnt(3)
	v_mfma_f32_16x16x32_bf16 v[112:115], v[132:135], v[194:197], v[112:115]
	v_mfma_f32_16x16x32_bf16 v[108:111], v[140:143], v[194:197], v[108:111]
	s_waitcnt lgkmcnt(1)
	v_mfma_f32_16x16x32_bf16 v[104:107], v[132:135], v[214:217], v[104:107]
	v_mfma_f32_16x16x32_bf16 v[100:103], v[140:143], v[214:217], v[100:103]
	v_mfma_f32_16x16x32_bf16 v[128:131], v[136:139], v[182:185], v[128:131]
	v_mfma_f32_16x16x32_bf16 v[124:127], v[154:157], v[182:185], v[124:127]
	v_mfma_f32_16x16x32_bf16 v[120:123], v[136:139], v[190:193], v[120:123]
	v_mfma_f32_16x16x32_bf16 v[116:119], v[154:157], v[190:193], v[116:119]
	v_mfma_f32_16x16x32_bf16 v[112:115], v[136:139], v[198:201], v[112:115]
	v_mfma_f32_16x16x32_bf16 v[108:111], v[154:157], v[198:201], v[108:111]
	s_waitcnt lgkmcnt(0)
	v_mfma_f32_16x16x32_bf16 v[104:107], v[136:139], v[218:221], v[104:107]
	v_mfma_f32_16x16x32_bf16 v[100:103], v[154:157], v[218:221], v[100:103]
	s_setprio 0
	s_setprio 1
	v_mfma_f32_16x16x32_bf16 v[96:99], v[158:161], v[174:177], v[96:99]
	v_mfma_f32_16x16x32_bf16 v[92:95], v[166:169], v[174:177], v[92:95]
	v_mfma_f32_16x16x32_bf16 v[88:91], v[158:161], v[186:189], v[88:91]
	v_mfma_f32_16x16x32_bf16 v[84:87], v[166:169], v[186:189], v[84:87]
	v_mfma_f32_16x16x32_bf16 v[80:83], v[158:161], v[194:197], v[80:83]
	v_mfma_f32_16x16x32_bf16 v[76:79], v[166:169], v[194:197], v[76:79]
	v_mfma_f32_16x16x32_bf16 v[68:71], v[158:161], v[214:217], v[68:71]
	v_mfma_f32_16x16x32_bf16 v[60:63], v[166:169], v[214:217], v[60:63]
	v_mfma_f32_16x16x32_bf16 v[96:99], v[162:165], v[182:185], v[96:99]
	v_mfma_f32_16x16x32_bf16 v[92:95], v[170:173], v[182:185], v[92:95]
	v_mfma_f32_16x16x32_bf16 v[88:91], v[162:165], v[190:193], v[88:91]
	v_mfma_f32_16x16x32_bf16 v[84:87], v[170:173], v[190:193], v[84:87]
	v_mfma_f32_16x16x32_bf16 v[80:83], v[162:165], v[198:201], v[80:83]
	v_mfma_f32_16x16x32_bf16 v[76:79], v[170:173], v[198:201], v[76:79]
	v_mfma_f32_16x16x32_bf16 v[68:71], v[162:165], v[218:221], v[68:71]
	v_mfma_f32_16x16x32_bf16 v[60:63], v[170:173], v[218:221], v[60:63]
	s_setprio 0
	s_barrier
	ds_read_b128 v[174:177], v153 offset:16384
	ds_read_b128 v[182:185], v153 offset:17408
	ds_read_b128 v[186:189], v153 offset:18432
	ds_read_b128 v[190:193], v153 offset:19456
	ds_read_b128 v[194:197], v153 offset:20480
	ds_read_b128 v[198:201], v153 offset:21504
	ds_read_b128 v[214:217], v153 offset:22528
	ds_read_b128 v[218:221], v153 offset:23552
	s_mov_b32 m0, s5
	s_nop 0
	global_load_lds_dwordx4 v147, s[38:39]
	s_mov_b32 m0, s6
	s_nop 0
	global_load_lds_dwordx4 v149, s[38:39]
	s_add_u32 s34, s38, 0x40000
	s_addc_u32 s35, s39, 0
	s_mov_b32 m0, s7
	s_nop 0
	global_load_lds_dwordx4 v147, s[34:35]
	s_mov_b32 m0, s8
	s_nop 0
	global_load_lds_dwordx4 v149, s[34:35]
	s_mov_b32 m0, s4
	s_nop 0
	global_load_lds_dwordx4 v146, s[40:41]
	s_mov_b32 m0, s9
	s_nop 0
	global_load_lds_dwordx4 v148, s[40:41]
	s_waitcnt vmcnt(8)
	s_waitcnt lgkmcnt(0)
	s_barrier
; #define PG8_STAGE(bufoff, gbase, voff) do { _Pragma("unroll") for (int _i = 0; _i < 2; ++_i) \
;         glds_s((voff)[_i], (const void*)(gbase), ldsbase + (unsigned)((bufoff) + _i * 8192)); } while (0)
; #define PG8_LDA(dst, b, h) do { _Pragma("unroll") for (int m = 0; m < 4; ++m) _Pragma("unroll") for (int k = 0; k < 2; ++k) dst[m][k] = *(const LAS bf16x8*)(lds + PG8_SA(b, h) + aoff + m * 2048 + k * 1024); } while (0)
; #define PG8_LDB(dst, b, h) do { _Pragma("unroll") for (int n = 0; n < 2; ++n) _Pragma("unroll") for (int k = 0; k < 2; ++k) dst[n][k] = *(const LAS bf16x8*)(lds + PG8_SB(b, h) + boff + n * 2048 + k * 1024); } while (0)
; #define PG8_MMA(ai, bj, At, Bt) do { __builtin_amdgcn_s_setprio(1); _Pragma("unroll") for (int m = 0; m < 4; ++m) _Pragma("unroll") for (int n = 0; n < 2; ++n) _Pragma("unroll") for (int k = 0; k < 2; ++k) \
;         acc[ai][bj][m][n] = __builtin_amdgcn_mfma_f32_16x16x32_bf16(Bt[n][k], At[m][k], acc[ai][bj][m][n], 0, 0, 0); __builtin_amdgcn_s_setprio(0); } while (0)
; #define PG8_WAIT_V(n) asm volatile("s_waitcnt vmcnt(" #n ")" ::: "memory")
; #define PG8_WAIT_L(n) asm volatile("s_waitcnt lgkmcnt(" #n ")" ::: "memory")
; #define PG8_BAR __builtin_amdgcn_s_barrier()
; #define PG8_SCHED __builtin_amdgcn_sched_barrier(0)
; template <class Epi, class Sched, bool ALIGN_EPI, bool SP2>
; __device__ __forceinline__ void gemm_phase(LAS unsigned char* lds, const int K, const Sched& S, const Epi& E) {
;     ...
;             PG8_WAIT_V(8); PG8_WAIT_L(0); PG8_BAR; PG8_MMA(1, 0, At, B0); PG8_MMA(1, 1, At, B1); PG8_BAR; PG8_SCHED;
;             PG8_LDB(B0, 1, 0); PG8_LDB(B1, 1, 1); PG8_SCHED; PG8_LDA(At, 1, 0); PG8_STAGE(PG8_SA(0, 1), a2 + hstep, voffA);
;             PG8_WAIT_V(8); PG8_WAIT_L(0); PG8_BAR; PG8_MMA(0, 0, At, B0); PG8_MMA(0, 1, At, B1); PG8_BAR; PG8_SCHED;
	s_setprio 1
	s_waitcnt lgkmcnt(7)
	v_mfma_f32_16x16x32_bf16 v[72:75], v[132:135], v[174:177], v[72:75]
	v_mfma_f32_16x16x32_bf16 v[64:67], v[140:143], v[174:177], v[64:67]
	s_waitcnt lgkmcnt(5)
	v_mfma_f32_16x16x32_bf16 v[56:59], v[132:135], v[186:189], v[56:59]
	v_mfma_f32_16x16x32_bf16 v[52:55], v[140:143], v[186:189], v[52:55]
	s_waitcnt lgkmcnt(3)
	v_mfma_f32_16x16x32_bf16 v[48:51], v[132:135], v[194:197], v[48:51]
	v_mfma_f32_16x16x32_bf16 v[44:47], v[140:143], v[194:197], v[44:47]
	s_waitcnt lgkmcnt(1)
	v_mfma_f32_16x16x32_bf16 v[40:43], v[132:135], v[214:217], v[40:43]
	v_mfma_f32_16x16x32_bf16 v[36:39], v[140:143], v[214:217], v[36:39]
	v_mfma_f32_16x16x32_bf16 v[72:75], v[136:139], v[182:185], v[72:75]
	v_mfma_f32_16x16x32_bf16 v[64:67], v[154:157], v[182:185], v[64:67]
	v_mfma_f32_16x16x32_bf16 v[56:59], v[136:139], v[190:193], v[56:59]
	v_mfma_f32_16x16x32_bf16 v[52:55], v[154:157], v[190:193], v[52:55]
	v_mfma_f32_16x16x32_bf16 v[48:51], v[136:139], v[198:201], v[48:51]
	v_mfma_f32_16x16x32_bf16 v[44:47], v[154:157], v[198:201], v[44:47]
	s_waitcnt lgkmcnt(0)
	v_mfma_f32_16x16x32_bf16 v[40:43], v[136:139], v[218:221], v[40:43]
	v_mfma_f32_16x16x32_bf16 v[36:39], v[154:157], v[218:221], v[36:39]
	s_setprio 0
	s_setprio 1
	v_mfma_f32_16x16x32_bf16 v[32:35], v[158:161], v[174:177], v[32:35]
	v_mfma_f32_16x16x32_bf16 v[28:31], v[166:169], v[174:177], v[28:31]
	v_mfma_f32_16x16x32_bf16 v[24:27], v[158:161], v[186:189], v[24:27]
	v_mfma_f32_16x16x32_bf16 v[20:23], v[166:169], v[186:189], v[20:23]
	v_mfma_f32_16x16x32_bf16 v[16:19], v[158:161], v[194:197], v[16:19]
	v_mfma_f32_16x16x32_bf16 v[12:15], v[166:169], v[194:197], v[12:15]
	v_mfma_f32_16x16x32_bf16 v[8:11], v[158:161], v[214:217], v[8:11]
	v_mfma_f32_16x16x32_bf16 v[2:5], v[166:169], v[214:217], v[4:7]
	v_mfma_f32_16x16x32_bf16 v[32:35], v[162:165], v[182:185], v[32:35]
	v_mfma_f32_16x16x32_bf16 v[28:31], v[170:173], v[182:185], v[28:31]
	v_mfma_f32_16x16x32_bf16 v[24:27], v[162:165], v[190:193], v[24:27]
	v_mfma_f32_16x16x32_bf16 v[20:23], v[170:173], v[190:193], v[20:23]
	v_mfma_f32_16x16x32_bf16 v[16:19], v[162:165], v[198:201], v[16:19]
	v_mfma_f32_16x16x32_bf16 v[12:15], v[170:173], v[198:201], v[12:15]
	v_mfma_f32_16x16x32_bf16 v[8:11], v[162:165], v[218:221], v[8:11]
	v_mfma_f32_16x16x32_bf16 v[2:5], v[170:173], v[218:221], v[2:5]
	s_setprio 0
	s_barrier
	v_add_u32_e32 v0, 0x18000, v152
	ds_read_b128 v[132:135], v0
	ds_read_b128 v[136:139], v0 offset:1024
	ds_read_b128 v[140:143], v0 offset:2048
	ds_read_b128 v[154:157], v0 offset:3072
	v_add_u32_e32 v0, 0x1c000, v152
	ds_read_b128 v[158:161], v0
	ds_read_b128 v[162:165], v0 offset:1024
	ds_read_b128 v[166:169], v0 offset:2048
	ds_read_b128 v[170:173], v0 offset:3072
	ds_read_b128 v[174:177], v153 offset:32768
	ds_read_b128 v[182:185], v153 offset:33792
	ds_read_b128 v[186:189], v153 offset:34816
	ds_read_b128 v[190:193], v153 offset:35840
	ds_read_b128 v[194:197], v153 offset:36864
	ds_read_b128 v[198:201], v153 offset:37888
	ds_read_b128 v[214:217], v153 offset:38912
	ds_read_b128 v[218:221], v153 offset:39936
	s_add_u32 s34, s40, 0x40000
	s_addc_u32 s35, s41, 0
	s_mov_b32 m0, s10
	s_nop 0
	global_load_lds_dwordx4 v146, s[34:35]
	s_mov_b32 m0, s11
	s_nop 0
	global_load_lds_dwordx4 v148, s[34:35]
	s_waitcnt vmcnt(8)
	s_waitcnt lgkmcnt(0)
	s_barrier
	s_setprio 1
	s_waitcnt lgkmcnt(7)
	v_mfma_f32_16x16x32_bf16 v[128:131], v[132:135], v[174:177], v[128:131]
	v_mfma_f32_16x16x32_bf16 v[124:127], v[140:143], v[174:177], v[124:127]
	s_waitcnt lgkmcnt(5)
	v_mfma_f32_16x16x32_bf16 v[120:123], v[132:135], v[186:189], v[120:123]
	v_mfma_f32_16x16x32_bf16 v[116:119], v[140:143], v[186:189], v[116:119]
	s_waitcnt lgkmcnt(3)
	v_mfma_f32_16x16x32_bf16 v[112:115], v[132:135], v[194:197], v[112:115]
	v_mfma_f32_16x16x32_bf16 v[108:111], v[140:143], v[194:197], v[108:111]
	s_waitcnt lgkmcnt(1)
	v_mfma_f32_16x16x32_bf16 v[104:107], v[132:135], v[214:217], v[104:107]
	v_mfma_f32_16x16x32_bf16 v[100:103], v[140:143], v[214:217], v[100:103]
	v_mfma_f32_16x16x32_bf16 v[128:131], v[136:139], v[182:185], v[128:131]
	v_mfma_f32_16x16x32_bf16 v[124:127], v[154:157], v[182:185], v[124:127]
	v_mfma_f32_16x16x32_bf16 v[120:123], v[136:139], v[190:193], v[120:123]
	v_mfma_f32_16x16x32_bf16 v[116:119], v[154:157], v[190:193], v[116:119]
	v_mfma_f32_16x16x32_bf16 v[112:115], v[136:139], v[198:201], v[112:115]
	v_mfma_f32_16x16x32_bf16 v[108:111], v[154:157], v[198:201], v[108:111]
	s_waitcnt lgkmcnt(0)
	v_mfma_f32_16x16x32_bf16 v[104:107], v[136:139], v[218:221], v[104:107]
	v_mfma_f32_16x16x32_bf16 v[100:103], v[154:157], v[218:221], v[100:103]
	s_setprio 0
	s_setprio 1
	v_mfma_f32_16x16x32_bf16 v[96:99], v[158:161], v[174:177], v[96:99]
	v_mfma_f32_16x16x32_bf16 v[92:95], v[166:169], v[174:177], v[92:95]
	v_mfma_f32_16x16x32_bf16 v[88:91], v[158:161], v[186:189], v[88:91]
	v_mfma_f32_16x16x32_bf16 v[84:87], v[166:169], v[186:189], v[84:87]
	v_mfma_f32_16x16x32_bf16 v[80:83], v[158:161], v[194:197], v[80:83]
	v_mfma_f32_16x16x32_bf16 v[76:79], v[166:169], v[194:197], v[76:79]
	v_mfma_f32_16x16x32_bf16 v[68:71], v[158:161], v[214:217], v[68:71]
	v_mfma_f32_16x16x32_bf16 v[60:63], v[166:169], v[214:217], v[60:63]
	v_mfma_f32_16x16x32_bf16 v[96:99], v[162:165], v[182:185], v[96:99]
	v_mfma_f32_16x16x32_bf16 v[92:95], v[170:173], v[182:185], v[92:95]
	v_mfma_f32_16x16x32_bf16 v[88:91], v[162:165], v[190:193], v[88:91]
	v_mfma_f32_16x16x32_bf16 v[84:87], v[170:173], v[190:193], v[84:87]
	v_mfma_f32_16x16x32_bf16 v[80:83], v[162:165], v[198:201], v[80:83]
	v_mfma_f32_16x16x32_bf16 v[76:79], v[170:173], v[198:201], v[76:79]
	v_mfma_f32_16x16x32_bf16 v[68:71], v[162:165], v[218:221], v[68:71]
	v_mfma_f32_16x16x32_bf16 v[60:63], v[170:173], v[218:221], v[60:63]
	s_setprio 0
	s_barrier
; #define PG8_STAGE(bufoff, gbase, voff) do { _Pragma("unroll") for (int _i = 0; _i < 2; ++_i) \
;         glds_s((voff)[_i], (const void*)(gbase), ldsbase + (unsigned)((bufoff) + _i * 8192)); } while (0)
; #define PG8_LDA(dst, b, h) do { _Pragma("unroll") for (int m = 0; m < 4; ++m) _Pragma("unroll") for (int k = 0; k < 2; ++k) dst[m][k] = *(const LAS bf16x8*)(lds + PG8_SA(b, h) + aoff + m * 2048 + k * 1024); } while (0)
; #define PG8_MMA(ai, bj, At, Bt) do { __builtin_amdgcn_s_setprio(1); _Pragma("unroll") for (int m = 0; m < 4; ++m) _Pragma("unroll") for (int n = 0; n < 2; ++n) _Pragma("unroll") for (int k = 0; k < 2; ++k) \
;         acc[ai][bj][m][n] = __builtin_amdgcn_mfma_f32_16x16x32_bf16(Bt[n][k], At[m][k], acc[ai][bj][m][n], 0, 0, 0); __builtin_amdgcn_s_setprio(0); } while (0)
; #define PG8_WAIT_V(n) asm volatile("s_waitcnt vmcnt(" #n ")" ::: "memory")
; #define PG8_WAIT_L(n) asm volatile("s_waitcnt lgkmcnt(" #n ")" ::: "memory")
; #define PG8_BAR __builtin_amdgcn_s_barrier()
; #define PG8_SCHED __builtin_amdgcn_sched_barrier(0)
; template <class Epi, class Sched, bool ALIGN_EPI, bool SP2>
; __device__ __forceinline__ void gemm_phase(LAS unsigned char* lds, const int K, const Sched& S, const Epi& E) {
;     ...
;             PG8_LDA(At, 1, 1); PG8_STAGE(PG8_SB(1, 0), b3, voffB); PG8_STAGE(PG8_SB(1, 1), b3 + hstep, voffB); PG8_STAGE(PG8_SA(1, 0), a3, voffA);
;             PG8_WAIT_V(8); PG8_WAIT_L(0); PG8_BAR; PG8_MMA(1, 0, At, B0); PG8_MMA(1, 1, At, B1); PG8_BAR; PG8_SCHED;
	ds_read_b128 v[174:177], v153 offset:49152
	ds_read_b128 v[182:185], v153 offset:50176
	ds_read_b128 v[186:189], v153 offset:51200
	ds_read_b128 v[190:193], v153 offset:52224
	ds_read_b128 v[194:197], v153 offset:53248
	ds_read_b128 v[198:201], v153 offset:54272
	ds_read_b128 v[214:217], v153 offset:55296
	ds_read_b128 v[218:221], v153 offset:56320
	s_add_u32 s34, s38, 0x80
	s_addc_u32 s35, s39, 0
	s_mov_b32 m0, s20
	s_nop 0
	global_load_lds_dwordx4 v147, s[34:35]
	s_mov_b32 m0, s21
	s_nop 0
	global_load_lds_dwordx4 v149, s[34:35]
	s_add_u32 s34, s38, 0x40080
	s_addc_u32 s35, s39, 0
	s_mov_b32 m0, s31
	s_nop 0
	global_load_lds_dwordx4 v147, s[34:35]
	s_mov_b32 m0, s42
	s_nop 0
	global_load_lds_dwordx4 v149, s[34:35]
	s_mov_b32 m0, s28
	s_nop 0
	global_load_lds_dwordx4 v146, s[36:37]
	s_mov_b32 m0, s30
	s_nop 0
	global_load_lds_dwordx4 v148, s[36:37]
	s_waitcnt vmcnt(8)
	s_waitcnt lgkmcnt(0)
	s_barrier
	s_setprio 1
	s_waitcnt lgkmcnt(7)
	v_mfma_f32_16x16x32_bf16 v[72:75], v[132:135], v[174:177], v[72:75]
	v_mfma_f32_16x16x32_bf16 v[64:67], v[140:143], v[174:177], v[64:67]
	s_waitcnt lgkmcnt(5)
	v_mfma_f32_16x16x32_bf16 v[56:59], v[132:135], v[186:189], v[56:59]
	v_mfma_f32_16x16x32_bf16 v[52:55], v[140:143], v[186:189], v[52:55]
	s_waitcnt lgkmcnt(3)
	v_mfma_f32_16x16x32_bf16 v[48:51], v[132:135], v[194:197], v[48:51]
	v_mfma_f32_16x16x32_bf16 v[44:47], v[140:143], v[194:197], v[44:47]
	s_waitcnt lgkmcnt(1)
	v_mfma_f32_16x16x32_bf16 v[40:43], v[132:135], v[214:217], v[40:43]
	v_mfma_f32_16x16x32_bf16 v[36:39], v[140:143], v[214:217], v[36:39]
	v_mfma_f32_16x16x32_bf16 v[72:75], v[136:139], v[182:185], v[72:75]
	v_mfma_f32_16x16x32_bf16 v[64:67], v[154:157], v[182:185], v[64:67]
	v_mfma_f32_16x16x32_bf16 v[56:59], v[136:139], v[190:193], v[56:59]
	v_mfma_f32_16x16x32_bf16 v[52:55], v[154:157], v[190:193], v[52:55]
	v_mfma_f32_16x16x32_bf16 v[48:51], v[136:139], v[198:201], v[48:51]
	v_mfma_f32_16x16x32_bf16 v[44:47], v[154:157], v[198:201], v[44:47]
	s_waitcnt lgkmcnt(0)
	v_mfma_f32_16x16x32_bf16 v[40:43], v[136:139], v[218:221], v[40:43]
	v_mfma_f32_16x16x32_bf16 v[36:39], v[154:157], v[218:221], v[36:39]
	s_setprio 0
	s_setprio 1
	v_mfma_f32_16x16x32_bf16 v[32:35], v[158:161], v[174:177], v[32:35]
	v_mfma_f32_16x16x32_bf16 v[28:31], v[166:169], v[174:177], v[28:31]
	v_mfma_f32_16x16x32_bf16 v[24:27], v[158:161], v[186:189], v[24:27]
	v_mfma_f32_16x16x32_bf16 v[20:23], v[166:169], v[186:189], v[20:23]
	v_mfma_f32_16x16x32_bf16 v[16:19], v[158:161], v[194:197], v[16:19]
	v_mfma_f32_16x16x32_bf16 v[12:15], v[166:169], v[194:197], v[12:15]
	v_mfma_f32_16x16x32_bf16 v[6:9], v[158:161], v[214:217], v[8:11]
	v_mfma_f32_16x16x32_bf16 v[2:5], v[166:169], v[214:217], v[2:5]
	v_mfma_f32_16x16x32_bf16 v[32:35], v[162:165], v[182:185], v[32:35]
	v_mfma_f32_16x16x32_bf16 v[28:31], v[170:173], v[182:185], v[28:31]
	v_mfma_f32_16x16x32_bf16 v[24:27], v[162:165], v[190:193], v[24:27]
	v_mfma_f32_16x16x32_bf16 v[20:23], v[170:173], v[190:193], v[20:23]
	v_mfma_f32_16x16x32_bf16 v[16:19], v[162:165], v[198:201], v[16:19]
	v_mfma_f32_16x16x32_bf16 v[12:15], v[170:173], v[198:201], v[12:15]
	v_mfma_f32_16x16x32_bf16 v[8:11], v[162:165], v[218:221], v[6:9]
	v_mfma_f32_16x16x32_bf16 v[4:7], v[170:173], v[218:221], v[2:5]
	s_setprio 0
	s_barrier
	s_add_i32 s53, s53, 2
	s_add_u32 s17, s17, 0x100
	s_addc_u32 s52, s52, 0
	s_cmp_gt_u32 s53, 13
	s_mov_b64 s[34:35], s[0:1]
	s_cbranch_scc0 .LBB0_685
	s_and_b64 vcc, exec, s[14:15]
	s_cbranch_vccz .LBB0_688
	s_barrier

; #define PG8_STAGE(bufoff, gbase, voff) do { _Pragma("unroll") for (int _i = 0; _i < 2; ++_i) \
;         glds_s((voff)[_i], (const void*)(gbase), ldsbase + (unsigned)((bufoff) + _i * 8192)); } while (0)
; #define PG8_WAIT_V(n) asm volatile("s_waitcnt vmcnt(" #n ")" ::: "memory")
; #define PG8_BAR __builtin_amdgcn_s_barrier()
; template <class Epi, class Sched, bool ALIGN_EPI, bool SP2>
; __device__ __forceinline__ void gemm_phase(LAS unsigned char* lds, const int K, const Sched& S, const Epi& E) {
;     ...
;     for (int i = 0; i < 2; ++i) { int R, C; stage_rc(tid * 16 + i * 8192, R, C); const int Rb = Epi::PERM ? ((R & ~31) + perm32(R & 31)) : R;
;         voffA[i] = (unsigned)(R * K + C) * 2u; voffB[i] = (unsigned)(Rb * K + C) * 2u; }
;     const size_t kstep = (size_t)(BK * 2);
;     const size_t hstep = (size_t)HALF * K * 2;
;     const unsigned ldsw = (unsigned)wid * 1024u;
;     const unsigned ldsbase = (unsigned)__builtin_amdgcn_readfirstlane((int)((unsigned)(uintptr_t)lds + ldsw));
;     const int aoff = lds_byte(wr * 64 + fr, fq * 8), boff = lds_byte(wc * 32 + fr, fq * 8);
;     ...
;     Unit cur, nxt; int ui = 0;
;     if (!S.next(0, cur)) return;
;     f32x4 acc[2][2][4][2];
; #pragma unroll
;     for (int a = 0; a < 2; ++a)
; #pragma unroll
;         for (int b = 0; b < 2; ++b)
; #pragma unroll
;             for (int m = 0; m < 4; ++m)
; #pragma unroll
;                 for (int n = 0; n < 2; ++n) acc[a][b][m][n] = (f32x4){0.f, 0.f, 0.f, 0.f};
;     bf16x8 At[4][2], B0[2][2], B1[2][2];
;     const char* cA = cur.A; const char* cB = cur.B;
;     if constexpr (SP2) {
;         PG8_STAGE(PG8_SB(0, 0), cB, voffB); PG8_STAGE(PG8_SB(0, 1), cB + hstep, voffB); PG8_STAGE(PG8_SA(0, 0), cA, voffA); PG8_STAGE(PG8_SA(0, 1), cA + hstep, voffA);
;         if (wr == 1) PG8_BAR;
;         PG8_WAIT_V(2); PG8_BAR;
;         PG8_STAGE(PG8_SB(1, 0), cB + kstep, voffB); PG8_STAGE(PG8_SA(1, 0), cA + kstep, voffA); PG8_STAGE(PG8_SB(1, 1), cB + hstep + kstep, voffB);
;         PG8_WAIT_V(6); PG8_BAR;
.LBB0_806:
	s_or_b64 exec, exec, s[0:1]
	s_waitcnt lgkmcnt(0)
	v_mov_b32_e32 v2, v202
	v_readlane_b32 s0, v250, 21
	s_barrier
	v_readlane_b32 s1, v250, 22
	v_readfirstlane_b32 s12, v2
	s_and_b64 vcc, exec, s[0:1]
	s_ashr_i32 s13, s12, 6
	s_cbranch_vccnz .LBB0_826
	v_bfe_i32 v4, v2, 27, 1
	v_lshlrev_b32_e32 v3, 4, v2
	v_lshrrev_b32_e32 v4, 22, v4
	v_add_u32_e32 v4, v3, v4
	v_and_b32_e32 v4, 0xfffffc00, v4
	v_sub_u32_e32 v4, v3, v4
	v_lshrrev_b32_e32 v5, 4, v4
	v_ashrrev_i32_e32 v0, 31, v2
	v_bitop3_b32 v4, v5, v4, 32 bitop3:0x6c
	v_lshrrev_b32_e32 v0, 26, v0
	v_ashrrev_i32_e32 v6, 31, v4
	v_add_u32_e32 v0, v2, v0
	v_lshrrev_b32_e32 v6, 26, v6
	v_ashrrev_i32_e32 v0, 6, v0
	v_add_u32_e32 v6, v4, v6
	v_lshlrev_b32_e32 v5, 3, v0
	v_lshrrev_b32_e32 v7, 6, v6
	v_and_b32_e32 v6, 0xc0, v6
	v_and_b32_e32 v5, 0xffff0, v5
	v_lshlrev_b32_e32 v0, 5, v0
	v_sub_u32_e32 v4, v4, v6
	v_add_u32_e32 v5, v7, v5
	v_and_b32_e32 v0, 32, v0
	v_ashrrev_i16_sdwa v4, v205, sext(v4) dst_sel:DWORD dst_unused:UNUSED_PAD src0_sel:DWORD src1_sel:BYTE_0
	v_bfe_i32 v4, v4, 0, 16
	v_lshl_or_b32 v0, v5, 11, v0
	v_add_u32_e32 v3, 0x2000, v3
	v_add_lshl_u32 v0, v0, v4, 1
	v_ashrrev_i32_e32 v4, 31, v3
	v_lshrrev_b32_e32 v4, 22, v4
	v_add_u32_e32 v4, v3, v4
	v_ashrrev_i32_e32 v4, 10, v4
	v_mul_i32_i24_e32 v5, 0x400, v4
	v_sub_u32_e32 v3, v3, v5
	v_lshrrev_b32_e32 v5, 4, v3
	v_bitop3_b32 v3, v5, v3, 32 bitop3:0x6c
	v_ashrrev_i32_e32 v6, 31, v3
	v_lshrrev_b32_e32 v6, 26, v6
	v_add_u32_e32 v6, v3, v6
	v_lshlrev_b32_e32 v5, 3, v4
	v_lshrrev_b32_e32 v7, 6, v6
	v_and_b32_e32 v6, 0xc0, v6
	v_and_b32_e32 v5, 0xffff0, v5
	v_lshlrev_b32_e32 v4, 5, v4
	v_sub_u32_e32 v3, v3, v6
	s_lshl_b32 s0, s13, 10
	v_add_u32_e32 v5, v7, v5
	v_and_b32_e32 v4, 32, v4
	v_ashrrev_i16_sdwa v3, v205, sext(v3) dst_sel:DWORD dst_unused:UNUSED_PAD src0_sel:DWORD src1_sel:BYTE_0
	s_add_i32 s4, s0, 0
	v_readlane_b32 s8, v252, 54
	v_bfe_i32 v3, v3, 0, 16
	v_lshl_or_b32 v4, v5, 11, v4
	s_add_i32 s5, s4, 0x10000
	v_readlane_b32 s9, v252, 55
	s_mov_b32 m0, s5
	s_nop 0
	global_load_lds_dwordx4 v0, s[8:9]
	s_waitcnt vmcnt(21)
	v_add_lshl_u32 v152, v4, v3, 1
	s_add_i32 s6, s4, 0x12000
	s_mov_b32 m0, s6
	s_nop 0
	global_load_lds_dwordx4 v152, s[8:9]
	v_readlane_b32 s10, v252, 44
	s_add_i32 s7, s4, 0x14000
	v_readlane_b32 s11, v252, 45
	s_mov_b32 m0, s7
	s_nop 0
	global_load_lds_dwordx4 v0, s[10:11]
	s_add_i32 s8, s4, 0x16000
	s_mov_b32 m0, s8
	s_nop 0
	global_load_lds_dwordx4 v152, s[10:11]
	v_readlane_b32 s10, v252, 50
	v_readlane_b32 s11, v252, 51
	s_mov_b32 m0, s4
	s_nop 0
	global_load_lds_dwordx4 v0, s[10:11]
	s_add_i32 s9, s4, 0x2000
	s_mov_b32 m0, s9
	s_nop 0
	global_load_lds_dwordx4 v152, s[10:11]
	v_readlane_b32 s16, v252, 46
	s_add_i32 s10, s4, 0x4000
	v_readlane_b32 s17, v252, 47
	s_mov_b32 m0, s10
	s_nop 0
	global_load_lds_dwordx4 v0, s[16:17]
	s_ashr_i32 s14, s12, 8
	s_add_i32 s11, s4, 0x6000
	s_mov_b32 m0, s11
	s_nop 0
	global_load_lds_dwordx4 v152, s[16:17]
	s_cmp_eq_u32 s14, 1
	s_cselect_b64 s[0:1], -1, 0
	s_cmp_lg_u32 s14, 1
	s_cbranch_scc1 .LBB0_809
	s_barrier
.LBB0_809:
	v_readlane_b32 s15, v250, 19
	v_bfe_u32 v3, v2, 4, 2
	s_add_u32 s20, s15, 0x4000
	v_readlane_b32 s15, v250, 20
	v_and_b32_e32 v4, 15, v2
	v_lshlrev_b32_e32 v5, 4, v3
	v_lshlrev_b32_e32 v2, 2, v2
	s_addc_u32 s21, s15, 0
	v_lshl_or_b32 v153, s14, 6, v4
	v_lshl_or_b32 v4, v4, 6, v5
	s_lshl_b32 s14, s14, 13
	v_and_b32_e32 v2, 32, v2
	s_lshl_b32 s13, s13, 5
	v_bitop3_b32 v5, v4, s14, v2 bitop3:0xde
	s_and_b32 s14, s13, 0x60
	s_lshl_b32 s13, s14, 7
	v_readlane_b32 s16, v252, 48
	v_bitop3_b32 v2, v4, s13, v2 bitop3:0xde
	s_waitcnt vmcnt(2)
	s_barrier
	s_add_i32 s28, s4, 0x18000
	v_readlane_b32 s17, v252, 49
	s_mov_b32 m0, s28
	s_nop 0
	global_load_lds_dwordx4 v0, s[16:17]
	s_add_i32 s30, s4, 0x1a000
	s_mov_b32 m0, s30
	s_nop 0
	global_load_lds_dwordx4 v152, s[16:17]
	v_readlane_b32 s16, v252, 52
	s_add_i32 s31, s4, 0x8000
	v_readlane_b32 s17, v252, 53
	s_mov_b32 m0, s31
	s_nop 0
	global_load_lds_dwordx4 v0, s[16:17]
	s_add_i32 s38, s4, 0xa000
	s_mov_b32 m0, s38
	s_nop 0
	global_load_lds_dwordx4 v152, s[16:17]
	v_readlane_b32 s16, v252, 56
	s_add_i32 s39, s4, 0x1c000
	v_readlane_b32 s17, v252, 57
	s_mov_b32 m0, s39
	s_nop 0
	global_load_lds_dwordx4 v0, s[16:17]
	s_add_i32 s40, s4, 0x1e000
	s_mov_b32 m0, s40
	s_nop 0
	global_load_lds_dwordx4 v152, s[16:17]
	s_waitcnt vmcnt(6)
	s_add_i32 s41, s4, 0xc000
	v_readlane_b32 s26, v252, 54
	v_readlane_b32 s24, v252, 50
	s_cmpk_lt_u32 s12, 0x100
	v_lshl_or_b32 v154, v3, 2, s14
	v_readlane_b32 s14, v253, 1
	v_readlane_b32 s27, v252, 55
	v_readlane_b32 s25, v252, 51
	s_cselect_b64 s[12:13], -1, 0
	s_add_i32 s42, s4, 0xe000
	s_mov_b32 s43, 0
	v_add_u32_e32 v155, 0, v2
	s_waitcnt vmcnt(17)
	v_add_u32_e32 v156, 0, v5
	v_readlane_b32 s46, v253, 3
	s_mov_b32 s45, s14
	s_mov_b64 s[18:19], s[24:25]
	s_mov_b64 s[22:23], s[26:27]
	s_barrier
	v_readlane_b32 s15, v253, 2
	s_branch .LBB0_812

; #define PG8_STAGE(bufoff, gbase, voff) do { _Pragma("unroll") for (int _i = 0; _i < 2; ++_i) \
;         glds_s((voff)[_i], (const void*)(gbase), ldsbase + (unsigned)((bufoff) + _i * 8192)); } while (0)
; #define PG8_LDA(dst, b, h) do { _Pragma("unroll") for (int m = 0; m < 4; ++m) _Pragma("unroll") for (int k = 0; k < 2; ++k) dst[m][k] = *(const LAS bf16x8*)(lds + PG8_SA(b, h) + aoff + m * 2048 + k * 1024); } while (0)
; #define PG8_LDB(dst, b, h) do { _Pragma("unroll") for (int n = 0; n < 2; ++n) _Pragma("unroll") for (int k = 0; k < 2; ++k) dst[n][k] = *(const LAS bf16x8*)(lds + PG8_SB(b, h) + boff + n * 2048 + k * 1024); } while (0)
; #define PG8_MMA(ai, bj, At, Bt) do { __builtin_amdgcn_s_setprio(1); _Pragma("unroll") for (int m = 0; m < 4; ++m) _Pragma("unroll") for (int n = 0; n < 2; ++n) _Pragma("unroll") for (int k = 0; k < 2; ++k) \
;         acc[ai][bj][m][n] = __builtin_amdgcn_mfma_f32_16x16x32_bf16(Bt[n][k], At[m][k], acc[ai][bj][m][n], 0, 0, 0); __builtin_amdgcn_s_setprio(0); } while (0)
; #define PG8_WAIT_V(n) asm volatile("s_waitcnt vmcnt(" #n ")" ::: "memory")
; #define PG8_WAIT_L(n) asm volatile("s_waitcnt lgkmcnt(" #n ")" ::: "memory")
; #define PG8_BAR __builtin_amdgcn_s_barrier()
; #define PG8_SCHED __builtin_amdgcn_sched_barrier(0)
; template <class Epi, class Sched, bool ALIGN_EPI, bool SP2>
; __device__ __forceinline__ void gemm_phase(LAS unsigned char* lds, const int K, const Sched& S, const Epi& E) {
;     ...
;             PG8_LDB(B0, 0, 0); PG8_LDB(B1, 0, 1); PG8_SCHED; PG8_LDA(At, 0, 0); PG8_STAGE(PG8_SA(1, 1), a1 + hstep, voffA);
;             PG8_WAIT_V(8); PG8_WAIT_L(0); PG8_BAR; PG8_MMA(0, 0, At, B0); PG8_MMA(0, 1, At, B1); PG8_BAR; PG8_SCHED;
;             PG8_LDA(At, 0, 1); PG8_STAGE(PG8_SB(0, 0), b2, voffB); PG8_STAGE(PG8_SB(0, 1), b2 + hstep, voffB); PG8_STAGE(PG8_SA(0, 0), a2, voffA);
;             PG8_WAIT_V(8); PG8_WAIT_L(0); PG8_BAR; PG8_MMA(1, 0, At, B0); PG8_MMA(1, 1, At, B1); PG8_BAR; PG8_SCHED;
;             PG8_LDB(B0, 1, 0); PG8_LDB(B1, 1, 1); PG8_SCHED; PG8_LDA(At, 1, 0); PG8_STAGE(PG8_SA(0, 1), a2 + hstep, voffA);
;             PG8_WAIT_V(8); PG8_WAIT_L(0); PG8_BAR; PG8_MMA(0, 0, At, B0); PG8_MMA(0, 1, At, B1); PG8_BAR; PG8_SCHED;
.LBB0_819:
	v_add_u32_e32 v142, 0x10000, v155
	v_add_u32_e32 v150, 0x14000, v155
	ds_read_b128 v[126:129], v142
	ds_read_b128 v[130:133], v142 offset:1024
	ds_read_b128 v[134:137], v142 offset:2048
	ds_read_b128 v[142:145], v142 offset:3072
	ds_read_b128 v[146:149], v150
	ds_read_b128 v[158:161], v150 offset:1024
	ds_read_b128 v[162:165], v150 offset:2048
	ds_read_b128 v[166:169], v150 offset:3072
	s_cmp_eq_u32 s53, 28
	s_cselect_b32 s24, s18, s15
	s_cselect_b32 s25, s19, s47
	s_cselect_b32 s36, s22, s51
	s_cselect_b32 s37, s23, s52
	s_add_u32 s34, s24, 0x80
	s_addc_u32 s35, s25, 0
	ds_read_b128 v[170:173], v156
	ds_read_b128 v[174:177], v156 offset:1024
	ds_read_b128 v[182:185], v156 offset:2048
	ds_read_b128 v[186:189], v156 offset:3072
	ds_read_b128 v[190:193], v156 offset:4096
	ds_read_b128 v[194:197], v156 offset:5120
	ds_read_b128 v[198:201], v156 offset:6144
	ds_read_b128 v[214:217], v156 offset:7168
	s_mov_b32 m0, s41
	s_nop 0
	global_load_lds_dwordx4 v0, s[26:27]
	s_mov_b32 m0, s42
	s_nop 0
	global_load_lds_dwordx4 v152, s[26:27]
	s_waitcnt vmcnt(8)
	s_waitcnt lgkmcnt(0)
	s_barrier
	s_setprio 1
	s_waitcnt lgkmcnt(7)
	v_mfma_f32_16x16x32_bf16 v[138:141], v[126:129], v[170:173], v[138:141]
	v_mfma_f32_16x16x32_bf16 v[122:125], v[134:137], v[170:173], v[122:125]
	s_waitcnt lgkmcnt(5)
	v_mfma_f32_16x16x32_bf16 v[110:113], v[126:129], v[182:185], v[110:113]
	v_mfma_f32_16x16x32_bf16 v[106:109], v[134:137], v[182:185], v[106:109]
	s_waitcnt lgkmcnt(3)
	v_mfma_f32_16x16x32_bf16 v[94:97], v[126:129], v[190:193], v[94:97]
	v_mfma_f32_16x16x32_bf16 v[90:93], v[134:137], v[190:193], v[90:93]
	s_waitcnt lgkmcnt(1)
	v_mfma_f32_16x16x32_bf16 v[78:81], v[126:129], v[198:201], v[78:81]
	v_mfma_f32_16x16x32_bf16 v[74:77], v[134:137], v[198:201], v[74:77]
	v_mfma_f32_16x16x32_bf16 v[138:141], v[130:133], v[174:177], v[138:141]
	v_mfma_f32_16x16x32_bf16 v[122:125], v[142:145], v[174:177], v[122:125]
	v_mfma_f32_16x16x32_bf16 v[110:113], v[130:133], v[186:189], v[110:113]
	v_mfma_f32_16x16x32_bf16 v[106:109], v[142:145], v[186:189], v[106:109]
	v_mfma_f32_16x16x32_bf16 v[94:97], v[130:133], v[194:197], v[94:97]
	v_mfma_f32_16x16x32_bf16 v[90:93], v[142:145], v[194:197], v[90:93]
	s_waitcnt lgkmcnt(0)
	v_mfma_f32_16x16x32_bf16 v[78:81], v[130:133], v[214:217], v[78:81]
	v_mfma_f32_16x16x32_bf16 v[74:77], v[142:145], v[214:217], v[74:77]
	s_setprio 0
	s_setprio 1
	v_mfma_f32_16x16x32_bf16 v[118:121], v[146:149], v[170:173], v[118:121]
	v_mfma_f32_16x16x32_bf16 v[114:117], v[162:165], v[170:173], v[114:117]
	v_mfma_f32_16x16x32_bf16 v[102:105], v[146:149], v[182:185], v[102:105]
	v_mfma_f32_16x16x32_bf16 v[98:101], v[162:165], v[182:185], v[98:101]
	v_mfma_f32_16x16x32_bf16 v[86:89], v[146:149], v[190:193], v[86:89]
	v_mfma_f32_16x16x32_bf16 v[82:85], v[162:165], v[190:193], v[82:85]
	v_mfma_f32_16x16x32_bf16 v[70:73], v[146:149], v[198:201], v[70:73]
	v_mfma_f32_16x16x32_bf16 v[66:69], v[162:165], v[198:201], v[66:69]
	v_mfma_f32_16x16x32_bf16 v[118:121], v[158:161], v[174:177], v[118:121]
	v_mfma_f32_16x16x32_bf16 v[114:117], v[166:169], v[174:177], v[114:117]
	v_mfma_f32_16x16x32_bf16 v[102:105], v[158:161], v[186:189], v[102:105]
	v_mfma_f32_16x16x32_bf16 v[98:101], v[166:169], v[186:189], v[98:101]
	v_mfma_f32_16x16x32_bf16 v[86:89], v[158:161], v[194:197], v[86:89]
	v_mfma_f32_16x16x32_bf16 v[82:85], v[166:169], v[194:197], v[82:85]
	v_mfma_f32_16x16x32_bf16 v[70:73], v[158:161], v[214:217], v[70:73]
	v_mfma_f32_16x16x32_bf16 v[66:69], v[166:169], v[214:217], v[66:69]
	s_setprio 0
	s_barrier
	ds_read_b128 v[170:173], v156 offset:16384
	ds_read_b128 v[174:177], v156 offset:17408
	ds_read_b128 v[182:185], v156 offset:18432
	ds_read_b128 v[186:189], v156 offset:19456
	ds_read_b128 v[190:193], v156 offset:20480
	ds_read_b128 v[194:197], v156 offset:21504
	ds_read_b128 v[198:201], v156 offset:22528
	ds_read_b128 v[214:217], v156 offset:23552
	s_mov_b32 m0, s5
	s_nop 0
	global_load_lds_dwordx4 v0, s[36:37]
	s_mov_b32 m0, s6
	s_nop 0
	global_load_lds_dwordx4 v152, s[36:37]
	s_add_u32 s54, s36, 0x80000
	s_addc_u32 s55, s37, 0
	s_mov_b32 m0, s7
	s_nop 0
	global_load_lds_dwordx4 v0, s[54:55]
	s_mov_b32 m0, s8
	s_nop 0
	global_load_lds_dwordx4 v152, s[54:55]
	s_mov_b32 m0, s4
	s_nop 0
	global_load_lds_dwordx4 v0, s[24:25]
	s_mov_b32 m0, s9
	s_nop 0
	global_load_lds_dwordx4 v152, s[24:25]
	s_waitcnt vmcnt(8)
	s_waitcnt lgkmcnt(0)
	s_barrier
	s_setprio 1
	s_waitcnt lgkmcnt(7)
	v_mfma_f32_16x16x32_bf16 v[62:65], v[126:129], v[170:173], v[62:65]
	v_mfma_f32_16x16x32_bf16 v[58:61], v[134:137], v[170:173], v[58:61]
	s_waitcnt lgkmcnt(5)
	v_mfma_f32_16x16x32_bf16 v[46:49], v[126:129], v[182:185], v[46:49]
	v_mfma_f32_16x16x32_bf16 v[42:45], v[134:137], v[182:185], v[42:45]
	s_waitcnt lgkmcnt(3)
	v_mfma_f32_16x16x32_bf16 v[30:33], v[126:129], v[190:193], v[30:33]
	v_mfma_f32_16x16x32_bf16 v[26:29], v[134:137], v[190:193], v[26:29]
	s_waitcnt lgkmcnt(1)
	v_mfma_f32_16x16x32_bf16 v[14:17], v[126:129], v[198:201], v[14:17]
	v_mfma_f32_16x16x32_bf16 v[10:13], v[134:137], v[198:201], v[10:13]
	v_mfma_f32_16x16x32_bf16 v[62:65], v[130:133], v[174:177], v[62:65]
	v_mfma_f32_16x16x32_bf16 v[58:61], v[142:145], v[174:177], v[58:61]
	v_mfma_f32_16x16x32_bf16 v[46:49], v[130:133], v[186:189], v[46:49]
	v_mfma_f32_16x16x32_bf16 v[42:45], v[142:145], v[186:189], v[42:45]
	v_mfma_f32_16x16x32_bf16 v[30:33], v[130:133], v[194:197], v[30:33]
	v_mfma_f32_16x16x32_bf16 v[26:29], v[142:145], v[194:197], v[26:29]
	s_waitcnt lgkmcnt(0)
	v_mfma_f32_16x16x32_bf16 v[14:17], v[130:133], v[214:217], v[14:17]
	v_mfma_f32_16x16x32_bf16 v[10:13], v[142:145], v[214:217], v[10:13]
	s_setprio 0
	s_setprio 1
	v_mfma_f32_16x16x32_bf16 v[54:57], v[146:149], v[170:173], v[54:57]
	v_mfma_f32_16x16x32_bf16 v[50:53], v[162:165], v[170:173], v[50:53]
	v_mfma_f32_16x16x32_bf16 v[38:41], v[146:149], v[182:185], v[38:41]
	v_mfma_f32_16x16x32_bf16 v[34:37], v[162:165], v[182:185], v[34:37]
	v_mfma_f32_16x16x32_bf16 v[22:25], v[146:149], v[190:193], v[22:25]
	v_mfma_f32_16x16x32_bf16 v[18:21], v[162:165], v[190:193], v[18:21]
	v_mfma_f32_16x16x32_bf16 v[6:9], v[146:149], v[198:201], v[6:9]
	v_mfma_f32_16x16x32_bf16 v[2:5], v[162:165], v[198:201], v[2:5]
	v_mfma_f32_16x16x32_bf16 v[54:57], v[158:161], v[174:177], v[54:57]
	v_mfma_f32_16x16x32_bf16 v[50:53], v[166:169], v[174:177], v[50:53]
	v_mfma_f32_16x16x32_bf16 v[38:41], v[158:161], v[186:189], v[38:41]
	v_mfma_f32_16x16x32_bf16 v[34:37], v[166:169], v[186:189], v[34:37]
	v_mfma_f32_16x16x32_bf16 v[22:25], v[158:161], v[194:197], v[22:25]
	v_mfma_f32_16x16x32_bf16 v[18:21], v[166:169], v[194:197], v[18:21]
	v_mfma_f32_16x16x32_bf16 v[6:9], v[158:161], v[214:217], v[6:9]
	v_mfma_f32_16x16x32_bf16 v[2:5], v[166:169], v[214:217], v[2:5]
	s_setprio 0
	s_barrier
; #define PG8_STAGE(bufoff, gbase, voff) do { _Pragma("unroll") for (int _i = 0; _i < 2; ++_i) \
;         glds_s((voff)[_i], (const void*)(gbase), ldsbase + (unsigned)((bufoff) + _i * 8192)); } while (0)
; #define PG8_LDA(dst, b, h) do { _Pragma("unroll") for (int m = 0; m < 4; ++m) _Pragma("unroll") for (int k = 0; k < 2; ++k) dst[m][k] = *(const LAS bf16x8*)(lds + PG8_SA(b, h) + aoff + m * 2048 + k * 1024); } while (0)
; #define PG8_LDB(dst, b, h) do { _Pragma("unroll") for (int n = 0; n < 2; ++n) _Pragma("unroll") for (int k = 0; k < 2; ++k) dst[n][k] = *(const LAS bf16x8*)(lds + PG8_SB(b, h) + boff + n * 2048 + k * 1024); } while (0)
; #define PG8_MMA(ai, bj, At, Bt) do { __builtin_amdgcn_s_setprio(1); _Pragma("unroll") for (int m = 0; m < 4; ++m) _Pragma("unroll") for (int n = 0; n < 2; ++n) _Pragma("unroll") for (int k = 0; k < 2; ++k) \
;         acc[ai][bj][m][n] = __builtin_amdgcn_mfma_f32_16x16x32_bf16(Bt[n][k], At[m][k], acc[ai][bj][m][n], 0, 0, 0); __builtin_amdgcn_s_setprio(0); } while (0)
; #define PG8_WAIT_V(n) asm volatile("s_waitcnt vmcnt(" #n ")" ::: "memory")
; #define PG8_WAIT_L(n) asm volatile("s_waitcnt lgkmcnt(" #n ")" ::: "memory")
; #define PG8_BAR __builtin_amdgcn_s_barrier()
; #define PG8_SCHED __builtin_amdgcn_sched_barrier(0)
; template <class Epi, class Sched, bool ALIGN_EPI, bool SP2>
; __device__ __forceinline__ void gemm_phase(LAS unsigned char* lds, const int K, const Sched& S, const Epi& E) {
;     ...
;             PG8_LDB(B0, 1, 0); PG8_LDB(B1, 1, 1); PG8_SCHED; PG8_LDA(At, 1, 0); PG8_STAGE(PG8_SA(0, 1), a2 + hstep, voffA);
;             PG8_WAIT_V(8); PG8_WAIT_L(0); PG8_BAR; PG8_MMA(0, 0, At, B0); PG8_MMA(0, 1, At, B1); PG8_BAR; PG8_SCHED;
;             PG8_LDA(At, 1, 1); PG8_STAGE(PG8_SB(1, 0), b3, voffB); PG8_STAGE(PG8_SB(1, 1), b3 + hstep, voffB); PG8_STAGE(PG8_SA(1, 0), a3, voffA);
;             PG8_WAIT_V(8); PG8_WAIT_L(0); PG8_BAR; PG8_MMA(1, 0, At, B0); PG8_MMA(1, 1, At, B1); PG8_BAR; PG8_SCHED;
	v_add_u32_e32 v142, 0x18000, v155
	v_add_u32_e32 v150, 0x1c000, v155
	ds_read_b128 v[126:129], v142
	ds_read_b128 v[130:133], v142 offset:1024
	ds_read_b128 v[134:137], v142 offset:2048
	ds_read_b128 v[142:145], v142 offset:3072
	ds_read_b128 v[146:149], v150
	ds_read_b128 v[158:161], v150 offset:1024
	ds_read_b128 v[162:165], v150 offset:2048
	ds_read_b128 v[166:169], v150 offset:3072
	ds_read_b128 v[170:173], v156 offset:32768
	ds_read_b128 v[174:177], v156 offset:33792
	ds_read_b128 v[182:185], v156 offset:34816
	ds_read_b128 v[186:189], v156 offset:35840
	ds_read_b128 v[190:193], v156 offset:36864
	ds_read_b128 v[194:197], v156 offset:37888
	ds_read_b128 v[198:201], v156 offset:38912
	ds_read_b128 v[214:217], v156 offset:39936
	s_add_u32 s24, s24, 0x80000
	s_addc_u32 s25, s25, 0
	s_mov_b32 m0, s10
	s_nop 0
	global_load_lds_dwordx4 v0, s[24:25]
	s_mov_b32 m0, s11
	s_nop 0
	global_load_lds_dwordx4 v152, s[24:25]
	s_waitcnt vmcnt(8)
	s_waitcnt lgkmcnt(0)
	s_barrier
	s_setprio 1
	s_waitcnt lgkmcnt(7)
	v_mfma_f32_16x16x32_bf16 v[138:141], v[126:129], v[170:173], v[138:141]
	v_mfma_f32_16x16x32_bf16 v[122:125], v[134:137], v[170:173], v[122:125]
	s_waitcnt lgkmcnt(5)
	v_mfma_f32_16x16x32_bf16 v[110:113], v[126:129], v[182:185], v[110:113]
	v_mfma_f32_16x16x32_bf16 v[106:109], v[134:137], v[182:185], v[106:109]
	s_waitcnt lgkmcnt(3)
	v_mfma_f32_16x16x32_bf16 v[94:97], v[126:129], v[190:193], v[94:97]
	v_mfma_f32_16x16x32_bf16 v[90:93], v[134:137], v[190:193], v[90:93]
	s_waitcnt lgkmcnt(1)
	v_mfma_f32_16x16x32_bf16 v[78:81], v[126:129], v[198:201], v[78:81]
	v_mfma_f32_16x16x32_bf16 v[74:77], v[134:137], v[198:201], v[74:77]
	v_mfma_f32_16x16x32_bf16 v[138:141], v[130:133], v[174:177], v[138:141]
	v_mfma_f32_16x16x32_bf16 v[122:125], v[142:145], v[174:177], v[122:125]
	v_mfma_f32_16x16x32_bf16 v[110:113], v[130:133], v[186:189], v[110:113]
	v_mfma_f32_16x16x32_bf16 v[106:109], v[142:145], v[186:189], v[106:109]
	v_mfma_f32_16x16x32_bf16 v[94:97], v[130:133], v[194:197], v[94:97]
	v_mfma_f32_16x16x32_bf16 v[90:93], v[142:145], v[194:197], v[90:93]
	s_waitcnt lgkmcnt(0)
	v_mfma_f32_16x16x32_bf16 v[78:81], v[130:133], v[214:217], v[78:81]
	v_mfma_f32_16x16x32_bf16 v[74:77], v[142:145], v[214:217], v[74:77]
	s_setprio 0
	s_setprio 1
	v_mfma_f32_16x16x32_bf16 v[118:121], v[146:149], v[170:173], v[118:121]
	v_mfma_f32_16x16x32_bf16 v[114:117], v[162:165], v[170:173], v[114:117]
	v_mfma_f32_16x16x32_bf16 v[102:105], v[146:149], v[182:185], v[102:105]
	v_mfma_f32_16x16x32_bf16 v[98:101], v[162:165], v[182:185], v[98:101]
	v_mfma_f32_16x16x32_bf16 v[86:89], v[146:149], v[190:193], v[86:89]
	v_mfma_f32_16x16x32_bf16 v[82:85], v[162:165], v[190:193], v[82:85]
	v_mfma_f32_16x16x32_bf16 v[70:73], v[146:149], v[198:201], v[70:73]
	v_mfma_f32_16x16x32_bf16 v[66:69], v[162:165], v[198:201], v[66:69]
	v_mfma_f32_16x16x32_bf16 v[118:121], v[158:161], v[174:177], v[118:121]
	v_mfma_f32_16x16x32_bf16 v[114:117], v[166:169], v[174:177], v[114:117]
	v_mfma_f32_16x16x32_bf16 v[102:105], v[158:161], v[186:189], v[102:105]
	v_mfma_f32_16x16x32_bf16 v[98:101], v[166:169], v[186:189], v[98:101]
	v_mfma_f32_16x16x32_bf16 v[86:89], v[158:161], v[194:197], v[86:89]
	v_mfma_f32_16x16x32_bf16 v[82:85], v[166:169], v[194:197], v[82:85]
	v_mfma_f32_16x16x32_bf16 v[70:73], v[158:161], v[214:217], v[70:73]
	v_mfma_f32_16x16x32_bf16 v[66:69], v[166:169], v[214:217], v[66:69]
	s_setprio 0
	s_barrier
	ds_read_b128 v[170:173], v156 offset:49152
	ds_read_b128 v[174:177], v156 offset:50176
	ds_read_b128 v[182:185], v156 offset:51200
	ds_read_b128 v[186:189], v156 offset:52224
	ds_read_b128 v[190:193], v156 offset:53248
	ds_read_b128 v[194:197], v156 offset:54272
	ds_read_b128 v[198:201], v156 offset:55296
	ds_read_b128 v[214:217], v156 offset:56320
	s_add_u32 s24, s36, 0x80
	s_addc_u32 s25, s37, 0
	s_mov_b32 m0, s28
	s_nop 0
	global_load_lds_dwordx4 v0, s[24:25]
	s_mov_b32 m0, s30
	s_nop 0
	global_load_lds_dwordx4 v152, s[24:25]
	s_add_u32 s24, s36, 0x80080
	s_addc_u32 s25, s37, 0
	s_mov_b32 m0, s39
	s_nop 0
	global_load_lds_dwordx4 v0, s[24:25]
	s_mov_b32 m0, s40
	s_nop 0
	global_load_lds_dwordx4 v152, s[24:25]
	s_mov_b32 m0, s31
	s_nop 0
	global_load_lds_dwordx4 v0, s[34:35]
	s_mov_b32 m0, s38
	s_nop 0
	global_load_lds_dwordx4 v152, s[34:35]
	s_waitcnt vmcnt(8)
	s_waitcnt lgkmcnt(0)
	s_barrier
	s_setprio 1
	s_waitcnt lgkmcnt(7)
	v_mfma_f32_16x16x32_bf16 v[62:65], v[126:129], v[170:173], v[62:65]
	v_mfma_f32_16x16x32_bf16 v[58:61], v[134:137], v[170:173], v[58:61]
	s_waitcnt lgkmcnt(5)
	v_mfma_f32_16x16x32_bf16 v[46:49], v[126:129], v[182:185], v[46:49]
	v_mfma_f32_16x16x32_bf16 v[42:45], v[134:137], v[182:185], v[42:45]
	s_waitcnt lgkmcnt(3)
	v_mfma_f32_16x16x32_bf16 v[30:33], v[126:129], v[190:193], v[30:33]
	v_mfma_f32_16x16x32_bf16 v[26:29], v[134:137], v[190:193], v[26:29]
	s_waitcnt lgkmcnt(1)
	v_mfma_f32_16x16x32_bf16 v[14:17], v[126:129], v[198:201], v[14:17]
	v_mfma_f32_16x16x32_bf16 v[10:13], v[134:137], v[198:201], v[10:13]
	v_mfma_f32_16x16x32_bf16 v[62:65], v[130:133], v[174:177], v[62:65]
	v_mfma_f32_16x16x32_bf16 v[58:61], v[142:145], v[174:177], v[58:61]
	v_mfma_f32_16x16x32_bf16 v[46:49], v[130:133], v[186:189], v[46:49]
	v_mfma_f32_16x16x32_bf16 v[42:45], v[142:145], v[186:189], v[42:45]
	v_mfma_f32_16x16x32_bf16 v[30:33], v[130:133], v[194:197], v[30:33]
	v_mfma_f32_16x16x32_bf16 v[26:29], v[142:145], v[194:197], v[26:29]
	s_waitcnt lgkmcnt(0)
	v_mfma_f32_16x16x32_bf16 v[14:17], v[130:133], v[214:217], v[14:17]
	v_mfma_f32_16x16x32_bf16 v[10:13], v[142:145], v[214:217], v[10:13]
	s_setprio 0
	s_setprio 1
	v_mfma_f32_16x16x32_bf16 v[54:57], v[146:149], v[170:173], v[54:57]
	v_mfma_f32_16x16x32_bf16 v[50:53], v[162:165], v[170:173], v[50:53]
	v_mfma_f32_16x16x32_bf16 v[38:41], v[146:149], v[182:185], v[38:41]
	v_mfma_f32_16x16x32_bf16 v[34:37], v[162:165], v[182:185], v[34:37]
	v_mfma_f32_16x16x32_bf16 v[22:25], v[146:149], v[190:193], v[22:25]
	v_mfma_f32_16x16x32_bf16 v[18:21], v[162:165], v[190:193], v[18:21]
	v_mfma_f32_16x16x32_bf16 v[6:9], v[146:149], v[198:201], v[6:9]
	v_mfma_f32_16x16x32_bf16 v[2:5], v[162:165], v[198:201], v[2:5]
	v_mfma_f32_16x16x32_bf16 v[54:57], v[158:161], v[174:177], v[54:57]
	v_mfma_f32_16x16x32_bf16 v[50:53], v[166:169], v[174:177], v[50:53]
	v_mfma_f32_16x16x32_bf16 v[38:41], v[158:161], v[186:189], v[38:41]
	v_mfma_f32_16x16x32_bf16 v[34:37], v[166:169], v[186:189], v[34:37]
	v_mfma_f32_16x16x32_bf16 v[22:25], v[158:161], v[194:197], v[22:25]
	v_mfma_f32_16x16x32_bf16 v[18:21], v[166:169], v[194:197], v[18:21]
	v_mfma_f32_16x16x32_bf16 v[6:9], v[158:161], v[214:217], v[6:9]
	v_mfma_f32_16x16x32_bf16 v[2:5], v[166:169], v[214:217], v[2:5]
	s_setprio 0
	s_barrier
	s_add_i32 s53, s53, 2
	s_add_u32 s15, s15, 0x100
	s_addc_u32 s47, s47, 0
	s_add_u32 s51, s51, 0x100
	s_addc_u32 s52, s52, 0
	s_add_u32 s26, s26, 0x100
	s_addc_u32 s27, s27, 0
	s_cmp_gt_u32 s53, 29
	s_cbranch_scc0 .LBB0_819
	s_and_b64 vcc, exec, s[12:13]
	s_mov_b64 s[52:53], 0x1d0000
	s_cbranch_vccz .LBB0_822
	s_barrier

; #define PG8_STAGE(bufoff, gbase, voff) do { _Pragma("unroll") for (int _i = 0; _i < 2; ++_i) \
;         glds_s((voff)[_i], (const void*)(gbase), ldsbase + (unsigned)((bufoff) + _i * 8192)); } while (0)
; #define PG8_WAIT_V(n) asm volatile("s_waitcnt vmcnt(" #n ")" ::: "memory")
; #define PG8_BAR __builtin_amdgcn_s_barrier()
; template <class Epi, class Sched, bool ALIGN_EPI, bool SP2>
; __device__ __forceinline__ void gemm_phase(LAS unsigned char* lds, const int K, const Sched& S, const Epi& E) {
;     ...
;     for (int i = 0; i < 2; ++i) { int R, C; stage_rc(tid * 16 + i * 8192, R, C); const int Rb = Epi::PERM ? ((R & ~31) + perm32(R & 31)) : R;
;         voffA[i] = (unsigned)(R * K + C) * 2u; voffB[i] = (unsigned)(Rb * K + C) * 2u; }
;     const size_t kstep = (size_t)(BK * 2);
;     const size_t hstep = (size_t)HALF * K * 2;
;     const unsigned ldsw = (unsigned)wid * 1024u;
;     const unsigned ldsbase = (unsigned)__builtin_amdgcn_readfirstlane((int)((unsigned)(uintptr_t)lds + ldsw));
;     const int aoff = lds_byte(wr * 64 + fr, fq * 8), boff = lds_byte(wc * 32 + fr, fq * 8);
;     ...
;     Unit cur, nxt; int ui = 0;
;     if (!S.next(0, cur)) return;
;     f32x4 acc[2][2][4][2];
; #pragma unroll
;     for (int a = 0; a < 2; ++a)
; #pragma unroll
;         for (int b = 0; b < 2; ++b)
; #pragma unroll
;             for (int m = 0; m < 4; ++m)
; #pragma unroll
;                 for (int n = 0; n < 2; ++n) acc[a][b][m][n] = (f32x4){0.f, 0.f, 0.f, 0.f};
;     bf16x8 At[4][2], B0[2][2], B1[2][2];
;     const char* cA = cur.A; const char* cB = cur.B;
;     if constexpr (SP2) {
;         PG8_STAGE(PG8_SB(0, 0), cB, voffB); PG8_STAGE(PG8_SB(0, 1), cB + hstep, voffB); PG8_STAGE(PG8_SA(0, 0), cA, voffA); PG8_STAGE(PG8_SA(0, 1), cA + hstep, voffA);
;         if (wr == 1) PG8_BAR;
;         PG8_WAIT_V(2); PG8_BAR;
;         PG8_STAGE(PG8_SB(1, 0), cB + kstep, voffB); PG8_STAGE(PG8_SA(1, 0), cA + kstep, voffA); PG8_STAGE(PG8_SB(1, 1), cB + hstep + kstep, voffB);
;         PG8_WAIT_V(6); PG8_BAR;
.LBB0_937:
	s_or_b64 exec, exec, s[0:1]
	v_readlane_b32 s4, v254, 8
	s_mul_i32 s0, s82, 0x21000
	v_readlane_b32 s14, v254, 18
	v_readlane_b32 s16, v254, 20
	v_readlane_b32 s5, v254, 9
	v_readlane_b32 s15, v254, 19
	v_readlane_b32 s17, v254, 21
	s_add_u32 s14, s16, s0
	v_readlane_b32 s18, v254, 22
	s_addc_u32 s15, s17, 0
	s_mul_i32 s0, s82, 0xb000
	v_mov_b32_e32 v0, v202
	v_readlane_b32 s4, v252, 36
	s_waitcnt lgkmcnt(0)
	s_barrier
	v_readlane_b32 s19, v254, 23
	s_add_u32 s22, s18, s0
	v_readlane_b32 s5, v252, 37
	v_readfirstlane_b32 s0, v0
	s_addc_u32 s23, s19, 0
	s_andn2_b64 vcc, exec, s[4:5]
	s_ashr_i32 s1, s0, 6
	v_readlane_b32 s6, v254, 10
	v_readlane_b32 s7, v254, 11
	v_readlane_b32 s8, v254, 12
	v_readlane_b32 s9, v254, 13
	v_readlane_b32 s10, v254, 14
	v_readlane_b32 s11, v254, 15
	v_readlane_b32 s12, v254, 16
	v_readlane_b32 s13, v254, 17
	s_cbranch_vccnz .LBB0_1000
	v_bfe_i32 v4, v0, 27, 1
	v_lshlrev_b32_e32 v2, 4, v0
	v_lshrrev_b32_e32 v4, 22, v4
	v_add_u32_e32 v4, v2, v4
	v_and_b32_e32 v4, 0xfffffc00, v4
	v_sub_u32_e32 v4, v2, v4
	v_ashrrev_i32_e32 v3, 31, v0
	v_lshrrev_b32_e32 v5, 4, v4
	v_lshrrev_b32_e32 v3, 26, v3
	v_bitop3_b32 v4, v5, v4, 32 bitop3:0x6c
	v_add_u32_e32 v3, v0, v3
	v_ashrrev_i32_e32 v6, 31, v4
	v_ashrrev_i32_e32 v3, 6, v3
	v_lshrrev_b32_e32 v6, 26, v6
	v_lshlrev_b32_e32 v5, 3, v3
	v_add_u32_e32 v6, v4, v6
	v_and_b32_e32 v5, -16, v5
	v_ashrrev_i32_e32 v7, 6, v6
	v_and_b32_e32 v6, 0xc0, v6
	v_add_u32_e32 v5, v7, v5
	v_sub_u32_e32 v4, v4, v6
	v_lshlrev_b32_e32 v3, 5, v3
	v_ashrrev_i16_sdwa v4, v205, sext(v4) dst_sel:DWORD dst_unused:UNUSED_PAD src0_sel:DWORD src1_sel:BYTE_0
	v_lshlrev_b32_e32 v6, 1, v5
	v_lshrrev_b32_e32 v8, 2, v5
	v_and_b32_e32 v7, 3, v7
	v_and_b32_e32 v3, 32, v3
	v_bfe_i32 v4, v4, 0, 16
	v_and_b32_e32 v6, 24, v6
	v_and_b32_e32 v8, 4, v8
	v_and_or_b32 v7, v5, s83, v7
	v_or3_b32 v6, v7, v8, v6
	v_add_lshl_u32 v3, v3, v4, 1
	v_add_u32_e32 v2, 0x2000, v2
	v_lshl_add_u32 v183, v5, 12, v3
	v_lshl_add_u32 v198, v6, 12, v3
	v_ashrrev_i32_e32 v3, 31, v2
	v_lshrrev_b32_e32 v3, 22, v3
	v_add_u32_e32 v3, v2, v3
	v_ashrrev_i32_e32 v3, 10, v3
	v_mul_i32_i24_e32 v4, 0x400, v3
	v_sub_u32_e32 v2, v2, v4
	v_lshrrev_b32_e32 v4, 4, v2
	v_bitop3_b32 v2, v4, v2, 32 bitop3:0x6c
	v_ashrrev_i32_e32 v5, 31, v2
	v_lshrrev_b32_e32 v5, 26, v5
	v_lshlrev_b32_e32 v4, 3, v3
	v_add_u32_e32 v5, v2, v5
	v_and_b32_e32 v4, -16, v4
	v_ashrrev_i32_e32 v6, 6, v5
	v_and_b32_e32 v5, 0xc0, v5
	v_add_u32_e32 v4, v6, v4
	v_sub_u32_e32 v2, v2, v5
	v_lshlrev_b32_e32 v3, 5, v3
	v_ashrrev_i16_sdwa v2, v205, sext(v2) dst_sel:DWORD dst_unused:UNUSED_PAD src0_sel:DWORD src1_sel:BYTE_0
	v_lshlrev_b32_e32 v5, 1, v4
	v_lshrrev_b32_e32 v7, 2, v4
	v_and_b32_e32 v6, 3, v6
	s_lshl_b32 s4, s1, 10
	v_and_b32_e32 v3, 32, v3
	v_bfe_i32 v2, v2, 0, 16
	v_and_b32_e32 v5, 24, v5
	v_and_b32_e32 v7, 4, v7
	v_and_or_b32 v6, v4, s83, v6
	s_add_i32 s28, s4, 0
	v_readlane_b32 s6, v253, 44
	v_or3_b32 v5, v6, v7, v5
	v_add_lshl_u32 v2, v3, v2, 1
	s_add_i32 s60, s28, 0x10000
	v_readlane_b32 s7, v253, 45
	s_mov_b32 m0, s60
	s_nop 0
	global_load_lds_dwordx4 v198, s[6:7]
	v_lshl_add_u32 v200, v5, 12, v2
	s_add_i32 s82, s28, 0x12000
	s_mov_b32 m0, s82
	s_nop 0
	global_load_lds_dwordx4 v200, s[6:7]
	v_readlane_b32 s6, v253, 34
	s_add_i32 s83, s28, 0x14000
	v_readlane_b32 s7, v253, 35
	s_mov_b32 m0, s83
	s_nop 0
	global_load_lds_dwordx4 v198, s[6:7]
	s_add_i32 s80, s28, 0x16000
	s_mov_b32 m0, s80
	s_nop 0
	global_load_lds_dwordx4 v200, s[6:7]
	v_readlane_b32 s6, v253, 40
	v_readlane_b32 s7, v253, 41
	s_mov_b32 m0, s28
	s_nop 0
	global_load_lds_dwordx4 v183, s[6:7]
	v_lshl_add_u32 v199, v4, 12, v2
	s_add_i32 s81, s28, 0x2000
	s_mov_b32 m0, s81
	s_nop 0
	global_load_lds_dwordx4 v199, s[6:7]
	v_readlane_b32 s6, v253, 36
	s_ashr_i32 s12, s0, 8
	s_add_i32 s89, s28, 0x4000
	v_readlane_b32 s7, v253, 37
	s_mov_b32 m0, s89
	s_nop 0
	global_load_lds_dwordx4 v183, s[6:7]
	s_add_i32 s51, s28, 0x6000
	s_mov_b32 m0, s51
	s_nop 0
	global_load_lds_dwordx4 v199, s[6:7]
	s_cmp_eq_u32 s12, 1
	s_cselect_b64 s[4:5], -1, 0
	v_writelane_b32 v250, s4, 17
	s_cmp_lg_u32 s12, 1
	s_nop 0
	v_writelane_b32 v250, s5, 18
	s_cbranch_scc1 .LBB0_940
	s_barrier
; #define LAS __attribute__((address_space(3)))
; #define PG8_WAIT_V(n) asm volatile("s_waitcnt vmcnt(" #n ")" ::: "memory")
; template <class Epi, class Sched, bool ALIGN_EPI, bool SP2>
; __device__ __forceinline__ void gemm_phase(LAS unsigned char* lds, const int K, const Sched& S, const Epi& E) {
;     ...
;         PG8_STAGE(PG8_SB(0, 0), cB, voffB); PG8_STAGE(PG8_SB(0, 1), cB + hstep, voffB); PG8_STAGE(PG8_SA(0, 0), cA, voffA); PG8_STAGE(PG8_SA(0, 1), cA + hstep, voffA);
;         if (wr == 1) PG8_BAR;
;         PG8_WAIT_V(2); PG8_BAR;
;         PG8_STAGE(PG8_SB(1, 0), cB + kstep, voffB); PG8_STAGE(PG8_SA(1, 0), cA + kstep, voffA); PG8_STAGE(PG8_SB(1, 1), cB + hstep + kstep, voffB);
;         PG8_WAIT_V(6); PG8_BAR;
;     __device__ __forceinline__ void operator()(const f32x4 (&acc)[2][2][4][2], const Unit& u, int wr, int wc, int fr, int fq) const {
;         const int colw = 32 * wc + 8 * fq;
; #pragma unroll
;         for (int ai = 0; ai < 2; ++ai) { const int blk = 2 * ai + wr;
;             if (fr == 0) {
; #pragma unroll
;                 for (int bj = 0; bj < 2; ++bj)
; #pragma unroll
;                     for (int n = 0; n < 2; ++n) *(LAS f32x4*)(xl + (blk * 2 + 0) * 256 + 128 * bj + colw + 4 * n) = acc[ai][bj][0][n]; }
;             if (fr == 15) {
; #pragma unroll
;                 for (int bj = 0; bj < 2; ++bj)
; #pragma unroll
;                     for (int n = 0; n < 2; ++n) *(LAS f32x4*)(xl + (blk * 2 + 1) * 256 + 128 * bj + colw + 4 * n) = acc[ai][bj][3][n]; } }
;         if (wr == 0 && fr < 2) { float* hp = HALO + ((size_t)(u.pm * 4 + fr)) * FF2 + 256 * u.pn + colw;
; #pragma unroll
;             for (int bj = 0; bj < 2; ++bj)
; #pragma unroll
;                 for (int n = 0; n < 2; ++n) *(f32x4*)(hp + 128 * bj + 4 * n) = acc[0][bj][0][n]; }
;         if (wr == 1 && fr >= 14) { float* hp = HALO + ((size_t)(u.pm * 4 + 2 + (fr - 14))) * FF2 + 256 * u.pn + colw;
; #pragma unroll
;             for (int bj = 0; bj < 2; ++bj)
; #pragma unroll
;                 for (int n = 0; n < 2; ++n) *(f32x4*)(hp + 128 * bj + 4 * n) = acc[1][bj][3][n]; }
;         asm volatile("s_waitcnt lgkmcnt(0)" ::: "memory"); __builtin_amdgcn_s_barrier(); asm volatile("" ::: "memory");
;         const f32x4 z4 = (f32x4){0.f, 0.f, 0.f, 0.f};
; #pragma unroll
;         for (int n = 0; n < 2; ++n) {
;             const int ch = 128 * u.pn + colw + 4 * n;
.LBB0_940:
	v_lshrrev_b32_e32 v2, 1, v0
	v_and_b32_e32 v2, 24, v2
	v_and_b32_e32 v201, 15, v0
	v_lshlrev_b32_e32 v3, 1, v2
	v_lshlrev_b32_e32 v0, 2, v0
	s_lshl_b32 s1, s1, 5
	v_lshl_or_b32 v3, v201, 6, v3
	s_lshl_b32 s4, s12, 13
	v_and_b32_e32 v0, 32, v0
	s_and_b32 s1, s1, 0x60
	v_bitop3_b32 v4, v3, s4, v0 bitop3:0xde
	s_lshl_b32 s4, s1, 7
	v_readlane_b32 s8, v253, 38
	v_bitop3_b32 v0, v3, s4, v0 bitop3:0xde
	s_waitcnt vmcnt(2)
	s_barrier
	s_add_i32 s4, s28, 0x18000
	v_readlane_b32 s9, v253, 39
	s_mov_b32 m0, s4
	s_nop 0
	global_load_lds_dwordx4 v198, s[8:9]
	s_add_i32 s5, s28, 0x1a000
	s_mov_b32 m0, s5
	s_nop 0
	global_load_lds_dwordx4 v200, s[8:9]
	v_readlane_b32 s10, v253, 42
	s_add_i32 s6, s28, 0x8000
	v_readlane_b32 s11, v253, 43
	s_mov_b32 m0, s6
	s_nop 0
	global_load_lds_dwordx4 v183, s[10:11]
	s_add_i32 s7, s28, 0xa000
	s_mov_b32 m0, s7
	s_nop 0
	global_load_lds_dwordx4 v199, s[10:11]
	v_readlane_b32 s16, v253, 46
	s_add_i32 s8, s28, 0x1c000
	v_readlane_b32 s17, v253, 47
	s_mov_b32 m0, s8
	s_nop 0
	global_load_lds_dwordx4 v198, s[16:17]
	s_add_i32 s9, s28, 0x1e000
	s_mov_b32 m0, s9
	s_nop 0
	global_load_lds_dwordx4 v200, s[16:17]
	s_add_i32 s10, s28, 0xc000
	s_cmpk_lt_u32 s0, 0x100
	s_cselect_b64 s[56:57], -1, 0
	v_or_b32_e32 v182, s1, v2
	v_cmp_gt_u32_e32 vcc, 2, v201
	v_readlane_b32 s0, v250, 17
	s_and_b64 s[58:59], s[56:57], vcc
	v_cmp_lt_u32_e32 vcc, 13, v201
	v_readlane_b32 s1, v250, 18
	s_lshl_b32 s13, s12, 11
	s_and_b64 s[40:41], s[0:1], vcc
	s_cmp_gt_i32 s12, 0
	s_cselect_b64 s[38:39], -1, 0
	s_cmp_lt_i32 s12, 3
	s_cselect_b64 s[68:69], -1, 0
	s_cmp_gt_i32 s12, -2
	s_cselect_b64 s[16:17], -1, 0
	s_cmp_lt_i32 s12, 1
	s_cselect_b64 s[52:53], -1, 0
	s_add_i32 s18, s13, 0
	s_add_i32 s73, s28, 0xe000
	s_add_i32 s30, s18, 0x20000
	s_add_i32 s31, s18, 0x20400
	s_add_u32 s54, s14, 0xb000
	s_addc_u32 s55, s15, 0
	s_add_u32 s62, s14, 0x16000
	s_addc_u32 s63, s15, 0
	s_add_u32 s64, s14, 0x5800
	s_addc_u32 s65, s15, 0
	s_add_u32 s66, s14, 0x10800
	s_addc_u32 s67, s15, 0
	v_lshl_or_b32 v213, s12, 6, v201
	s_add_u32 s12, s14, 0x1b800
	s_addc_u32 s13, s15, 0
	s_add_u32 s86, s22, 0x5800
	v_lshlrev_b32_e32 v2, 2, v182
	s_addc_u32 s87, s23, 0
	s_add_i32 s19, s18, 0x1fc00
	s_add_i32 s18, s18, 0x1fe00
	s_waitcnt vmcnt(6)
	v_add_u32_e32 v219, s19, v2
	v_add_u32_e32 v220, s18, v2
	v_readlane_b32 s18, v252, 59
	v_readlane_b32 s24, v253, 44
	v_readlane_b32 s42, v253, 40
	v_add_u32_e32 v218, s30, v2
	v_readlane_b32 s19, v252, 60
	v_readlane_b32 s25, v253, 45
	v_readlane_b32 s43, v253, 41
	v_add_u32_e32 v214, -12, v201
	s_mov_b32 s11, 0
	v_cmp_eq_u32_e64 s[0:1], 0, v201
	v_cmp_eq_u32_e64 s[36:37], 15, v201
	v_or_b32_e32 v215, 16, v213
	v_or_b32_e32 v216, 32, v213
	v_or_b32_e32 v217, 48, v213
	v_add_u32_e32 v221, 0xfffffc10, v218
	v_add_u32_e32 v222, 0xfffffe10, v218
	v_add_u32_e32 v223, 0, v0
	v_add_u32_e32 v224, 0, v4
	v_readlane_b32 s20, v252, 58
	s_mov_b32 s21, s18
	s_mov_b64 s[18:19], s[24:25]
	s_mov_b64 s[76:77], s[42:43]
	s_barrier
	s_branch .LBB0_943

; #define PG8_STAGE(bufoff, gbase, voff) do { _Pragma("unroll") for (int _i = 0; _i < 2; ++_i) \
;         glds_s((voff)[_i], (const void*)(gbase), ldsbase + (unsigned)((bufoff) + _i * 8192)); } while (0)
; #define PG8_LDA(dst, b, h) do { _Pragma("unroll") for (int m = 0; m < 4; ++m) _Pragma("unroll") for (int k = 0; k < 2; ++k) dst[m][k] = *(const LAS bf16x8*)(lds + PG8_SA(b, h) + aoff + m * 2048 + k * 1024); } while (0)
; #define PG8_LDB(dst, b, h) do { _Pragma("unroll") for (int n = 0; n < 2; ++n) _Pragma("unroll") for (int k = 0; k < 2; ++k) dst[n][k] = *(const LAS bf16x8*)(lds + PG8_SB(b, h) + boff + n * 2048 + k * 1024); } while (0)
; #define PG8_MMA(ai, bj, At, Bt) do { __builtin_amdgcn_s_setprio(1); _Pragma("unroll") for (int m = 0; m < 4; ++m) _Pragma("unroll") for (int n = 0; n < 2; ++n) _Pragma("unroll") for (int k = 0; k < 2; ++k) \
;         acc[ai][bj][m][n] = __builtin_amdgcn_mfma_f32_16x16x32_bf16(Bt[n][k], At[m][k], acc[ai][bj][m][n], 0, 0, 0); __builtin_amdgcn_s_setprio(0); } while (0)
; #define PG8_WAIT_V(n) asm volatile("s_waitcnt vmcnt(" #n ")" ::: "memory")
; #define PG8_WAIT_L(n) asm volatile("s_waitcnt lgkmcnt(" #n ")" ::: "memory")
; #define PG8_BAR __builtin_amdgcn_s_barrier()
; #define PG8_SCHED __builtin_amdgcn_sched_barrier(0)
; template <class Epi, class Sched, bool ALIGN_EPI, bool SP2>
; __device__ __forceinline__ void gemm_phase(LAS unsigned char* lds, const int K, const Sched& S, const Epi& E) {
;     ...
;             PG8_LDB(B0, 0, 0); PG8_LDB(B1, 0, 1); PG8_SCHED; PG8_LDA(At, 0, 0); PG8_STAGE(PG8_SA(1, 1), a1 + hstep, voffA);
;             PG8_WAIT_V(8); PG8_WAIT_L(0); PG8_BAR; PG8_MMA(0, 0, At, B0); PG8_MMA(0, 1, At, B1); PG8_BAR; PG8_SCHED;
;             PG8_LDA(At, 0, 1); PG8_STAGE(PG8_SB(0, 0), b2, voffB); PG8_STAGE(PG8_SB(0, 1), b2 + hstep, voffB); PG8_STAGE(PG8_SA(0, 0), a2, voffA);
;             PG8_WAIT_V(8); PG8_WAIT_L(0); PG8_BAR; PG8_MMA(1, 0, At, B0); PG8_MMA(1, 1, At, B1); PG8_BAR; PG8_SCHED;
.LBB0_946:
	v_add_u32_e32 v0, 0x10000, v223
	ds_read_b128 v[106:109], v0
	ds_read_b128 v[110:113], v0 offset:1024
	ds_read_b128 v[114:117], v0 offset:2048
	ds_read_b128 v[118:121], v0 offset:3072
	v_add_u32_e32 v0, 0x14000, v223
	ds_read_b128 v[146:149], v0
	ds_read_b128 v[150:153], v0 offset:1024
	ds_read_b128 v[154:157], v0 offset:2048
	ds_read_b128 v[158:161], v0 offset:3072
	s_add_u32 s44, s42, 0x100
	s_addc_u32 s45, s43, 0
	s_cmp_eq_u32 vcc_lo, 28
	s_cselect_b32 s24, s76, s44
	s_cselect_b32 s25, s77, s45
	s_cselect_b32 s48, s18, s35
	s_cselect_b32 s49, s19, s97
	s_add_u32 s46, s24, 0x80
	s_addc_u32 s47, s25, 0
	ds_read_b128 v[162:165], v224
	ds_read_b128 v[166:169], v224 offset:1024
	ds_read_b128 v[170:173], v224 offset:2048
	ds_read_b128 v[174:177], v224 offset:3072
	ds_read_b128 v[184:187], v224 offset:4096
	ds_read_b128 v[188:191], v224 offset:5120
	ds_read_b128 v[192:195], v224 offset:6144
	ds_read_b128 v[226:229], v224 offset:7168
	s_add_u32 s42, s42, 0x80080
	s_addc_u32 s43, s43, 0
	s_mov_b32 vcc_hi, m0
	s_mov_b32 m0, s10
	s_nop 0
	global_load_lds_dwordx4 v183, s[42:43]
	s_mov_b32 m0, vcc_hi
	s_nop 0
	s_mov_b32 vcc_hi, m0
	s_mov_b32 m0, s73
	s_nop 0
	global_load_lds_dwordx4 v199, s[42:43]
	s_mov_b32 m0, vcc_hi
	s_waitcnt vmcnt(8)
	s_waitcnt lgkmcnt(0)
	s_barrier
	s_setprio 1
	s_waitcnt lgkmcnt(7)
	v_mfma_f32_16x16x32_bf16 v[142:145], v[106:109], v[162:165], v[142:145]
	v_mfma_f32_16x16x32_bf16 v[62:65], v[114:117], v[162:165], v[62:65]
	s_waitcnt lgkmcnt(5)
	v_mfma_f32_16x16x32_bf16 v[134:137], v[106:109], v[170:173], v[134:137]
	v_mfma_f32_16x16x32_bf16 v[54:57], v[114:117], v[170:173], v[54:57]
	s_waitcnt lgkmcnt(3)
	v_mfma_f32_16x16x32_bf16 v[126:129], v[106:109], v[184:187], v[126:129]
	v_mfma_f32_16x16x32_bf16 v[46:49], v[114:117], v[184:187], v[46:49]
	s_waitcnt lgkmcnt(1)
	v_mfma_f32_16x16x32_bf16 v[102:105], v[106:109], v[192:195], v[102:105]
	v_mfma_f32_16x16x32_bf16 v[38:41], v[114:117], v[192:195], v[38:41]
	v_mfma_f32_16x16x32_bf16 v[142:145], v[110:113], v[166:169], v[142:145]
	v_mfma_f32_16x16x32_bf16 v[62:65], v[118:121], v[166:169], v[62:65]
	v_mfma_f32_16x16x32_bf16 v[134:137], v[110:113], v[174:177], v[134:137]
	v_mfma_f32_16x16x32_bf16 v[54:57], v[118:121], v[174:177], v[54:57]
	v_mfma_f32_16x16x32_bf16 v[126:129], v[110:113], v[188:191], v[126:129]
	v_mfma_f32_16x16x32_bf16 v[46:49], v[118:121], v[188:191], v[46:49]
	s_waitcnt lgkmcnt(0)
	v_mfma_f32_16x16x32_bf16 v[102:105], v[110:113], v[226:229], v[102:105]
	v_mfma_f32_16x16x32_bf16 v[38:41], v[118:121], v[226:229], v[38:41]
	s_setprio 0
	s_setprio 1
	v_mfma_f32_16x16x32_bf16 v[138:141], v[146:149], v[162:165], v[138:141]
	v_mfma_f32_16x16x32_bf16 v[58:61], v[154:157], v[162:165], v[58:61]
	v_mfma_f32_16x16x32_bf16 v[130:133], v[146:149], v[170:173], v[130:133]
	v_mfma_f32_16x16x32_bf16 v[50:53], v[154:157], v[170:173], v[50:53]
	v_mfma_f32_16x16x32_bf16 v[122:125], v[146:149], v[184:187], v[122:125]
	v_mfma_f32_16x16x32_bf16 v[42:45], v[154:157], v[184:187], v[42:45]
	v_mfma_f32_16x16x32_bf16 v[98:101], v[146:149], v[192:195], v[98:101]
	v_mfma_f32_16x16x32_bf16 v[34:37], v[154:157], v[192:195], v[34:37]
	v_mfma_f32_16x16x32_bf16 v[138:141], v[150:153], v[166:169], v[138:141]
	v_mfma_f32_16x16x32_bf16 v[58:61], v[158:161], v[166:169], v[58:61]
	v_mfma_f32_16x16x32_bf16 v[130:133], v[150:153], v[174:177], v[130:133]
	v_mfma_f32_16x16x32_bf16 v[50:53], v[158:161], v[174:177], v[50:53]
	v_mfma_f32_16x16x32_bf16 v[122:125], v[150:153], v[188:191], v[122:125]
	v_mfma_f32_16x16x32_bf16 v[42:45], v[158:161], v[188:191], v[42:45]
	v_mfma_f32_16x16x32_bf16 v[98:101], v[150:153], v[226:229], v[98:101]
	v_mfma_f32_16x16x32_bf16 v[34:37], v[158:161], v[226:229], v[34:37]
	s_setprio 0
	s_barrier
	ds_read_b128 v[162:165], v224 offset:16384
	ds_read_b128 v[166:169], v224 offset:17408
	ds_read_b128 v[170:173], v224 offset:18432
	ds_read_b128 v[174:177], v224 offset:19456
	ds_read_b128 v[184:187], v224 offset:20480
	ds_read_b128 v[188:191], v224 offset:21504
	ds_read_b128 v[192:195], v224 offset:22528
	ds_read_b128 v[226:229], v224 offset:23552
	s_mov_b32 m0, s60
	s_nop 0
	global_load_lds_dwordx4 v198, s[48:49]
	s_mov_b32 m0, s82
	s_nop 0
	global_load_lds_dwordx4 v200, s[48:49]
	s_add_u32 s42, s48, 0x80000
	s_addc_u32 s43, s49, 0
	s_mov_b32 vcc_hi, m0
	s_mov_b32 m0, s83
	s_nop 0
	global_load_lds_dwordx4 v198, s[42:43]
	s_mov_b32 m0, vcc_hi
	s_nop 0
	s_mov_b32 vcc_hi, m0
	s_mov_b32 m0, s80
	s_nop 0
	global_load_lds_dwordx4 v200, s[42:43]
	s_mov_b32 m0, vcc_hi
	s_mov_b32 m0, s28
	s_nop 0
	global_load_lds_dwordx4 v183, s[24:25]
	s_mov_b32 m0, s81
	s_nop 0
	global_load_lds_dwordx4 v199, s[24:25]
	s_waitcnt vmcnt(8)
	s_waitcnt lgkmcnt(0)
	s_barrier
; #define PG8_STAGE(bufoff, gbase, voff) do { _Pragma("unroll") for (int _i = 0; _i < 2; ++_i) \
;         glds_s((voff)[_i], (const void*)(gbase), ldsbase + (unsigned)((bufoff) + _i * 8192)); } while (0)
; #define PG8_LDA(dst, b, h) do { _Pragma("unroll") for (int m = 0; m < 4; ++m) _Pragma("unroll") for (int k = 0; k < 2; ++k) dst[m][k] = *(const LAS bf16x8*)(lds + PG8_SA(b, h) + aoff + m * 2048 + k * 1024); } while (0)
; #define PG8_LDB(dst, b, h) do { _Pragma("unroll") for (int n = 0; n < 2; ++n) _Pragma("unroll") for (int k = 0; k < 2; ++k) dst[n][k] = *(const LAS bf16x8*)(lds + PG8_SB(b, h) + boff + n * 2048 + k * 1024); } while (0)
; #define PG8_MMA(ai, bj, At, Bt) do { __builtin_amdgcn_s_setprio(1); _Pragma("unroll") for (int m = 0; m < 4; ++m) _Pragma("unroll") for (int n = 0; n < 2; ++n) _Pragma("unroll") for (int k = 0; k < 2; ++k) \
;         acc[ai][bj][m][n] = __builtin_amdgcn_mfma_f32_16x16x32_bf16(Bt[n][k], At[m][k], acc[ai][bj][m][n], 0, 0, 0); __builtin_amdgcn_s_setprio(0); } while (0)
; #define PG8_WAIT_V(n) asm volatile("s_waitcnt vmcnt(" #n ")" ::: "memory")
; #define PG8_WAIT_L(n) asm volatile("s_waitcnt lgkmcnt(" #n ")" ::: "memory")
; #define PG8_BAR __builtin_amdgcn_s_barrier()
; #define PG8_SCHED __builtin_amdgcn_sched_barrier(0)
; template <class Epi, class Sched, bool ALIGN_EPI, bool SP2>
; __device__ __forceinline__ void gemm_phase(LAS unsigned char* lds, const int K, const Sched& S, const Epi& E) {
;     ...
;             PG8_WAIT_V(8); PG8_WAIT_L(0); PG8_BAR; PG8_MMA(1, 0, At, B0); PG8_MMA(1, 1, At, B1); PG8_BAR; PG8_SCHED;
;             PG8_LDB(B0, 1, 0); PG8_LDB(B1, 1, 1); PG8_SCHED; PG8_LDA(At, 1, 0); PG8_STAGE(PG8_SA(0, 1), a2 + hstep, voffA);
;             PG8_WAIT_V(8); PG8_WAIT_L(0); PG8_BAR; PG8_MMA(0, 0, At, B0); PG8_MMA(0, 1, At, B1); PG8_BAR; PG8_SCHED;
	s_setprio 1
	s_waitcnt lgkmcnt(7)
	v_mfma_f32_16x16x32_bf16 v[94:97], v[106:109], v[162:165], v[94:97]
	v_mfma_f32_16x16x32_bf16 v[30:33], v[114:117], v[162:165], v[30:33]
	s_waitcnt lgkmcnt(5)
	v_mfma_f32_16x16x32_bf16 v[86:89], v[106:109], v[170:173], v[86:89]
	v_mfma_f32_16x16x32_bf16 v[22:25], v[114:117], v[170:173], v[22:25]
	s_waitcnt lgkmcnt(3)
	v_mfma_f32_16x16x32_bf16 v[78:81], v[106:109], v[184:187], v[78:81]
	v_mfma_f32_16x16x32_bf16 v[14:17], v[114:117], v[184:187], v[14:17]
	s_waitcnt lgkmcnt(1)
	v_mfma_f32_16x16x32_bf16 v[70:73], v[106:109], v[192:195], v[70:73]
	v_mfma_f32_16x16x32_bf16 v[6:9], v[114:117], v[192:195], v[6:9]
	v_mfma_f32_16x16x32_bf16 v[94:97], v[110:113], v[166:169], v[94:97]
	v_mfma_f32_16x16x32_bf16 v[30:33], v[118:121], v[166:169], v[30:33]
	v_mfma_f32_16x16x32_bf16 v[86:89], v[110:113], v[174:177], v[86:89]
	v_mfma_f32_16x16x32_bf16 v[22:25], v[118:121], v[174:177], v[22:25]
	v_mfma_f32_16x16x32_bf16 v[78:81], v[110:113], v[188:191], v[78:81]
	v_mfma_f32_16x16x32_bf16 v[14:17], v[118:121], v[188:191], v[14:17]
	s_waitcnt lgkmcnt(0)
	v_mfma_f32_16x16x32_bf16 v[70:73], v[110:113], v[226:229], v[70:73]
	v_mfma_f32_16x16x32_bf16 v[6:9], v[118:121], v[226:229], v[6:9]
	s_setprio 0
	s_setprio 1
	v_mfma_f32_16x16x32_bf16 v[90:93], v[146:149], v[162:165], v[90:93]
	v_mfma_f32_16x16x32_bf16 v[26:29], v[154:157], v[162:165], v[26:29]
	v_mfma_f32_16x16x32_bf16 v[82:85], v[146:149], v[170:173], v[82:85]
	v_mfma_f32_16x16x32_bf16 v[18:21], v[154:157], v[170:173], v[18:21]
	v_mfma_f32_16x16x32_bf16 v[74:77], v[146:149], v[184:187], v[74:77]
	v_mfma_f32_16x16x32_bf16 v[10:13], v[154:157], v[184:187], v[10:13]
	v_mfma_f32_16x16x32_bf16 v[66:69], v[146:149], v[192:195], v[66:69]
	v_mfma_f32_16x16x32_bf16 v[2:5], v[154:157], v[192:195], v[2:5]
	v_mfma_f32_16x16x32_bf16 v[90:93], v[150:153], v[166:169], v[90:93]
	v_mfma_f32_16x16x32_bf16 v[26:29], v[158:161], v[166:169], v[26:29]
	v_mfma_f32_16x16x32_bf16 v[82:85], v[150:153], v[174:177], v[82:85]
	v_mfma_f32_16x16x32_bf16 v[18:21], v[158:161], v[174:177], v[18:21]
	v_mfma_f32_16x16x32_bf16 v[74:77], v[150:153], v[188:191], v[74:77]
	v_mfma_f32_16x16x32_bf16 v[10:13], v[158:161], v[188:191], v[10:13]
	v_mfma_f32_16x16x32_bf16 v[66:69], v[150:153], v[226:229], v[66:69]
	v_mfma_f32_16x16x32_bf16 v[2:5], v[158:161], v[226:229], v[2:5]
	s_setprio 0
	s_barrier
	v_add_u32_e32 v0, 0x18000, v223
	ds_read_b128 v[106:109], v0
	ds_read_b128 v[110:113], v0 offset:1024
	ds_read_b128 v[114:117], v0 offset:2048
	ds_read_b128 v[118:121], v0 offset:3072
	v_add_u32_e32 v0, 0x1c000, v223
	ds_read_b128 v[146:149], v0
	ds_read_b128 v[150:153], v0 offset:1024
	ds_read_b128 v[154:157], v0 offset:2048
	ds_read_b128 v[158:161], v0 offset:3072
	ds_read_b128 v[162:165], v224 offset:32768
	ds_read_b128 v[166:169], v224 offset:33792
	ds_read_b128 v[170:173], v224 offset:34816
	ds_read_b128 v[174:177], v224 offset:35840
	ds_read_b128 v[184:187], v224 offset:36864
	ds_read_b128 v[188:191], v224 offset:37888
	ds_read_b128 v[192:195], v224 offset:38912
	ds_read_b128 v[226:229], v224 offset:39936
	s_add_u32 s24, s24, 0x80000
	s_addc_u32 s25, s25, 0
	s_mov_b32 m0, s89
	s_nop 0
	global_load_lds_dwordx4 v183, s[24:25]
	s_mov_b32 m0, s51
	s_nop 0
	global_load_lds_dwordx4 v199, s[24:25]
	s_waitcnt vmcnt(8)
	s_waitcnt lgkmcnt(0)
	s_barrier
	s_setprio 1
	s_waitcnt lgkmcnt(7)
	v_mfma_f32_16x16x32_bf16 v[142:145], v[106:109], v[162:165], v[142:145]
	v_mfma_f32_16x16x32_bf16 v[62:65], v[114:117], v[162:165], v[62:65]
	s_waitcnt lgkmcnt(5)
	v_mfma_f32_16x16x32_bf16 v[134:137], v[106:109], v[170:173], v[134:137]
	v_mfma_f32_16x16x32_bf16 v[54:57], v[114:117], v[170:173], v[54:57]
	s_waitcnt lgkmcnt(3)
	v_mfma_f32_16x16x32_bf16 v[126:129], v[106:109], v[184:187], v[126:129]
	v_mfma_f32_16x16x32_bf16 v[46:49], v[114:117], v[184:187], v[46:49]
	s_waitcnt lgkmcnt(1)
	v_mfma_f32_16x16x32_bf16 v[102:105], v[106:109], v[192:195], v[102:105]
	v_mfma_f32_16x16x32_bf16 v[38:41], v[114:117], v[192:195], v[38:41]
	v_mfma_f32_16x16x32_bf16 v[142:145], v[110:113], v[166:169], v[142:145]
	v_mfma_f32_16x16x32_bf16 v[62:65], v[118:121], v[166:169], v[62:65]
	v_mfma_f32_16x16x32_bf16 v[134:137], v[110:113], v[174:177], v[134:137]
	v_mfma_f32_16x16x32_bf16 v[54:57], v[118:121], v[174:177], v[54:57]
	v_mfma_f32_16x16x32_bf16 v[126:129], v[110:113], v[188:191], v[126:129]
	v_mfma_f32_16x16x32_bf16 v[46:49], v[118:121], v[188:191], v[46:49]
	s_waitcnt lgkmcnt(0)
	v_mfma_f32_16x16x32_bf16 v[102:105], v[110:113], v[226:229], v[102:105]
	v_mfma_f32_16x16x32_bf16 v[38:41], v[118:121], v[226:229], v[38:41]
	s_setprio 0
	s_setprio 1
	v_mfma_f32_16x16x32_bf16 v[138:141], v[146:149], v[162:165], v[138:141]
	v_mfma_f32_16x16x32_bf16 v[58:61], v[154:157], v[162:165], v[58:61]
	v_mfma_f32_16x16x32_bf16 v[130:133], v[146:149], v[170:173], v[130:133]
	v_mfma_f32_16x16x32_bf16 v[50:53], v[154:157], v[170:173], v[50:53]
	v_mfma_f32_16x16x32_bf16 v[122:125], v[146:149], v[184:187], v[122:125]
	v_mfma_f32_16x16x32_bf16 v[42:45], v[154:157], v[184:187], v[42:45]
	v_mfma_f32_16x16x32_bf16 v[98:101], v[146:149], v[192:195], v[98:101]
	v_mfma_f32_16x16x32_bf16 v[34:37], v[154:157], v[192:195], v[34:37]
	v_mfma_f32_16x16x32_bf16 v[138:141], v[150:153], v[166:169], v[138:141]
	v_mfma_f32_16x16x32_bf16 v[58:61], v[158:161], v[166:169], v[58:61]
	v_mfma_f32_16x16x32_bf16 v[130:133], v[150:153], v[174:177], v[130:133]
	v_mfma_f32_16x16x32_bf16 v[50:53], v[158:161], v[174:177], v[50:53]
	v_mfma_f32_16x16x32_bf16 v[122:125], v[150:153], v[188:191], v[122:125]
	v_mfma_f32_16x16x32_bf16 v[42:45], v[158:161], v[188:191], v[42:45]
	v_mfma_f32_16x16x32_bf16 v[98:101], v[150:153], v[226:229], v[98:101]
	v_mfma_f32_16x16x32_bf16 v[34:37], v[158:161], v[226:229], v[34:37]
	s_setprio 0
	s_barrier
; #define PG8_STAGE(bufoff, gbase, voff) do { _Pragma("unroll") for (int _i = 0; _i < 2; ++_i) \
;         glds_s((voff)[_i], (const void*)(gbase), ldsbase + (unsigned)((bufoff) + _i * 8192)); } while (0)
; #define PG8_LDA(dst, b, h) do { _Pragma("unroll") for (int m = 0; m < 4; ++m) _Pragma("unroll") for (int k = 0; k < 2; ++k) dst[m][k] = *(const LAS bf16x8*)(lds + PG8_SA(b, h) + aoff + m * 2048 + k * 1024); } while (0)
; #define PG8_MMA(ai, bj, At, Bt) do { __builtin_amdgcn_s_setprio(1); _Pragma("unroll") for (int m = 0; m < 4; ++m) _Pragma("unroll") for (int n = 0; n < 2; ++n) _Pragma("unroll") for (int k = 0; k < 2; ++k) \
;         acc[ai][bj][m][n] = __builtin_amdgcn_mfma_f32_16x16x32_bf16(Bt[n][k], At[m][k], acc[ai][bj][m][n], 0, 0, 0); __builtin_amdgcn_s_setprio(0); } while (0)
; #define PG8_WAIT_V(n) asm volatile("s_waitcnt vmcnt(" #n ")" ::: "memory")
; #define PG8_WAIT_L(n) asm volatile("s_waitcnt lgkmcnt(" #n ")" ::: "memory")
; #define PG8_BAR __builtin_amdgcn_s_barrier()
; #define PG8_SCHED __builtin_amdgcn_sched_barrier(0)
; template <class Epi, class Sched, bool ALIGN_EPI, bool SP2>
; __device__ __forceinline__ void gemm_phase(LAS unsigned char* lds, const int K, const Sched& S, const Epi& E) {
;     ...
;             PG8_LDA(At, 1, 1); PG8_STAGE(PG8_SB(1, 0), b3, voffB); PG8_STAGE(PG8_SB(1, 1), b3 + hstep, voffB); PG8_STAGE(PG8_SA(1, 0), a3, voffA);
;             PG8_WAIT_V(8); PG8_WAIT_L(0); PG8_BAR; PG8_MMA(1, 0, At, B0); PG8_MMA(1, 1, At, B1); PG8_BAR; PG8_SCHED;
	ds_read_b128 v[162:165], v224 offset:49152
	ds_read_b128 v[166:169], v224 offset:50176
	ds_read_b128 v[170:173], v224 offset:51200
	ds_read_b128 v[174:177], v224 offset:52224
	ds_read_b128 v[184:187], v224 offset:53248
	ds_read_b128 v[188:191], v224 offset:54272
	ds_read_b128 v[192:195], v224 offset:55296
	ds_read_b128 v[226:229], v224 offset:56320
	s_add_u32 s24, s48, 0x80
	s_addc_u32 s25, s49, 0
	s_mov_b32 m0, s4
	s_nop 0
	global_load_lds_dwordx4 v198, s[24:25]
	s_mov_b32 m0, s5
	s_nop 0
	global_load_lds_dwordx4 v200, s[24:25]
	s_add_u32 s24, s48, 0x80080
	s_addc_u32 s25, s49, 0
	s_mov_b32 m0, s8
	s_nop 0
	global_load_lds_dwordx4 v198, s[24:25]
	s_mov_b32 m0, s9
	s_nop 0
	global_load_lds_dwordx4 v200, s[24:25]
	s_mov_b32 m0, s6
	s_nop 0
	global_load_lds_dwordx4 v183, s[46:47]
	s_mov_b32 m0, s7
	s_nop 0
	global_load_lds_dwordx4 v199, s[46:47]
	s_waitcnt vmcnt(8)
	s_waitcnt lgkmcnt(0)
	s_barrier
	s_setprio 1
	s_waitcnt lgkmcnt(7)
	v_mfma_f32_16x16x32_bf16 v[94:97], v[106:109], v[162:165], v[94:97]
	v_mfma_f32_16x16x32_bf16 v[30:33], v[114:117], v[162:165], v[30:33]
	s_waitcnt lgkmcnt(5)
	v_mfma_f32_16x16x32_bf16 v[86:89], v[106:109], v[170:173], v[86:89]
	v_mfma_f32_16x16x32_bf16 v[22:25], v[114:117], v[170:173], v[22:25]
	s_waitcnt lgkmcnt(3)
	v_mfma_f32_16x16x32_bf16 v[78:81], v[106:109], v[184:187], v[78:81]
	v_mfma_f32_16x16x32_bf16 v[14:17], v[114:117], v[184:187], v[14:17]
	s_waitcnt lgkmcnt(1)
	v_mfma_f32_16x16x32_bf16 v[70:73], v[106:109], v[192:195], v[70:73]
	v_mfma_f32_16x16x32_bf16 v[6:9], v[114:117], v[192:195], v[6:9]
	v_mfma_f32_16x16x32_bf16 v[94:97], v[110:113], v[166:169], v[94:97]
	v_mfma_f32_16x16x32_bf16 v[30:33], v[118:121], v[166:169], v[30:33]
	v_mfma_f32_16x16x32_bf16 v[86:89], v[110:113], v[174:177], v[86:89]
	v_mfma_f32_16x16x32_bf16 v[22:25], v[118:121], v[174:177], v[22:25]
	v_mfma_f32_16x16x32_bf16 v[78:81], v[110:113], v[188:191], v[78:81]
	v_mfma_f32_16x16x32_bf16 v[14:17], v[118:121], v[188:191], v[14:17]
	s_waitcnt lgkmcnt(0)
	v_mfma_f32_16x16x32_bf16 v[70:73], v[110:113], v[226:229], v[70:73]
	v_mfma_f32_16x16x32_bf16 v[6:9], v[118:121], v[226:229], v[6:9]
	s_setprio 0
	s_setprio 1
	v_mfma_f32_16x16x32_bf16 v[90:93], v[146:149], v[162:165], v[90:93]
	v_mfma_f32_16x16x32_bf16 v[26:29], v[154:157], v[162:165], v[26:29]
	v_mfma_f32_16x16x32_bf16 v[82:85], v[146:149], v[170:173], v[82:85]
	v_mfma_f32_16x16x32_bf16 v[18:21], v[154:157], v[170:173], v[18:21]
	v_mfma_f32_16x16x32_bf16 v[74:77], v[146:149], v[184:187], v[74:77]
	v_mfma_f32_16x16x32_bf16 v[10:13], v[154:157], v[184:187], v[10:13]
	v_mfma_f32_16x16x32_bf16 v[66:69], v[146:149], v[192:195], v[66:69]
	v_mfma_f32_16x16x32_bf16 v[2:5], v[154:157], v[192:195], v[2:5]
	v_mfma_f32_16x16x32_bf16 v[90:93], v[150:153], v[166:169], v[90:93]
	v_mfma_f32_16x16x32_bf16 v[26:29], v[158:161], v[166:169], v[26:29]
	v_mfma_f32_16x16x32_bf16 v[82:85], v[150:153], v[174:177], v[82:85]
	v_mfma_f32_16x16x32_bf16 v[18:21], v[158:161], v[174:177], v[18:21]
	v_mfma_f32_16x16x32_bf16 v[74:77], v[150:153], v[188:191], v[74:77]
	v_mfma_f32_16x16x32_bf16 v[10:13], v[158:161], v[188:191], v[10:13]
	v_mfma_f32_16x16x32_bf16 v[66:69], v[150:153], v[226:229], v[66:69]
	v_mfma_f32_16x16x32_bf16 v[2:5], v[158:161], v[226:229], v[2:5]
	s_setprio 0
	s_barrier
	s_add_i32 vcc_lo, vcc_lo, 2
	s_add_u32 s35, s35, 0x100
	s_addc_u32 s97, s97, 0
	s_cmp_gt_u32 vcc_lo, 29
	s_mov_b64 s[42:43], s[44:45]
	s_cbranch_scc0 .LBB0_946
	s_and_b64 vcc, exec, s[56:57]
	s_cbranch_vccz .LBB0_949
	s_barrier

; #define PG8_STAGE(bufoff, gbase, voff) do { _Pragma("unroll") for (int _i = 0; _i < 2; ++_i) \
;         glds_s((voff)[_i], (const void*)(gbase), ldsbase + (unsigned)((bufoff) + _i * 8192)); } while (0)
; #define PG8_WAIT_V(n) asm volatile("s_waitcnt vmcnt(" #n ")" ::: "memory")
; #define PG8_BAR __builtin_amdgcn_s_barrier()
; template <class Epi, class Sched, bool ALIGN_EPI, bool SP2>
; __device__ __forceinline__ void gemm_phase(LAS unsigned char* lds, const int K, const Sched& S, const Epi& E) {
;     ...
;     for (int i = 0; i < 2; ++i) { int R, C; stage_rc(tid * 16 + i * 8192, R, C); const int Rb = Epi::PERM ? ((R & ~31) + perm32(R & 31)) : R;
;         voffA[i] = (unsigned)(R * K + C) * 2u; voffB[i] = (unsigned)(Rb * K + C) * 2u; }
;     const size_t kstep = (size_t)(BK * 2);
;     const size_t hstep = (size_t)HALF * K * 2;
;     const unsigned ldsw = (unsigned)wid * 1024u;
;     const unsigned ldsbase = (unsigned)__builtin_amdgcn_readfirstlane((int)((unsigned)(uintptr_t)lds + ldsw));
;     const int aoff = lds_byte(wr * 64 + fr, fq * 8), boff = lds_byte(wc * 32 + fr, fq * 8);
;     ...
;     Unit cur, nxt; int ui = 0;
;     if (!S.next(0, cur)) return;
;     f32x4 acc[2][2][4][2];
; #pragma unroll
;     for (int a = 0; a < 2; ++a)
; #pragma unroll
;         for (int b = 0; b < 2; ++b)
; #pragma unroll
;             for (int m = 0; m < 4; ++m)
; #pragma unroll
;                 for (int n = 0; n < 2; ++n) acc[a][b][m][n] = (f32x4){0.f, 0.f, 0.f, 0.f};
;     bf16x8 At[4][2], B0[2][2], B1[2][2];
;     const char* cA = cur.A; const char* cB = cur.B;
;     if constexpr (SP2) {
;         PG8_STAGE(PG8_SB(0, 0), cB, voffB); PG8_STAGE(PG8_SB(0, 1), cB + hstep, voffB); PG8_STAGE(PG8_SA(0, 0), cA, voffA); PG8_STAGE(PG8_SA(0, 1), cA + hstep, voffA);
;         if (wr == 1) PG8_BAR;
;         PG8_WAIT_V(2); PG8_BAR;
;         PG8_STAGE(PG8_SB(1, 0), cB + kstep, voffB); PG8_STAGE(PG8_SA(1, 0), cA + kstep, voffA); PG8_STAGE(PG8_SB(1, 1), cB + hstep + kstep, voffB);
;         PG8_WAIT_V(6); PG8_BAR;
.LBB0_1069:
	s_waitcnt vmcnt(0)
	v_mov_b32_e32 v2, v202
	v_readlane_b32 s0, v250, 21
	s_barrier
	v_readlane_b32 s1, v250, 22
	v_readfirstlane_b32 s12, v2
	s_and_b64 vcc, exec, s[0:1]
	s_ashr_i32 s13, s12, 6
	s_mov_b64 s[34:35], 0x100
	s_cbranch_vccnz .LBB0_1089
	v_bfe_i32 v4, v2, 27, 1
	v_lshlrev_b32_e32 v3, 4, v2
	v_lshrrev_b32_e32 v4, 22, v4
	v_add_u32_e32 v4, v3, v4
	v_and_b32_e32 v4, 0xfffffc00, v4
	v_sub_u32_e32 v4, v3, v4
	v_ashrrev_i32_e32 v0, 31, v2
	v_lshrrev_b32_e32 v5, 4, v4
	v_lshrrev_b32_e32 v0, 26, v0
	v_bitop3_b32 v4, v5, v4, 32 bitop3:0x6c
	v_add_u32_e32 v0, v2, v0
	v_ashrrev_i32_e32 v6, 31, v4
	v_ashrrev_i32_e32 v0, 6, v0
	v_lshrrev_b32_e32 v6, 26, v6
	v_lshlrev_b32_e32 v5, 3, v0
	v_add_u32_e32 v6, v4, v6
	v_and_b32_e32 v5, 0x7ffff0, v5
	v_lshrrev_b32_e32 v7, 6, v6
	v_and_b32_e32 v6, 0xc0, v6
	v_add_u32_e32 v5, v7, v5
	v_sub_u32_e32 v4, v4, v6
	s_movk_i32 s0, 0x1600
	v_lshlrev_b32_e32 v0, 5, v0
	v_ashrrev_i16_sdwa v4, v205, sext(v4) dst_sel:DWORD dst_unused:UNUSED_PAD src0_sel:DWORD src1_sel:BYTE_0
	v_mul_lo_u32 v5, v5, s0
	v_bfe_i32 v4, v4, 0, 16
	v_and_or_b32 v0, v0, 32, v5
	v_add_u32_e32 v3, 0x2000, v3
	v_add_lshl_u32 v0, v0, v4, 1
	v_ashrrev_i32_e32 v4, 31, v3
	v_lshrrev_b32_e32 v4, 22, v4
	v_add_u32_e32 v4, v3, v4
	v_ashrrev_i32_e32 v4, 10, v4
	v_mul_i32_i24_e32 v5, 0x400, v4
	v_sub_u32_e32 v3, v3, v5
	v_lshrrev_b32_e32 v5, 4, v3
	v_bitop3_b32 v3, v5, v3, 32 bitop3:0x6c
	v_ashrrev_i32_e32 v6, 31, v3
	v_lshrrev_b32_e32 v6, 26, v6
	v_lshlrev_b32_e32 v5, 3, v4
	v_add_u32_e32 v6, v3, v6
	v_and_b32_e32 v5, 0x7ffff0, v5
	v_lshrrev_b32_e32 v7, 6, v6
	v_add_u32_e32 v5, v7, v5
	v_and_b32_e32 v6, 0xc0, v6
	v_sub_u32_e32 v3, v3, v6
	v_mul_lo_u32 v5, v5, s0
	s_lshl_b32 s0, s13, 10
	v_lshlrev_b32_e32 v4, 5, v4
	v_ashrrev_i16_sdwa v3, v205, sext(v3) dst_sel:DWORD dst_unused:UNUSED_PAD src0_sel:DWORD src1_sel:BYTE_0
	s_add_i32 s4, s0, 0
	v_readlane_b32 s8, v253, 16
	v_bfe_i32 v3, v3, 0, 16
	v_and_or_b32 v4, v4, 32, v5
	s_add_i32 s5, s4, 0x10000
	v_readlane_b32 s9, v253, 17
	s_mov_b32 m0, s5
	s_nop 0
	global_load_lds_dwordx4 v0, s[8:9]
	v_add_lshl_u32 v152, v4, v3, 1
	s_add_i32 s6, s4, 0x12000
	s_mov_b32 m0, s6
	s_nop 0
	global_load_lds_dwordx4 v152, s[8:9]
	v_readlane_b32 s10, v253, 6
	s_add_i32 s7, s4, 0x14000
	v_readlane_b32 s11, v253, 7
	s_mov_b32 m0, s7
	s_nop 0
	global_load_lds_dwordx4 v0, s[10:11]
	s_add_i32 s8, s4, 0x16000
	s_mov_b32 m0, s8
	s_nop 0
	global_load_lds_dwordx4 v152, s[10:11]
	v_readlane_b32 s10, v253, 12
	v_readlane_b32 s11, v253, 13
	s_mov_b32 m0, s4
	s_nop 0
	global_load_lds_dwordx4 v0, s[10:11]
	s_add_i32 s9, s4, 0x2000
	s_mov_b32 m0, s9
	s_nop 0
	global_load_lds_dwordx4 v152, s[10:11]
	v_readlane_b32 s16, v253, 8
	s_add_i32 s10, s4, 0x4000
	v_readlane_b32 s17, v253, 9
	s_mov_b32 m0, s10
	s_nop 0
	global_load_lds_dwordx4 v0, s[16:17]
	s_ashr_i32 s14, s12, 8
	s_add_i32 s11, s4, 0x6000
	s_mov_b32 m0, s11
	s_nop 0
	global_load_lds_dwordx4 v152, s[16:17]
	s_cmp_eq_u32 s14, 1
	s_cselect_b64 s[0:1], -1, 0
	s_cmp_lg_u32 s14, 1
	s_cbranch_scc1 .LBB0_1072
	s_barrier
.LBB0_1072:
	v_readlane_b32 s15, v250, 19
	v_bfe_u32 v3, v2, 4, 2
	s_add_u32 s20, s15, 0xa000
	v_readlane_b32 s15, v250, 20
	v_and_b32_e32 v4, 15, v2
	v_lshlrev_b32_e32 v5, 4, v3
	v_lshlrev_b32_e32 v2, 2, v2
	s_addc_u32 s21, s15, 0
	v_lshl_or_b32 v153, s14, 6, v4
	v_lshl_or_b32 v4, v4, 6, v5
	s_lshl_b32 s14, s14, 13
	v_and_b32_e32 v2, 32, v2
	s_lshl_b32 s13, s13, 5
	v_bitop3_b32 v5, v4, s14, v2 bitop3:0xde
	s_and_b32 s14, s13, 0x60
	s_lshl_b32 s13, s14, 7
	v_readlane_b32 s16, v253, 10
	v_bitop3_b32 v2, v4, s13, v2 bitop3:0xde
	s_waitcnt vmcnt(2)
	s_barrier
	s_add_i32 s28, s4, 0x18000
	v_readlane_b32 s17, v253, 11
	s_mov_b32 m0, s28
	s_nop 0
	global_load_lds_dwordx4 v0, s[16:17]
	s_add_i32 s30, s4, 0x1a000
	s_mov_b32 m0, s30
	s_nop 0
	global_load_lds_dwordx4 v152, s[16:17]
	v_readlane_b32 s16, v253, 14
	s_add_i32 s31, s4, 0x8000
	v_readlane_b32 s17, v253, 15
	s_mov_b32 m0, s31
	s_nop 0
	global_load_lds_dwordx4 v0, s[16:17]
	s_add_i32 s36, s4, 0xa000
	s_mov_b32 m0, s36
	s_nop 0
	global_load_lds_dwordx4 v152, s[16:17]
	v_readlane_b32 s16, v253, 18
	s_add_i32 s37, s4, 0x1c000
	v_readlane_b32 s17, v253, 19
	s_mov_b32 m0, s37
	s_nop 0
	global_load_lds_dwordx4 v0, s[16:17]
	s_add_i32 s38, s4, 0x1e000
	s_mov_b32 m0, s38
	s_nop 0
	global_load_lds_dwordx4 v152, s[16:17]
	s_waitcnt vmcnt(6)
	s_add_i32 s39, s4, 0xc000
	v_readlane_b32 s24, v253, 16
	v_readlane_b32 s22, v253, 12
	s_cmpk_lt_u32 s12, 0x100
	v_lshl_or_b32 v154, v3, 2, s14
	v_readlane_b32 s14, v253, 1
	v_readlane_b32 s25, v253, 17
	v_readlane_b32 s23, v253, 13
	s_cselect_b64 s[12:13], -1, 0
	s_add_i32 s40, s4, 0xe000
	s_mov_b32 s41, 0
	v_add_u32_e32 v155, 0, v2
	s_waitcnt vmcnt(17)
	v_add_u32_e32 v156, 0, v5
	v_readlane_b32 s45, v253, 3
	s_mov_b32 s44, s14
	s_mov_b64 s[16:17], s[22:23]
	s_mov_b64 s[18:19], s[24:25]
	s_barrier
	v_readlane_b32 s15, v253, 2
	s_branch .LBB0_1075

; #define PG8_STAGE(bufoff, gbase, voff) do { _Pragma("unroll") for (int _i = 0; _i < 2; ++_i) \
;         glds_s((voff)[_i], (const void*)(gbase), ldsbase + (unsigned)((bufoff) + _i * 8192)); } while (0)
; #define PG8_LDA(dst, b, h) do { _Pragma("unroll") for (int m = 0; m < 4; ++m) _Pragma("unroll") for (int k = 0; k < 2; ++k) dst[m][k] = *(const LAS bf16x8*)(lds + PG8_SA(b, h) + aoff + m * 2048 + k * 1024); } while (0)
; #define PG8_LDB(dst, b, h) do { _Pragma("unroll") for (int n = 0; n < 2; ++n) _Pragma("unroll") for (int k = 0; k < 2; ++k) dst[n][k] = *(const LAS bf16x8*)(lds + PG8_SB(b, h) + boff + n * 2048 + k * 1024); } while (0)
; #define PG8_MMA(ai, bj, At, Bt) do { __builtin_amdgcn_s_setprio(1); _Pragma("unroll") for (int m = 0; m < 4; ++m) _Pragma("unroll") for (int n = 0; n < 2; ++n) _Pragma("unroll") for (int k = 0; k < 2; ++k) \
;         acc[ai][bj][m][n] = __builtin_amdgcn_mfma_f32_16x16x32_bf16(Bt[n][k], At[m][k], acc[ai][bj][m][n], 0, 0, 0); __builtin_amdgcn_s_setprio(0); } while (0)
; #define PG8_WAIT_V(n) asm volatile("s_waitcnt vmcnt(" #n ")" ::: "memory")
; #define PG8_WAIT_L(n) asm volatile("s_waitcnt lgkmcnt(" #n ")" ::: "memory")
; #define PG8_BAR __builtin_amdgcn_s_barrier()
; #define PG8_SCHED __builtin_amdgcn_sched_barrier(0)
; template <class Epi, class Sched, bool ALIGN_EPI, bool SP2>
; __device__ __forceinline__ void gemm_phase(LAS unsigned char* lds, const int K, const Sched& S, const Epi& E) {
;     ...
;             PG8_LDB(B0, 0, 0); PG8_LDB(B1, 0, 1); PG8_SCHED; PG8_LDA(At, 0, 0); PG8_STAGE(PG8_SA(1, 1), a1 + hstep, voffA);
;             PG8_WAIT_V(8); PG8_WAIT_L(0); PG8_BAR; PG8_MMA(0, 0, At, B0); PG8_MMA(0, 1, At, B1); PG8_BAR; PG8_SCHED;
;             PG8_LDA(At, 0, 1); PG8_STAGE(PG8_SB(0, 0), b2, voffB); PG8_STAGE(PG8_SB(0, 1), b2 + hstep, voffB); PG8_STAGE(PG8_SA(0, 0), a2, voffA);
;             PG8_WAIT_V(8); PG8_WAIT_L(0); PG8_BAR; PG8_MMA(1, 0, At, B0); PG8_MMA(1, 1, At, B1); PG8_BAR; PG8_SCHED;
;             PG8_LDB(B0, 1, 0); PG8_LDB(B1, 1, 1); PG8_SCHED; PG8_LDA(At, 1, 0); PG8_STAGE(PG8_SA(0, 1), a2 + hstep, voffA);
;             PG8_WAIT_V(8); PG8_WAIT_L(0); PG8_BAR; PG8_MMA(0, 0, At, B0); PG8_MMA(0, 1, At, B1); PG8_BAR; PG8_SCHED;
.LBB0_1082:
	v_add_u32_e32 v94, 0x10000, v155
	v_add_u32_e32 v150, 0x14000, v155
	ds_read_b128 v[74:77], v94
	ds_read_b128 v[86:89], v94 offset:1024
	ds_read_b128 v[90:93], v94 offset:2048
	ds_read_b128 v[94:97], v94 offset:3072
	ds_read_b128 v[146:149], v150
	ds_read_b128 v[158:161], v150 offset:1024
	ds_read_b128 v[162:165], v150 offset:2048
	ds_read_b128 v[166:169], v150 offset:3072
	s_cmpk_eq_i32 s51, 0x54
	s_cselect_b32 s24, s16, s46
	s_cselect_b32 s25, s17, s47
	s_cselect_b32 s34, s18, s48
	s_cselect_b32 s35, s19, s49
	s_add_u32 s26, s24, 0x80
	s_addc_u32 s27, s25, 0
	ds_read_b128 v[170:173], v156
	ds_read_b128 v[174:177], v156 offset:1024
	ds_read_b128 v[182:185], v156 offset:2048
	ds_read_b128 v[186:189], v156 offset:3072
	ds_read_b128 v[190:193], v156 offset:4096
	ds_read_b128 v[194:197], v156 offset:5120
	ds_read_b128 v[198:201], v156 offset:6144
	ds_read_b128 v[214:217], v156 offset:7168
	s_mov_b32 m0, s39
	s_nop 0
	global_load_lds_dwordx4 v0, s[22:23]
	s_mov_b32 m0, s40
	s_nop 0
	global_load_lds_dwordx4 v152, s[22:23]
	s_waitcnt vmcnt(8)
	s_waitcnt lgkmcnt(0)
	s_barrier
	s_setprio 1
	s_waitcnt lgkmcnt(7)
	v_mfma_f32_16x16x32_bf16 v[142:145], v[74:77], v[170:173], v[142:145]
	v_mfma_f32_16x16x32_bf16 v[138:141], v[90:93], v[170:173], v[138:141]
	s_waitcnt lgkmcnt(5)
	v_mfma_f32_16x16x32_bf16 v[126:129], v[74:77], v[182:185], v[126:129]
	v_mfma_f32_16x16x32_bf16 v[122:125], v[90:93], v[182:185], v[122:125]
	s_waitcnt lgkmcnt(3)
	v_mfma_f32_16x16x32_bf16 v[110:113], v[74:77], v[190:193], v[110:113]
	v_mfma_f32_16x16x32_bf16 v[106:109], v[90:93], v[190:193], v[106:109]
	s_waitcnt lgkmcnt(1)
	v_mfma_f32_16x16x32_bf16 v[82:85], v[74:77], v[198:201], v[82:85]
	v_mfma_f32_16x16x32_bf16 v[78:81], v[90:93], v[198:201], v[78:81]
	v_mfma_f32_16x16x32_bf16 v[142:145], v[86:89], v[174:177], v[142:145]
	v_mfma_f32_16x16x32_bf16 v[138:141], v[94:97], v[174:177], v[138:141]
	v_mfma_f32_16x16x32_bf16 v[126:129], v[86:89], v[186:189], v[126:129]
	v_mfma_f32_16x16x32_bf16 v[122:125], v[94:97], v[186:189], v[122:125]
	v_mfma_f32_16x16x32_bf16 v[110:113], v[86:89], v[194:197], v[110:113]
	v_mfma_f32_16x16x32_bf16 v[106:109], v[94:97], v[194:197], v[106:109]
	s_waitcnt lgkmcnt(0)
	v_mfma_f32_16x16x32_bf16 v[82:85], v[86:89], v[214:217], v[82:85]
	v_mfma_f32_16x16x32_bf16 v[78:81], v[94:97], v[214:217], v[78:81]
	s_setprio 0
	s_setprio 1
	v_mfma_f32_16x16x32_bf16 v[134:137], v[146:149], v[170:173], v[134:137]
	v_mfma_f32_16x16x32_bf16 v[130:133], v[162:165], v[170:173], v[130:133]
	v_mfma_f32_16x16x32_bf16 v[118:121], v[146:149], v[182:185], v[118:121]
	v_mfma_f32_16x16x32_bf16 v[114:117], v[162:165], v[182:185], v[114:117]
	v_mfma_f32_16x16x32_bf16 v[102:105], v[146:149], v[190:193], v[102:105]
	v_mfma_f32_16x16x32_bf16 v[98:101], v[162:165], v[190:193], v[98:101]
	v_mfma_f32_16x16x32_bf16 v[70:73], v[146:149], v[198:201], v[70:73]
	v_mfma_f32_16x16x32_bf16 v[66:69], v[162:165], v[198:201], v[66:69]
	v_mfma_f32_16x16x32_bf16 v[134:137], v[158:161], v[174:177], v[134:137]
	v_mfma_f32_16x16x32_bf16 v[130:133], v[166:169], v[174:177], v[130:133]
	v_mfma_f32_16x16x32_bf16 v[118:121], v[158:161], v[186:189], v[118:121]
	v_mfma_f32_16x16x32_bf16 v[114:117], v[166:169], v[186:189], v[114:117]
	v_mfma_f32_16x16x32_bf16 v[102:105], v[158:161], v[194:197], v[102:105]
	v_mfma_f32_16x16x32_bf16 v[98:101], v[166:169], v[194:197], v[98:101]
	v_mfma_f32_16x16x32_bf16 v[70:73], v[158:161], v[214:217], v[70:73]
	v_mfma_f32_16x16x32_bf16 v[66:69], v[166:169], v[214:217], v[66:69]
	s_setprio 0
	s_barrier
	ds_read_b128 v[170:173], v156 offset:16384
	ds_read_b128 v[174:177], v156 offset:17408
	ds_read_b128 v[182:185], v156 offset:18432
	ds_read_b128 v[186:189], v156 offset:19456
	ds_read_b128 v[190:193], v156 offset:20480
	ds_read_b128 v[194:197], v156 offset:21504
	ds_read_b128 v[198:201], v156 offset:22528
	ds_read_b128 v[214:217], v156 offset:23552
	s_mov_b32 m0, s5
	s_nop 0
	global_load_lds_dwordx4 v0, s[34:35]
	s_mov_b32 m0, s6
	s_nop 0
	global_load_lds_dwordx4 v152, s[34:35]
	s_add_u32 s52, s34, 0x160000
	s_addc_u32 s53, s35, 0
	s_mov_b32 m0, s7
	s_nop 0
	global_load_lds_dwordx4 v0, s[52:53]
	s_mov_b32 m0, s8
	s_nop 0
	global_load_lds_dwordx4 v152, s[52:53]
	s_mov_b32 m0, s4
	s_nop 0
	global_load_lds_dwordx4 v0, s[24:25]
	s_mov_b32 m0, s9
	s_nop 0
	global_load_lds_dwordx4 v152, s[24:25]
	s_waitcnt vmcnt(8)
	s_waitcnt lgkmcnt(0)
	s_barrier
	s_setprio 1
	s_waitcnt lgkmcnt(7)
	v_mfma_f32_16x16x32_bf16 v[62:65], v[74:77], v[170:173], v[62:65]
	v_mfma_f32_16x16x32_bf16 v[58:61], v[90:93], v[170:173], v[58:61]
	s_waitcnt lgkmcnt(5)
	v_mfma_f32_16x16x32_bf16 v[46:49], v[74:77], v[182:185], v[46:49]
	v_mfma_f32_16x16x32_bf16 v[42:45], v[90:93], v[182:185], v[42:45]
	s_waitcnt lgkmcnt(3)
	v_mfma_f32_16x16x32_bf16 v[30:33], v[74:77], v[190:193], v[30:33]
	v_mfma_f32_16x16x32_bf16 v[26:29], v[90:93], v[190:193], v[26:29]
	s_waitcnt lgkmcnt(1)
	v_mfma_f32_16x16x32_bf16 v[14:17], v[74:77], v[198:201], v[14:17]
	v_mfma_f32_16x16x32_bf16 v[10:13], v[90:93], v[198:201], v[10:13]
	v_mfma_f32_16x16x32_bf16 v[62:65], v[86:89], v[174:177], v[62:65]
	v_mfma_f32_16x16x32_bf16 v[58:61], v[94:97], v[174:177], v[58:61]
	v_mfma_f32_16x16x32_bf16 v[46:49], v[86:89], v[186:189], v[46:49]
	v_mfma_f32_16x16x32_bf16 v[42:45], v[94:97], v[186:189], v[42:45]
	v_mfma_f32_16x16x32_bf16 v[30:33], v[86:89], v[194:197], v[30:33]
	v_mfma_f32_16x16x32_bf16 v[26:29], v[94:97], v[194:197], v[26:29]
	s_waitcnt lgkmcnt(0)
	v_mfma_f32_16x16x32_bf16 v[14:17], v[86:89], v[214:217], v[14:17]
	v_mfma_f32_16x16x32_bf16 v[10:13], v[94:97], v[214:217], v[10:13]
	s_setprio 0
	s_setprio 1
	v_mfma_f32_16x16x32_bf16 v[54:57], v[146:149], v[170:173], v[54:57]
	v_mfma_f32_16x16x32_bf16 v[50:53], v[162:165], v[170:173], v[50:53]
	v_mfma_f32_16x16x32_bf16 v[38:41], v[146:149], v[182:185], v[38:41]
	v_mfma_f32_16x16x32_bf16 v[34:37], v[162:165], v[182:185], v[34:37]
	v_mfma_f32_16x16x32_bf16 v[22:25], v[146:149], v[190:193], v[22:25]
	v_mfma_f32_16x16x32_bf16 v[18:21], v[162:165], v[190:193], v[18:21]
	v_mfma_f32_16x16x32_bf16 v[6:9], v[146:149], v[198:201], v[6:9]
	v_mfma_f32_16x16x32_bf16 v[2:5], v[162:165], v[198:201], v[2:5]
	v_mfma_f32_16x16x32_bf16 v[54:57], v[158:161], v[174:177], v[54:57]
	v_mfma_f32_16x16x32_bf16 v[50:53], v[166:169], v[174:177], v[50:53]
	v_mfma_f32_16x16x32_bf16 v[38:41], v[158:161], v[186:189], v[38:41]
	v_mfma_f32_16x16x32_bf16 v[34:37], v[166:169], v[186:189], v[34:37]
	v_mfma_f32_16x16x32_bf16 v[22:25], v[158:161], v[194:197], v[22:25]
	v_mfma_f32_16x16x32_bf16 v[18:21], v[166:169], v[194:197], v[18:21]
	v_mfma_f32_16x16x32_bf16 v[6:9], v[158:161], v[214:217], v[6:9]
	v_mfma_f32_16x16x32_bf16 v[2:5], v[166:169], v[214:217], v[2:5]
	s_setprio 0
	s_barrier
; #define PG8_STAGE(bufoff, gbase, voff) do { _Pragma("unroll") for (int _i = 0; _i < 2; ++_i) \
;         glds_s((voff)[_i], (const void*)(gbase), ldsbase + (unsigned)((bufoff) + _i * 8192)); } while (0)
; #define PG8_LDA(dst, b, h) do { _Pragma("unroll") for (int m = 0; m < 4; ++m) _Pragma("unroll") for (int k = 0; k < 2; ++k) dst[m][k] = *(const LAS bf16x8*)(lds + PG8_SA(b, h) + aoff + m * 2048 + k * 1024); } while (0)
; #define PG8_LDB(dst, b, h) do { _Pragma("unroll") for (int n = 0; n < 2; ++n) _Pragma("unroll") for (int k = 0; k < 2; ++k) dst[n][k] = *(const LAS bf16x8*)(lds + PG8_SB(b, h) + boff + n * 2048 + k * 1024); } while (0)
; #define PG8_MMA(ai, bj, At, Bt) do { __builtin_amdgcn_s_setprio(1); _Pragma("unroll") for (int m = 0; m < 4; ++m) _Pragma("unroll") for (int n = 0; n < 2; ++n) _Pragma("unroll") for (int k = 0; k < 2; ++k) \
;         acc[ai][bj][m][n] = __builtin_amdgcn_mfma_f32_16x16x32_bf16(Bt[n][k], At[m][k], acc[ai][bj][m][n], 0, 0, 0); __builtin_amdgcn_s_setprio(0); } while (0)
; #define PG8_WAIT_V(n) asm volatile("s_waitcnt vmcnt(" #n ")" ::: "memory")
; #define PG8_WAIT_L(n) asm volatile("s_waitcnt lgkmcnt(" #n ")" ::: "memory")
; #define PG8_BAR __builtin_amdgcn_s_barrier()
; #define PG8_SCHED __builtin_amdgcn_sched_barrier(0)
; template <class Epi, class Sched, bool ALIGN_EPI, bool SP2>
; __device__ __forceinline__ void gemm_phase(LAS unsigned char* lds, const int K, const Sched& S, const Epi& E) {
;     ...
;             PG8_LDB(B0, 1, 0); PG8_LDB(B1, 1, 1); PG8_SCHED; PG8_LDA(At, 1, 0); PG8_STAGE(PG8_SA(0, 1), a2 + hstep, voffA);
;             PG8_WAIT_V(8); PG8_WAIT_L(0); PG8_BAR; PG8_MMA(0, 0, At, B0); PG8_MMA(0, 1, At, B1); PG8_BAR; PG8_SCHED;
;             PG8_LDA(At, 1, 1); PG8_STAGE(PG8_SB(1, 0), b3, voffB); PG8_STAGE(PG8_SB(1, 1), b3 + hstep, voffB); PG8_STAGE(PG8_SA(1, 0), a3, voffA);
;             PG8_WAIT_V(8); PG8_WAIT_L(0); PG8_BAR; PG8_MMA(1, 0, At, B0); PG8_MMA(1, 1, At, B1); PG8_BAR; PG8_SCHED;
	v_add_u32_e32 v94, 0x18000, v155
	v_add_u32_e32 v150, 0x1c000, v155
	ds_read_b128 v[74:77], v94
	ds_read_b128 v[86:89], v94 offset:1024
	ds_read_b128 v[90:93], v94 offset:2048
	ds_read_b128 v[94:97], v94 offset:3072
	ds_read_b128 v[146:149], v150
	ds_read_b128 v[158:161], v150 offset:1024
	ds_read_b128 v[162:165], v150 offset:2048
	ds_read_b128 v[166:169], v150 offset:3072
	ds_read_b128 v[170:173], v156 offset:32768
	ds_read_b128 v[174:177], v156 offset:33792
	ds_read_b128 v[182:185], v156 offset:34816
	ds_read_b128 v[186:189], v156 offset:35840
	ds_read_b128 v[190:193], v156 offset:36864
	ds_read_b128 v[194:197], v156 offset:37888
	ds_read_b128 v[198:201], v156 offset:38912
	ds_read_b128 v[214:217], v156 offset:39936
	s_add_u32 s24, s24, 0x160000
	s_addc_u32 s25, s25, 0
	s_mov_b32 m0, s10
	s_nop 0
	global_load_lds_dwordx4 v0, s[24:25]
	s_mov_b32 m0, s11
	s_nop 0
	global_load_lds_dwordx4 v152, s[24:25]
	s_waitcnt vmcnt(8)
	s_waitcnt lgkmcnt(0)
	s_barrier
	s_setprio 1
	s_waitcnt lgkmcnt(7)
	v_mfma_f32_16x16x32_bf16 v[142:145], v[74:77], v[170:173], v[142:145]
	v_mfma_f32_16x16x32_bf16 v[138:141], v[90:93], v[170:173], v[138:141]
	s_waitcnt lgkmcnt(5)
	v_mfma_f32_16x16x32_bf16 v[126:129], v[74:77], v[182:185], v[126:129]
	v_mfma_f32_16x16x32_bf16 v[122:125], v[90:93], v[182:185], v[122:125]
	s_waitcnt lgkmcnt(3)
	v_mfma_f32_16x16x32_bf16 v[110:113], v[74:77], v[190:193], v[110:113]
	v_mfma_f32_16x16x32_bf16 v[106:109], v[90:93], v[190:193], v[106:109]
	s_waitcnt lgkmcnt(1)
	v_mfma_f32_16x16x32_bf16 v[82:85], v[74:77], v[198:201], v[82:85]
	v_mfma_f32_16x16x32_bf16 v[78:81], v[90:93], v[198:201], v[78:81]
	v_mfma_f32_16x16x32_bf16 v[142:145], v[86:89], v[174:177], v[142:145]
	v_mfma_f32_16x16x32_bf16 v[138:141], v[94:97], v[174:177], v[138:141]
	v_mfma_f32_16x16x32_bf16 v[126:129], v[86:89], v[186:189], v[126:129]
	v_mfma_f32_16x16x32_bf16 v[122:125], v[94:97], v[186:189], v[122:125]
	v_mfma_f32_16x16x32_bf16 v[110:113], v[86:89], v[194:197], v[110:113]
	v_mfma_f32_16x16x32_bf16 v[106:109], v[94:97], v[194:197], v[106:109]
	s_waitcnt lgkmcnt(0)
	v_mfma_f32_16x16x32_bf16 v[82:85], v[86:89], v[214:217], v[82:85]
	v_mfma_f32_16x16x32_bf16 v[78:81], v[94:97], v[214:217], v[78:81]
	s_setprio 0
	s_setprio 1
	v_mfma_f32_16x16x32_bf16 v[134:137], v[146:149], v[170:173], v[134:137]
	v_mfma_f32_16x16x32_bf16 v[130:133], v[162:165], v[170:173], v[130:133]
	v_mfma_f32_16x16x32_bf16 v[118:121], v[146:149], v[182:185], v[118:121]
	v_mfma_f32_16x16x32_bf16 v[114:117], v[162:165], v[182:185], v[114:117]
	v_mfma_f32_16x16x32_bf16 v[102:105], v[146:149], v[190:193], v[102:105]
	v_mfma_f32_16x16x32_bf16 v[98:101], v[162:165], v[190:193], v[98:101]
	v_mfma_f32_16x16x32_bf16 v[70:73], v[146:149], v[198:201], v[70:73]
	v_mfma_f32_16x16x32_bf16 v[66:69], v[162:165], v[198:201], v[66:69]
	v_mfma_f32_16x16x32_bf16 v[134:137], v[158:161], v[174:177], v[134:137]
	v_mfma_f32_16x16x32_bf16 v[130:133], v[166:169], v[174:177], v[130:133]
	v_mfma_f32_16x16x32_bf16 v[118:121], v[158:161], v[186:189], v[118:121]
	v_mfma_f32_16x16x32_bf16 v[114:117], v[166:169], v[186:189], v[114:117]
	v_mfma_f32_16x16x32_bf16 v[102:105], v[158:161], v[194:197], v[102:105]
	v_mfma_f32_16x16x32_bf16 v[98:101], v[166:169], v[194:197], v[98:101]
	v_mfma_f32_16x16x32_bf16 v[70:73], v[158:161], v[214:217], v[70:73]
	v_mfma_f32_16x16x32_bf16 v[66:69], v[166:169], v[214:217], v[66:69]
	s_setprio 0
	s_barrier
	ds_read_b128 v[170:173], v156 offset:49152
	ds_read_b128 v[174:177], v156 offset:50176
	ds_read_b128 v[182:185], v156 offset:51200
	ds_read_b128 v[186:189], v156 offset:52224
	ds_read_b128 v[190:193], v156 offset:53248
	ds_read_b128 v[194:197], v156 offset:54272
	ds_read_b128 v[198:201], v156 offset:55296
	ds_read_b128 v[214:217], v156 offset:56320
	s_add_u32 s24, s34, 0x80
	s_addc_u32 s25, s35, 0
	s_mov_b32 m0, s28
	s_nop 0
	global_load_lds_dwordx4 v0, s[24:25]
	s_mov_b32 m0, s30
	s_nop 0
	global_load_lds_dwordx4 v152, s[24:25]
	s_add_u32 s24, s34, 0x160080
	s_addc_u32 s25, s35, 0
	s_mov_b32 m0, s37
	s_nop 0
	global_load_lds_dwordx4 v0, s[24:25]
	s_mov_b32 m0, s38
	s_nop 0
	global_load_lds_dwordx4 v152, s[24:25]
	s_mov_b32 m0, s31
	s_nop 0
	global_load_lds_dwordx4 v0, s[26:27]
	s_mov_b32 m0, s36
	s_nop 0
	global_load_lds_dwordx4 v152, s[26:27]
	s_waitcnt vmcnt(8)
	s_waitcnt lgkmcnt(0)
	s_barrier
	s_setprio 1
	s_waitcnt lgkmcnt(7)
	v_mfma_f32_16x16x32_bf16 v[62:65], v[74:77], v[170:173], v[62:65]
	v_mfma_f32_16x16x32_bf16 v[58:61], v[90:93], v[170:173], v[58:61]
	s_waitcnt lgkmcnt(5)
	v_mfma_f32_16x16x32_bf16 v[46:49], v[74:77], v[182:185], v[46:49]
	v_mfma_f32_16x16x32_bf16 v[42:45], v[90:93], v[182:185], v[42:45]
	s_waitcnt lgkmcnt(3)
	v_mfma_f32_16x16x32_bf16 v[30:33], v[74:77], v[190:193], v[30:33]
	v_mfma_f32_16x16x32_bf16 v[26:29], v[90:93], v[190:193], v[26:29]
	s_waitcnt lgkmcnt(1)
	v_mfma_f32_16x16x32_bf16 v[14:17], v[74:77], v[198:201], v[14:17]
	v_mfma_f32_16x16x32_bf16 v[10:13], v[90:93], v[198:201], v[10:13]
	v_mfma_f32_16x16x32_bf16 v[62:65], v[86:89], v[174:177], v[62:65]
	v_mfma_f32_16x16x32_bf16 v[58:61], v[94:97], v[174:177], v[58:61]
	v_mfma_f32_16x16x32_bf16 v[46:49], v[86:89], v[186:189], v[46:49]
	v_mfma_f32_16x16x32_bf16 v[42:45], v[94:97], v[186:189], v[42:45]
	v_mfma_f32_16x16x32_bf16 v[30:33], v[86:89], v[194:197], v[30:33]
	v_mfma_f32_16x16x32_bf16 v[26:29], v[94:97], v[194:197], v[26:29]
	s_waitcnt lgkmcnt(0)
	v_mfma_f32_16x16x32_bf16 v[14:17], v[86:89], v[214:217], v[14:17]
	v_mfma_f32_16x16x32_bf16 v[10:13], v[94:97], v[214:217], v[10:13]
	s_setprio 0
	s_setprio 1
	v_mfma_f32_16x16x32_bf16 v[54:57], v[146:149], v[170:173], v[54:57]
	v_mfma_f32_16x16x32_bf16 v[50:53], v[162:165], v[170:173], v[50:53]
	v_mfma_f32_16x16x32_bf16 v[38:41], v[146:149], v[182:185], v[38:41]
	v_mfma_f32_16x16x32_bf16 v[34:37], v[162:165], v[182:185], v[34:37]
	v_mfma_f32_16x16x32_bf16 v[22:25], v[146:149], v[190:193], v[22:25]
	v_mfma_f32_16x16x32_bf16 v[18:21], v[162:165], v[190:193], v[18:21]
	v_mfma_f32_16x16x32_bf16 v[6:9], v[146:149], v[198:201], v[6:9]
	v_mfma_f32_16x16x32_bf16 v[2:5], v[162:165], v[198:201], v[2:5]
	v_mfma_f32_16x16x32_bf16 v[54:57], v[158:161], v[174:177], v[54:57]
	v_mfma_f32_16x16x32_bf16 v[50:53], v[166:169], v[174:177], v[50:53]
	v_mfma_f32_16x16x32_bf16 v[38:41], v[158:161], v[186:189], v[38:41]
	v_mfma_f32_16x16x32_bf16 v[34:37], v[166:169], v[186:189], v[34:37]
	v_mfma_f32_16x16x32_bf16 v[22:25], v[158:161], v[194:197], v[22:25]
	v_mfma_f32_16x16x32_bf16 v[18:21], v[166:169], v[194:197], v[18:21]
	v_mfma_f32_16x16x32_bf16 v[6:9], v[158:161], v[214:217], v[6:9]
	v_mfma_f32_16x16x32_bf16 v[2:5], v[166:169], v[214:217], v[2:5]
	s_setprio 0
	s_barrier
	s_add_i32 s51, s51, 2
	s_add_u32 s46, s46, 0x100
	s_addc_u32 s47, s47, 0
	s_add_u32 s48, s48, 0x100
	s_addc_u32 s49, s49, 0
	s_add_u32 s22, s22, 0x100
	s_addc_u32 s23, s23, 0
	s_cmpk_gt_u32 s51, 0x55
	s_cbranch_scc0 .LBB0_1082
	v_readlane_b32 s46, v250, 8
	s_and_b64 vcc, exec, s[12:13]
	v_readlane_b32 s47, v250, 9
	s_cbranch_vccz .LBB0_1085
	s_barrier
